# v69 + attention: dead cvt-init movs removed, V staged row-major and read with ds_read_b64_tr_b8, PV and QK LDS operand reads all issued ahead of back-to-back MFMAs
# speedup vs baseline: 1.0637x; 1.0166x over previous
; #define LAS __attribute__((address_space(3)))
; #define LDS_WAIT() asm volatile("s_waitcnt lgkmcnt(0)" ::: "memory")
;     ...
;     for (int i = 0; i < 8; ++i) wv[i] = __builtin_nontemporal_load((const f32x4*)(W + (size_t)(k0 + (lane >> 3) + 8 * i) * N + sc));
; #pragma unroll
;     for (int i = 0; i < 8; ++i) { LAS float* d = scr + ((lane >> 3) + 8 * i) * 33 + n4; d[0] = wv[i][0]; d[1] = wv[i][1]; d[2] = wv[i][2]; d[3] = wv[i][3]; }
;     LDS_WAIT();
;     const int c = lane & 7;
;     if (P8) {
; #pragma unroll
;         for (int j = 0; j < 4; ++j) { const int n = (lane >> 3) + 8 * j; const LAS float* s = scr + (8 * c) * 33 + n;
;             int w0 = 0, w1 = 0;
;             w0 = __builtin_amdgcn_cvt_pk_fp8_f32(s[0 * 33] * W8_SCALE, s[1 * 33] * W8_SCALE, w0, false); w0 = __builtin_amdgcn_cvt_pk_fp8_f32(s[2 * 33] * W8_SCALE, s[3 * 33] * W8_SCALE, w0, true);
;             w1 = __builtin_amdgcn_cvt_pk_fp8_f32(s[4 * 33] * W8_SCALE, s[5 * 33] * W8_SCALE, w1, false); w1 = __builtin_amdgcn_cvt_pk_fp8_f32(s[6 * 33] * W8_SCALE, s[7 * 33] * W8_SCALE, w1, true);
;             u32x2 o; o.x = (unsigned)w0; o.y = (unsigned)w1;
;             *(u32x2*)(B8 + (size_t)(n0 + n) * pitch + k0 + 8 * c) = o; }
;         LDS_WAIT(); return; }
.LBB0_14:
	s_andn2_b64 vcc, exec, s[0:1]
	s_cbranch_vccnz .LBB0_16
	s_add_i32 s0, s16, 0x400
	s_and_b32 s8, s0, 0x3c0
	s_add_i32 s0, s14, 0xfffdd000
	s_and_b32 s0, s0, 0x3e0
	v_or_b32_e32 v2, s0, v1
	v_readlane_b32 s20, v250, 0
	v_or_b32_e32 v42, s8, v16
	v_lshlrev_b32_e32 v2, 2, v2
	v_readlane_b32 s21, v250, 1
	v_lshl_add_u64 v[76:77], v[6:7], 0, s[8:9]
	v_lshl_add_u64 v[14:15], s[20:21], 0, v[2:3]
	v_lshlrev_b32_e32 v2, 12, v42
	v_lshl_add_u64 v[14:15], v[14:15], 0, v[2:3]
	v_add_co_u32_e32 v46, vcc, 0x8000, v14
	v_or_b32_e32 v2, s0, v16
	s_nop 0
	v_addc_co_u32_e32 v47, vcc, 0, v15, vcc
	v_add_co_u32_e32 v50, vcc, 0x10000, v14
	global_load_dwordx4 v[42:45], v[14:15], off nt
	s_nop 0
	global_load_dwordx4 v[46:49], v[46:47], off nt
	v_addc_co_u32_e32 v51, vcc, 0, v15, vcc
	v_add_co_u32_e32 v54, vcc, 0x18000, v14
	v_mul_u32_u24_e32 v2, 0x500, v2
	s_nop 0
	v_addc_co_u32_e32 v55, vcc, 0, v15, vcc
	v_add_co_u32_e32 v58, vcc, 0x20000, v14
	global_load_dwordx4 v[50:53], v[50:51], off nt
	s_nop 0
	global_load_dwordx4 v[54:57], v[54:55], off nt
	v_addc_co_u32_e32 v59, vcc, 0, v15, vcc
	v_add_co_u32_e32 v62, vcc, 0x28000, v14
	v_lshl_add_u64 v[78:79], v[76:77], 0, v[2:3]
	s_nop 0
	v_addc_co_u32_e32 v63, vcc, 0, v15, vcc
	global_load_dwordx4 v[58:61], v[58:59], off nt
	s_nop 0
	global_load_dwordx4 v[62:65], v[62:63], off nt
	v_add_co_u32_e32 v66, vcc, 0x30000, v14
	s_nop 0
	v_addc_co_u32_e32 v67, vcc, 0, v15, vcc
	global_load_dwordx4 v[66:69], v[66:67], off nt
	v_add_co_u32_e32 v14, vcc, 0x38000, v14
	v_readlane_b32 s22, v250, 2
	s_nop 0
	v_addc_co_u32_e32 v15, vcc, 0, v15, vcc
	global_load_dwordx4 v[70:73], v[14:15], off nt
	v_readlane_b32 s23, v250, 3
	v_readlane_b32 s24, v250, 4
	v_readlane_b32 s25, v250, 5
	v_readlane_b32 s26, v250, 6
	v_readlane_b32 s27, v250, 7
	s_waitcnt vmcnt(7)
	ds_write2_b32 v21, v42, v43 offset1:1
	ds_write2_b32 v21, v44, v45 offset0:2 offset1:3
	s_waitcnt vmcnt(6)
	ds_write2_b32 v22, v46, v47 offset1:1
	ds_write2_b32 v23, v48, v49 offset1:1
	s_waitcnt vmcnt(5)
	ds_write2_b32 v24, v50, v51 offset1:1
	ds_write2_b32 v25, v52, v53 offset1:1
	s_waitcnt vmcnt(4)
	ds_write2_b32 v26, v54, v55 offset1:1
	ds_write2_b32 v27, v56, v57 offset1:1
	s_waitcnt vmcnt(3)
	ds_write2_b32 v28, v58, v59 offset1:1
	ds_write2_b32 v29, v60, v61 offset1:1
	s_waitcnt vmcnt(2)
	ds_write2_b32 v30, v62, v63 offset1:1
	ds_write2_b32 v31, v64, v65 offset1:1
	s_waitcnt vmcnt(1)
	ds_write2_b32 v32, v66, v67 offset1:1
	ds_write2_b32 v33, v68, v69 offset1:1
	s_waitcnt vmcnt(0)
	ds_write2_b32 v34, v70, v71 offset1:1
	ds_write2_b32 v35, v72, v73 offset1:1
	s_waitcnt lgkmcnt(0)
	ds_read2_b32 v[42:43], v20 offset1:8
	ds_read2_b32 v[44:45], v20 offset0:33 offset1:41
	ds_read2_b32 v[46:47], v20 offset0:66 offset1:74
	ds_read2_b32 v[48:49], v20 offset0:99 offset1:107
	ds_read2_b32 v[50:51], v20 offset0:132 offset1:140
	ds_read2_b32 v[52:53], v20 offset0:165 offset1:173
	ds_read2_b32 v[54:55], v20 offset0:198 offset1:206
	ds_read2_b32 v[56:57], v20 offset0:231 offset1:239
	s_waitcnt lgkmcnt(0)
	v_mul_f32_e32 v2, 0x42000000, v42
	v_mul_f32_e32 v42, 0x42000000, v44
	v_mul_f32_e32 v44, 0x42000000, v46
	v_mul_f32_e32 v46, 0x42000000, v48
	v_mul_f32_e32 v48, 0x42000000, v50
	v_mul_f32_e32 v50, 0x42000000, v52
	v_mul_f32_e32 v43, 0x42000000, v43
	v_mul_f32_e32 v45, 0x42000000, v45
	v_mul_f32_e32 v51, 0x42000000, v51
	v_mul_f32_e32 v53, 0x42000000, v53
	v_cvt_pk_fp8_f32 v14, v2, v42
	v_cvt_pk_fp8_f32 v15, v48, v50
	v_cvt_pk_fp8_f32 v74, v43, v45
	v_cvt_pk_fp8_f32 v75, v51, v53
	v_mul_f32_e32 v52, 0x42000000, v54
	v_mul_f32_e32 v54, 0x42000000, v56
	v_mul_f32_e32 v47, 0x42000000, v47
	v_mul_f32_e32 v49, 0x42000000, v49
	v_mul_f32_e32 v55, 0x42000000, v55
	v_cvt_pk_fp8_f32 v14, v44, v46 op_sel:[0,0,1]
	v_cvt_pk_fp8_f32 v15, v52, v54 op_sel:[0,0,1]
	v_mul_f32_e32 v2, 0x42000000, v57
	v_cvt_pk_fp8_f32 v74, v47, v49 op_sel:[0,0,1]
	v_cvt_pk_fp8_f32 v75, v55, v2 op_sel:[0,0,1]
	v_or_b32_e32 v2, s0, v17
	v_mul_u32_u24_e32 v2, 0x500, v2
	global_store_dwordx2 v[78:79], v[14:15], off
	v_lshl_add_u64 v[44:45], v[76:77], 0, v[2:3]
	ds_read2_b32 v[14:15], v20 offset0:16 offset1:24
	ds_read2_b32 v[42:43], v20 offset0:49 offset1:57
	global_store_dwordx2 v[44:45], v[74:75], off
	ds_read2_b32 v[46:47], v20 offset0:82 offset1:90
	ds_read2_b32 v[48:49], v20 offset0:115 offset1:123
	ds_read2_b32 v[50:51], v20 offset0:148 offset1:156
	ds_read2_b32 v[52:53], v20 offset0:181 offset1:189
	s_waitcnt lgkmcnt(5)
	v_mul_f32_e32 v2, 0x42000000, v14
	s_waitcnt lgkmcnt(4)
	v_mul_f32_e32 v14, 0x42000000, v42
	ds_read2_b32 v[54:55], v20 offset0:214 offset1:222
	ds_read2_b32 v[56:57], v20 offset0:247 offset1:255
	v_cvt_pk_fp8_f32 v44, v2, v14
	s_waitcnt lgkmcnt(5)
	v_mul_f32_e32 v2, 0x42000000, v46
	s_waitcnt lgkmcnt(3)
	v_mul_f32_e32 v42, 0x42000000, v50
	s_waitcnt lgkmcnt(2)
	v_mul_f32_e32 v46, 0x42000000, v52
	v_cvt_pk_fp8_f32 v45, v42, v46
	v_mul_f32_e32 v14, 0x42000000, v48
	v_cvt_pk_fp8_f32 v44, v2, v14 op_sel:[0,0,1]
	s_waitcnt lgkmcnt(1)
	v_mul_f32_e32 v2, 0x42000000, v54
	s_waitcnt lgkmcnt(0)
	v_mul_f32_e32 v14, 0x42000000, v56
	v_cvt_pk_fp8_f32 v45, v2, v14 op_sel:[0,0,1]
	v_or_b32_e32 v2, s0, v18
	v_mul_u32_u24_e32 v2, 0x500, v2
	v_lshl_add_u64 v[58:59], v[76:77], 0, v[2:3]
	v_mul_f32_e32 v2, 0x42000000, v15
	v_mul_f32_e32 v15, 0x42000000, v43
	global_store_dwordx2 v[58:59], v[44:45], off
	v_cvt_pk_fp8_f32 v14, v2, v15
	v_mul_f32_e32 v43, 0x42000000, v51
	v_mul_f32_e32 v44, 0x42000000, v53
	v_cvt_pk_fp8_f32 v15, v43, v44
	v_mul_f32_e32 v2, 0x42000000, v47
	v_mul_f32_e32 v42, 0x42000000, v49
	v_cvt_pk_fp8_f32 v14, v2, v42 op_sel:[0,0,1]
	v_mul_f32_e32 v2, 0x42000000, v55
	v_mul_f32_e32 v42, 0x42000000, v57
	v_cvt_pk_fp8_f32 v15, v2, v42 op_sel:[0,0,1]
	v_or_b32_e32 v2, s0, v19
	v_mul_u32_u24_e32 v2, 0x500, v2
	v_lshl_add_u64 v[42:43], v[76:77], 0, v[2:3]
	global_store_dwordx2 v[42:43], v[14:15], off
	s_waitcnt lgkmcnt(0)

; #define LAS __attribute__((address_space(3)))
; #define LDS_WAIT() asm volatile("s_waitcnt lgkmcnt(0)" ::: "memory")
;     ...
;     for (int i = 0; i < 8; ++i) wv[i] = __builtin_nontemporal_load((const f32x4*)(W + (size_t)(k0 + (lane >> 3) + 8 * i) * N + sc));
; #pragma unroll
;     for (int i = 0; i < 8; ++i) { LAS float* d = scr + ((lane >> 3) + 8 * i) * 33 + n4; d[0] = wv[i][0]; d[1] = wv[i][1]; d[2] = wv[i][2]; d[3] = wv[i][3]; }
;     LDS_WAIT();
;     const int c = lane & 7;
;     if (P8) {
; #pragma unroll
;         for (int j = 0; j < 4; ++j) { const int n = (lane >> 3) + 8 * j; const LAS float* s = scr + (8 * c) * 33 + n;
;             int w0 = 0, w1 = 0;
;             w0 = __builtin_amdgcn_cvt_pk_fp8_f32(s[0 * 33] * W8_SCALE, s[1 * 33] * W8_SCALE, w0, false); w0 = __builtin_amdgcn_cvt_pk_fp8_f32(s[2 * 33] * W8_SCALE, s[3 * 33] * W8_SCALE, w0, true);
;             w1 = __builtin_amdgcn_cvt_pk_fp8_f32(s[4 * 33] * W8_SCALE, s[5 * 33] * W8_SCALE, w1, false); w1 = __builtin_amdgcn_cvt_pk_fp8_f32(s[6 * 33] * W8_SCALE, s[7 * 33] * W8_SCALE, w1, true);
;             u32x2 o; o.x = (unsigned)w0; o.y = (unsigned)w1;
;             *(u32x2*)(B8 + (size_t)(n0 + n) * pitch + k0 + 8 * c) = o; }
;         LDS_WAIT(); return; }
.LBB0_17:
	s_andn2_b64 vcc, exec, s[0:1]
	s_cbranch_vccnz .LBB0_19
	s_add_i32 s0, s16, 0x500
	s_and_b32 s8, s0, 0x3c0
	s_add_i32 s0, s14, 0xfffde000
	s_and_b32 s0, s0, 0x3e0
	v_or_b32_e32 v2, s0, v1
	v_or_b32_e32 v42, s8, v16
	v_lshlrev_b32_e32 v2, 2, v2
	s_waitcnt lgkmcnt(0)
	v_lshl_add_u64 v[14:15], s[90:91], 0, v[2:3]
	v_lshlrev_b32_e32 v2, 12, v42
	v_lshl_add_u64 v[14:15], v[14:15], 0, v[2:3]
	v_add_co_u32_e32 v46, vcc, 0x8000, v14
	v_or_b32_e32 v2, s0, v16
	s_nop 0
	v_addc_co_u32_e32 v47, vcc, 0, v15, vcc
	v_add_co_u32_e32 v50, vcc, 0x10000, v14
	global_load_dwordx4 v[42:45], v[14:15], off nt
	s_nop 0
	global_load_dwordx4 v[46:49], v[46:47], off nt
	v_addc_co_u32_e32 v51, vcc, 0, v15, vcc
	v_add_co_u32_e32 v54, vcc, 0x18000, v14
	v_lshl_add_u64 v[76:77], v[8:9], 0, s[8:9]
	s_nop 0
	v_addc_co_u32_e32 v55, vcc, 0, v15, vcc
	v_add_co_u32_e32 v58, vcc, 0x20000, v14
	global_load_dwordx4 v[50:53], v[50:51], off nt
	s_nop 0
	global_load_dwordx4 v[54:57], v[54:55], off nt
	v_addc_co_u32_e32 v59, vcc, 0, v15, vcc
	v_add_co_u32_e32 v62, vcc, 0x28000, v14
	v_mul_u32_u24_e32 v2, 0x500, v2
	s_nop 0
	v_addc_co_u32_e32 v63, vcc, 0, v15, vcc
	global_load_dwordx4 v[58:61], v[58:59], off nt
	s_nop 0
	global_load_dwordx4 v[62:65], v[62:63], off nt
	v_add_co_u32_e32 v66, vcc, 0x30000, v14
	v_lshl_add_u64 v[78:79], v[76:77], 0, v[2:3]
	s_nop 0
	v_addc_co_u32_e32 v67, vcc, 0, v15, vcc
	global_load_dwordx4 v[66:69], v[66:67], off nt
	v_add_co_u32_e32 v14, vcc, 0x38000, v14
	s_nop 0
	v_addc_co_u32_e32 v15, vcc, 0, v15, vcc
	global_load_dwordx4 v[70:73], v[14:15], off nt
	s_waitcnt vmcnt(7)
	ds_write2_b32 v21, v42, v43 offset1:1
	ds_write2_b32 v21, v44, v45 offset0:2 offset1:3
	s_waitcnt vmcnt(6)
	ds_write2_b32 v22, v46, v47 offset1:1
	ds_write2_b32 v23, v48, v49 offset1:1
	s_waitcnt vmcnt(5)
	ds_write2_b32 v24, v50, v51 offset1:1
	ds_write2_b32 v25, v52, v53 offset1:1
	s_waitcnt vmcnt(4)
	ds_write2_b32 v26, v54, v55 offset1:1
	ds_write2_b32 v27, v56, v57 offset1:1
	s_waitcnt vmcnt(3)
	ds_write2_b32 v28, v58, v59 offset1:1
	ds_write2_b32 v29, v60, v61 offset1:1
	s_waitcnt vmcnt(2)
	ds_write2_b32 v30, v62, v63 offset1:1
	ds_write2_b32 v31, v64, v65 offset1:1
	s_waitcnt vmcnt(1)
	ds_write2_b32 v32, v66, v67 offset1:1
	ds_write2_b32 v33, v68, v69 offset1:1
	s_waitcnt vmcnt(0)
	ds_write2_b32 v34, v70, v71 offset1:1
	ds_write2_b32 v35, v72, v73 offset1:1
	s_waitcnt lgkmcnt(0)
	ds_read2_b32 v[42:43], v20 offset1:8
	ds_read2_b32 v[44:45], v20 offset0:33 offset1:41
	ds_read2_b32 v[46:47], v20 offset0:66 offset1:74
	ds_read2_b32 v[48:49], v20 offset0:99 offset1:107
	ds_read2_b32 v[50:51], v20 offset0:132 offset1:140
	ds_read2_b32 v[52:53], v20 offset0:165 offset1:173
	ds_read2_b32 v[54:55], v20 offset0:198 offset1:206
	ds_read2_b32 v[56:57], v20 offset0:231 offset1:239
	s_waitcnt lgkmcnt(7)
	v_mul_f32_e32 v2, 0x42000000, v42
	s_waitcnt lgkmcnt(6)
	v_mul_f32_e32 v42, 0x42000000, v44
	s_waitcnt lgkmcnt(5)
	v_mul_f32_e32 v44, 0x42000000, v46
	s_waitcnt lgkmcnt(4)
	v_mul_f32_e32 v46, 0x42000000, v48
	s_waitcnt lgkmcnt(3)
	v_mul_f32_e32 v48, 0x42000000, v50
	s_waitcnt lgkmcnt(2)
	v_mul_f32_e32 v50, 0x42000000, v52
	v_mul_f32_e32 v43, 0x42000000, v43
	v_mul_f32_e32 v45, 0x42000000, v45
	v_mul_f32_e32 v51, 0x42000000, v51
	v_mul_f32_e32 v53, 0x42000000, v53
	v_cvt_pk_fp8_f32 v14, v2, v42
	v_cvt_pk_fp8_f32 v15, v48, v50
	v_cvt_pk_fp8_f32 v74, v43, v45
	v_cvt_pk_fp8_f32 v75, v51, v53
	s_waitcnt lgkmcnt(1)
	v_mul_f32_e32 v52, 0x42000000, v54
	s_waitcnt lgkmcnt(0)
	v_mul_f32_e32 v54, 0x42000000, v56
	v_mul_f32_e32 v47, 0x42000000, v47
	v_mul_f32_e32 v49, 0x42000000, v49
	v_mul_f32_e32 v55, 0x42000000, v55
	v_cvt_pk_fp8_f32 v14, v44, v46 op_sel:[0,0,1]
	v_cvt_pk_fp8_f32 v15, v52, v54 op_sel:[0,0,1]
	v_mul_f32_e32 v2, 0x42000000, v57
	v_cvt_pk_fp8_f32 v74, v47, v49 op_sel:[0,0,1]
	v_cvt_pk_fp8_f32 v75, v55, v2 op_sel:[0,0,1]
	v_or_b32_e32 v2, s0, v17
	v_mul_u32_u24_e32 v2, 0x500, v2
	global_store_dwordx2 v[78:79], v[14:15], off
	v_lshl_add_u64 v[44:45], v[76:77], 0, v[2:3]
	ds_read2_b32 v[14:15], v20 offset0:16 offset1:24
	ds_read2_b32 v[42:43], v20 offset0:49 offset1:57
	global_store_dwordx2 v[44:45], v[74:75], off
	ds_read2_b32 v[46:47], v20 offset0:82 offset1:90
	ds_read2_b32 v[48:49], v20 offset0:115 offset1:123
	ds_read2_b32 v[50:51], v20 offset0:148 offset1:156
	ds_read2_b32 v[52:53], v20 offset0:181 offset1:189
	s_waitcnt lgkmcnt(5)
	v_mul_f32_e32 v2, 0x42000000, v14
	s_waitcnt lgkmcnt(4)
	v_mul_f32_e32 v14, 0x42000000, v42
	ds_read2_b32 v[54:55], v20 offset0:214 offset1:222
	ds_read2_b32 v[56:57], v20 offset0:247 offset1:255
	v_cvt_pk_fp8_f32 v44, v2, v14
	s_waitcnt lgkmcnt(5)
	v_mul_f32_e32 v2, 0x42000000, v46
	s_waitcnt lgkmcnt(3)
	v_mul_f32_e32 v42, 0x42000000, v50
	s_waitcnt lgkmcnt(2)
	v_mul_f32_e32 v46, 0x42000000, v52
	v_cvt_pk_fp8_f32 v45, v42, v46
	v_mul_f32_e32 v14, 0x42000000, v48
	v_cvt_pk_fp8_f32 v44, v2, v14 op_sel:[0,0,1]
	s_waitcnt lgkmcnt(1)
	v_mul_f32_e32 v2, 0x42000000, v54
	s_waitcnt lgkmcnt(0)
	v_mul_f32_e32 v14, 0x42000000, v56
	v_cvt_pk_fp8_f32 v45, v2, v14 op_sel:[0,0,1]
	v_or_b32_e32 v2, s0, v18
	v_mul_u32_u24_e32 v2, 0x500, v2
	v_lshl_add_u64 v[58:59], v[76:77], 0, v[2:3]
	v_mul_f32_e32 v2, 0x42000000, v15
	v_mul_f32_e32 v15, 0x42000000, v43
	global_store_dwordx2 v[58:59], v[44:45], off
	v_cvt_pk_fp8_f32 v14, v2, v15
	v_mul_f32_e32 v43, 0x42000000, v51
	v_mul_f32_e32 v44, 0x42000000, v53
	v_cvt_pk_fp8_f32 v15, v43, v44
	v_mul_f32_e32 v2, 0x42000000, v47
	v_mul_f32_e32 v42, 0x42000000, v49
	v_cvt_pk_fp8_f32 v14, v2, v42 op_sel:[0,0,1]
	v_mul_f32_e32 v2, 0x42000000, v55
	v_mul_f32_e32 v42, 0x42000000, v57
	v_cvt_pk_fp8_f32 v15, v2, v42 op_sel:[0,0,1]
	v_or_b32_e32 v2, s0, v19
	v_mul_u32_u24_e32 v2, 0x500, v2
	v_lshl_add_u64 v[42:43], v[76:77], 0, v[2:3]
	global_store_dwordx2 v[42:43], v[14:15], off
	s_waitcnt lgkmcnt(0)

; #define LAS __attribute__((address_space(3)))
; #define LDS_WAIT() asm volatile("s_waitcnt lgkmcnt(0)" ::: "memory")
;     if (pitch == 0) pitch = K;
;     const int nblk = N / 32, kb = item / nblk, nb = item % nblk, k0 = 64 * kb, n0 = 32 * nb;
;     const int n4 = (lane & 7) * 4, sc = MAP ? src_col(n0 + n4) : (n0 + n4);
;     f32x4 wv[8];
; #pragma unroll
;     for (int i = 0; i < 8; ++i) wv[i] = __builtin_nontemporal_load((const f32x4*)(W + (size_t)(k0 + (lane >> 3) + 8 * i) * N + sc));
; #pragma unroll
;     for (int i = 0; i < 8; ++i) { LAS float* d = scr + ((lane >> 3) + 8 * i) * 33 + n4; d[0] = wv[i][0]; d[1] = wv[i][1]; d[2] = wv[i][2]; d[3] = wv[i][3]; }
;     LDS_WAIT();
;     const int c = lane & 7;
;     if (P8) {
; #pragma unroll
;         for (int j = 0; j < 4; ++j) { const int n = (lane >> 3) + 8 * j; const LAS float* s = scr + (8 * c) * 33 + n;
;             int w0 = 0, w1 = 0;
;             w0 = __builtin_amdgcn_cvt_pk_fp8_f32(s[0 * 33] * W8_SCALE, s[1 * 33] * W8_SCALE, w0, false); w0 = __builtin_amdgcn_cvt_pk_fp8_f32(s[2 * 33] * W8_SCALE, s[3 * 33] * W8_SCALE, w0, true);
;             w1 = __builtin_amdgcn_cvt_pk_fp8_f32(s[4 * 33] * W8_SCALE, s[5 * 33] * W8_SCALE, w1, false); w1 = __builtin_amdgcn_cvt_pk_fp8_f32(s[6 * 33] * W8_SCALE, s[7 * 33] * W8_SCALE, w1, true);
;             u32x2 o; o.x = (unsigned)w0; o.y = (unsigned)w1;
;             *(u32x2*)(B8 + (size_t)(n0 + n) * pitch + k0 + 8 * c) = o; }
;         LDS_WAIT(); return; }
;     if (MAP) { const int pn = n0 >> 8;
;         if (pn < 10 || pn >= 26) {
;             const int q = pn < 10 ? pn : pn - 16;
; #pragma unroll
;             for (int j = 0; j < 4; ++j) { const int n = (lane >> 3) + 8 * j; const LAS float* s = scr + (8 * c) * 33 + n;
;                 int w0 = 0, w1 = 0;
;                 w0 = __builtin_amdgcn_cvt_pk_fp8_f32(s[0 * 33] * W8_SCALE, s[1 * 33] * W8_SCALE, w0, false); w0 = __builtin_amdgcn_cvt_pk_fp8_f32(s[2 * 33] * W8_SCALE, s[3 * 33] * W8_SCALE, w0, true);
;                 w1 = __builtin_amdgcn_cvt_pk_fp8_f32(s[4 * 33] * W8_SCALE, s[5 * 33] * W8_SCALE, w1, false); w1 = __builtin_amdgcn_cvt_pk_fp8_f32(s[6 * 33] * W8_SCALE, s[7 * 33] * W8_SCALE, w1, true);
;                 u32x2 o; o.x = (unsigned)w0; o.y = (unsigned)w1;
;                 *(u32x2*)(B8 + (size_t)(q * 256 + (n0 & 255) + n) * 1024 + k0 + 8 * c) = o; }
;             LDS_WAIT(); return; } }
.LBB0_30:
	s_lshl_b32 s0, s21, 6
	v_or_b32_e32 v2, s0, v16
	v_ashrrev_i32_e32 v15, 31, v14
	s_waitcnt lgkmcnt(0)
	v_lshl_add_u64 v[14:15], v[14:15], 2, s[84:85]
	v_or_b32_e32 v44, 8, v2
	v_or_b32_e32 v50, 16, v2
	v_or_b32_e32 v52, 24, v2
	v_or_b32_e32 v58, 32, v2
	v_or_b32_e32 v60, 40, v2
	v_mad_i64_i32 v[42:43], s[10:11], v2, s19, v[14:15]
	v_mad_i64_i32 v[46:47], s[10:11], v44, s19, v[14:15]
	v_mad_i64_i32 v[50:51], s[10:11], v50, s19, v[14:15]
	v_mad_i64_i32 v[54:55], s[10:11], v52, s19, v[14:15]
	v_mad_i64_i32 v[58:59], s[10:11], v58, s19, v[14:15]
	v_mad_i64_i32 v[62:63], s[10:11], v60, s19, v[14:15]
	global_load_dwordx4 v[42:45], v[42:43], off nt
	s_nop 0
	global_load_dwordx4 v[46:49], v[46:47], off nt
	s_nop 0
	global_load_dwordx4 v[50:53], v[50:51], off nt
	s_nop 0
	global_load_dwordx4 v[54:57], v[54:55], off nt
	s_nop 0
	global_load_dwordx4 v[58:61], v[58:59], off nt
	s_nop 0
	global_load_dwordx4 v[62:65], v[62:63], off nt
	v_or_b32_e32 v66, 48, v2
	v_mad_i64_i32 v[66:67], s[10:11], v66, s19, v[14:15]
	global_load_dwordx4 v[66:69], v[66:67], off nt
	v_or_b32_e32 v2, 56, v2
	v_mad_i64_i32 v[14:15], s[10:11], v2, s19, v[14:15]
	global_load_dwordx4 v[70:73], v[14:15], off nt
	s_add_i32 s1, s20, -10
	s_cmp_gt_u32 s1, 15
	s_mov_b64 s[10:11], -1
	s_waitcnt vmcnt(7)
	ds_write2_b32 v21, v42, v43 offset1:1
	ds_write2_b32 v21, v44, v45 offset0:2 offset1:3
	s_waitcnt vmcnt(6)
	ds_write2_b32 v22, v46, v47 offset1:1
	ds_write2_b32 v23, v48, v49 offset1:1
	s_waitcnt vmcnt(5)
	ds_write2_b32 v24, v50, v51 offset1:1
	ds_write2_b32 v25, v52, v53 offset1:1
	s_waitcnt vmcnt(4)
	ds_write2_b32 v26, v54, v55 offset1:1
	ds_write2_b32 v27, v56, v57 offset1:1
	s_waitcnt vmcnt(3)
	ds_write2_b32 v28, v58, v59 offset1:1
	ds_write2_b32 v29, v60, v61 offset1:1
	s_waitcnt vmcnt(2)
	ds_write2_b32 v30, v62, v63 offset1:1
	ds_write2_b32 v31, v64, v65 offset1:1
	s_waitcnt vmcnt(1)
	ds_write2_b32 v32, v66, v67 offset1:1
	ds_write2_b32 v33, v68, v69 offset1:1
	s_waitcnt vmcnt(0)
	ds_write2_b32 v34, v70, v71 offset1:1
	ds_write2_b32 v35, v72, v73 offset1:1
	s_waitcnt lgkmcnt(0)
	s_cbranch_scc0 .LBB0_32
	ds_read2_b32 v[14:15], v20 offset1:8
	ds_read2_b32 v[42:43], v20 offset0:33 offset1:41
	ds_read2_b32 v[48:49], v20 offset0:66 offset1:74
	ds_read2_b32 v[50:51], v20 offset0:99 offset1:107
	ds_read2_b32 v[52:53], v20 offset0:132 offset1:140
	ds_read2_b32 v[54:55], v20 offset0:165 offset1:173
	ds_read2_b32 v[56:57], v20 offset0:198 offset1:206
	ds_read2_b32 v[58:59], v20 offset0:231 offset1:239
	s_waitcnt lgkmcnt(7)
	v_mul_f32_e32 v2, 0x42000000, v14
	s_waitcnt lgkmcnt(6)
	v_mul_f32_e32 v14, 0x42000000, v42
	s_lshl_b32 s1, s20, 8
	v_cvt_pk_fp8_f32 v46, v2, v14
	s_waitcnt lgkmcnt(5)
	v_mul_f32_e32 v2, 0x42000000, v48
	s_waitcnt lgkmcnt(3)
	v_mul_f32_e32 v42, 0x42000000, v52
	s_waitcnt lgkmcnt(2)
	v_mul_f32_e32 v48, 0x42000000, v54
	s_add_i32 s10, s1, 0xfffff000
	v_cvt_pk_fp8_f32 v47, v42, v48
	s_cmp_lt_i32 s20, 10
	s_cselect_b32 s1, s1, s10
	s_and_b32 s10, s8, 0xe0
	v_mul_f32_e32 v14, 0x42000000, v50
	s_or_b32 s10, s1, s10
	v_cvt_pk_fp8_f32 v46, v2, v14 op_sel:[0,0,1]
	s_waitcnt lgkmcnt(1)
	v_mul_f32_e32 v2, 0x42000000, v56
	s_waitcnt lgkmcnt(0)
	v_mul_f32_e32 v14, 0x42000000, v58
	v_cvt_pk_fp8_f32 v47, v2, v14 op_sel:[0,0,1]
	v_or_b32_e32 v60, s10, v16
	s_ashr_i32 s1, s0, 31
	v_ashrrev_i32_e32 v61, 31, v60
	v_lshl_add_u64 v[44:45], v[10:11], 0, s[0:1]
	v_lshlrev_b64 v[60:61], 10, v[60:61]
	v_lshl_add_u64 v[60:61], v[44:45], 0, v[60:61]
	v_mul_f32_e32 v2, 0x42000000, v15
	v_mul_f32_e32 v15, 0x42000000, v43
	global_store_dwordx2 v[60:61], v[46:47], off
	v_cvt_pk_fp8_f32 v14, v2, v15
	v_mul_f32_e32 v43, 0x42000000, v53
	v_mul_f32_e32 v46, 0x42000000, v55
	v_cvt_pk_fp8_f32 v15, v43, v46
	v_mul_f32_e32 v2, 0x42000000, v49
	v_mul_f32_e32 v42, 0x42000000, v51
	v_cvt_pk_fp8_f32 v14, v2, v42 op_sel:[0,0,1]
	v_mul_f32_e32 v2, 0x42000000, v57
	v_mul_f32_e32 v42, 0x42000000, v59
	v_cvt_pk_fp8_f32 v15, v2, v42 op_sel:[0,0,1]
	v_or_b32_e32 v42, s10, v17
	v_ashrrev_i32_e32 v43, 31, v42
	v_lshlrev_b64 v[42:43], 10, v[42:43]
	v_lshl_add_u64 v[42:43], v[44:45], 0, v[42:43]
	ds_read2_b32 v[46:47], v20 offset0:16 offset1:24
	ds_read2_b32 v[48:49], v20 offset0:49 offset1:57
	global_store_dwordx2 v[42:43], v[14:15], off
	ds_read2_b32 v[42:43], v20 offset0:82 offset1:90
	ds_read2_b32 v[50:51], v20 offset0:115 offset1:123
	ds_read2_b32 v[52:53], v20 offset0:148 offset1:156
	ds_read2_b32 v[54:55], v20 offset0:181 offset1:189
	s_waitcnt lgkmcnt(5)
	v_mul_f32_e32 v2, 0x42000000, v46
	s_waitcnt lgkmcnt(4)
	v_mul_f32_e32 v15, 0x42000000, v48
	ds_read2_b32 v[56:57], v20 offset0:214 offset1:222
	ds_read2_b32 v[58:59], v20 offset0:247 offset1:255
	v_cvt_pk_fp8_f32 v14, v2, v15
	s_waitcnt lgkmcnt(3)
	v_mul_f32_e32 v46, 0x42000000, v52
	s_waitcnt lgkmcnt(2)
	v_mul_f32_e32 v48, 0x42000000, v54
	v_cvt_pk_fp8_f32 v15, v46, v48
	v_mul_f32_e32 v2, 0x42000000, v42
	v_mul_f32_e32 v42, 0x42000000, v50
	v_cvt_pk_fp8_f32 v14, v2, v42 op_sel:[0,0,1]
	s_waitcnt lgkmcnt(1)
	v_mul_f32_e32 v2, 0x42000000, v56
	s_waitcnt lgkmcnt(0)
	v_mul_f32_e32 v42, 0x42000000, v58
	v_cvt_pk_fp8_f32 v15, v2, v42 op_sel:[0,0,1]
	v_or_b32_e32 v60, s10, v18
	v_ashrrev_i32_e32 v61, 31, v60
	v_lshlrev_b64 v[60:61], 10, v[60:61]
	v_lshl_add_u64 v[60:61], v[44:45], 0, v[60:61]
	global_store_dwordx2 v[60:61], v[14:15], off
	v_mul_f32_e32 v2, 0x42000000, v47
	v_mul_f32_e32 v15, 0x42000000, v49
	v_cvt_pk_fp8_f32 v14, v2, v15
	v_mul_f32_e32 v2, 0x42000000, v43
	v_mul_f32_e32 v43, 0x42000000, v53
	v_mul_f32_e32 v46, 0x42000000, v55
	v_cvt_pk_fp8_f32 v15, v43, v46
	v_mul_f32_e32 v42, 0x42000000, v51
	v_cvt_pk_fp8_f32 v14, v2, v42 op_sel:[0,0,1]
	v_mul_f32_e32 v2, 0x42000000, v57
	v_mul_f32_e32 v42, 0x42000000, v59
	v_cvt_pk_fp8_f32 v15, v2, v42 op_sel:[0,0,1]
	v_or_b32_e32 v42, s10, v19
	v_ashrrev_i32_e32 v43, 31, v42
	v_lshlrev_b64 v[42:43], 10, v[42:43]
	v_lshl_add_u64 v[42:43], v[44:45], 0, v[42:43]
	global_store_dwordx2 v[42:43], v[14:15], off
	s_waitcnt lgkmcnt(0)
	s_mov_b64 s[10:11], 0

; __device__ __forceinline__ unsigned cvt_pk_bf16(float lo, float hi) { f32x2_t v = {lo, hi}; bf16x2_t r = __builtin_convertvector(v, bf16x2_t); return __builtin_bit_cast(unsigned, r); }
; __global__ void __launch_bounds__(NTHREADS, 2) fwd(Params p) {
;     ...
;     for (int m4 = (bid < 48) ? bid * NWAVES + wave : 768 + (bid - 48) * NWAVES + wave; m4 < ((bid < 48) ? 768 : M / 4); m4 += (bid < 48) ? 48 * NWAVES : (G - 48) * NWAVES) {
;         const int m = m4 * 4;
;         const float* ad = ADA + (size_t)(m >> 11) * 3072;
;         f32x4 sh[4], sc[4], v[4][4];
; #pragma unroll
;         for (int r = 0; r < 4; ++r)
; #pragma unroll
;             for (int j = 0; j < 4; ++j) v[r][j] = __builtin_nontemporal_load((const f32x4*)(p.x + (size_t)(m + r) * D) + lane + 64 * j);
; #pragma unroll
;         for (int j = 0; j < 4; ++j) { sh[j] = *((const f32x4*)ad + lane + 64 * j); sc[j] = *((const f32x4*)(ad + 1024) + lane + 64 * j) + 1.0f; }
; #pragma unroll
;         for (int r = 0; r < 4; ++r) { unsigned long long* o8 = (unsigned long long*)(H + (size_t)(m + r) * D) + lane;
; #pragma unroll
;             for (int j = 0; j < 4; ++j) { const f32x4 h = v[r][j] * sc[j] + sh[j];
;                 o8[64 * j] = (unsigned long long)cvt_pk_bf16(h[0], h[1]) | ((unsigned long long)cvt_pk_bf16(h[2], h[3]) << 32);
;                 int w8 = 0; w8 = __builtin_amdgcn_cvt_pk_fp8_f32(h[0], h[1], w8, false); w8 = __builtin_amdgcn_cvt_pk_fp8_f32(h[2], h[3], w8, true);
;                 *((unsigned*)((unsigned char*)p.out + DO_H8 + (size_t)(m + r) * D) + lane + 64 * j) = (unsigned)w8; } }
.LBB0_54:
	s_ashr_i32 s7, s12, 9
	s_ashr_i32 s1, s0, 31
	s_add_i32 s6, s0, 1
	s_add_i32 s8, s0, 2
	s_add_i32 s10, s0, 3
	s_mul_hi_i32 s17, s7, 0x3000
	s_mul_i32 s24, s7, 0x3000
	s_lshl_b64 s[18:19], s[0:1], 12
	s_ashr_i32 s7, s6, 31
	s_ashr_i32 s9, s8, 31
	s_ashr_i32 s11, s10, 31
	v_lshl_add_u64 v[0:1], v[4:5], 0, s[18:19]
	s_lshl_b64 s[18:19], s[6:7], 12
	s_lshl_b64 s[20:21], s[8:9], 12
	s_lshl_b64 s[22:23], s[10:11], 12
	global_load_dwordx4 v[10:13], v[0:1], off nt
	global_load_dwordx4 v[14:17], v[0:1], off offset:1024 nt
	global_load_dwordx4 v[18:21], v[0:1], off offset:2048 nt
	global_load_dwordx4 v[22:25], v[0:1], off offset:3072 nt
	v_lshl_add_u64 v[0:1], v[4:5], 0, s[18:19]
	s_add_u32 s18, s96, s24
	v_lshl_add_u64 v[54:55], v[4:5], 0, s[20:21]
	v_lshl_add_u64 v[70:71], v[4:5], 0, s[22:23]
	s_addc_u32 s19, s97, s17
	global_load_dwordx4 v[26:29], v[0:1], off nt
	global_load_dwordx4 v[30:33], v[0:1], off offset:1024 nt
	global_load_dwordx4 v[34:37], v[0:1], off offset:2048 nt
	global_load_dwordx4 v[38:41], v[0:1], off offset:3072 nt
	global_load_dwordx4 v[42:45], v[54:55], off nt
	global_load_dwordx4 v[46:49], v[54:55], off offset:1024 nt
	global_load_dwordx4 v[50:53], v[54:55], off offset:2048 nt
	s_nop 0
	global_load_dwordx4 v[54:57], v[54:55], off offset:3072 nt
	s_nop 0
	global_load_dwordx4 v[58:61], v[70:71], off nt
	global_load_dwordx4 v[62:65], v[70:71], off offset:1024 nt
	global_load_dwordx4 v[66:69], v[70:71], off offset:2048 nt
	s_nop 0
	global_load_dwordx4 v[70:73], v[70:71], off offset:3072 nt
	v_lshl_add_u64 v[0:1], s[18:19], 0, v[2:3]
	v_lshl_add_u64 v[102:103], v[0:1], 0, s[4:5]
	v_add_co_u32_e32 v0, vcc, s16, v0
	global_load_dwordx4 v[74:77], v2, s[18:19]
	global_load_dwordx4 v[78:81], v2, s[18:19] offset:1024
	global_load_dwordx4 v[82:85], v2, s[18:19] offset:2048
	global_load_dwordx4 v[86:89], v2, s[18:19] offset:3072
	v_addc_co_u32_e32 v1, vcc, 0, v1, vcc
	global_load_dwordx4 v[90:93], v[0:1], off
	global_load_dwordx4 v[94:97], v[102:103], off offset:1024
	global_load_dwordx4 v[98:101], v[102:103], off offset:2048
	s_nop 0
	global_load_dwordx4 v[102:105], v[102:103], off offset:3072
	s_lshl_b64 s[20:21], s[0:1], 10
	s_lshl_b64 s[22:23], s[0:1], 11
	s_lshl_b64 s[24:25], s[6:7], 10
	s_lshl_b64 s[6:7], s[6:7], 11
	s_lshl_b64 s[26:27], s[8:9], 10
	s_lshl_b64 s[8:9], s[8:9], 11
	s_lshl_b64 s[28:29], s[10:11], 10
	s_lshl_b64 s[10:11], s[10:11], 11
	s_add_i32 s12, s12, s14
	s_add_i32 s0, s0, s15
	v_lshl_add_u64 v[106:107], v[6:7], 0, s[22:23]
	v_lshl_add_u64 v[108:109], v[8:9], 0, s[20:21]
	s_cmp_ge_i32 s12, s13
	v_lshl_add_u64 v[110:111], v[6:7], 0, s[6:7]
	v_lshl_add_u64 v[112:113], v[8:9], 0, s[24:25]
	v_lshl_add_u64 v[114:115], v[6:7], 0, s[8:9]
	v_lshl_add_u64 v[116:117], v[8:9], 0, s[26:27]
	v_lshl_add_u64 v[118:119], v[6:7], 0, s[10:11]
	v_lshl_add_u64 v[120:121], v[8:9], 0, s[28:29]
	s_waitcnt vmcnt(3)
	v_pk_add_f32 v[90:91], v[90:91], 1.0 op_sel_hi:[1,0]
	s_waitcnt vmcnt(2)
	v_pk_add_f32 v[94:95], v[94:95], 1.0 op_sel_hi:[1,0]
	v_pk_fma_f32 v[10:11], v[90:91], v[10:11], v[74:75]
	s_waitcnt vmcnt(1)
	v_pk_add_f32 v[98:99], v[98:99], 1.0 op_sel_hi:[1,0]
	v_pk_fma_f32 v[14:15], v[94:95], v[14:15], v[78:79]
	v_cvt_pk_fp8_f32 v122, v10, v11
	s_waitcnt vmcnt(0)
; __device__ __forceinline__ unsigned cvt_pk_bf16(float lo, float hi) { f32x2_t v = {lo, hi}; bf16x2_t r = __builtin_convertvector(v, bf16x2_t); return __builtin_bit_cast(unsigned, r); }
; __global__ void __launch_bounds__(NTHREADS, 2) fwd(Params p) {
;     ...
;         for (int r = 0; r < 4; ++r)
; #pragma unroll
;             for (int j = 0; j < 4; ++j) v[r][j] = __builtin_nontemporal_load((const f32x4*)(p.x + (size_t)(m + r) * D) + lane + 64 * j);
; #pragma unroll
;         for (int j = 0; j < 4; ++j) { sh[j] = *((const f32x4*)ad + lane + 64 * j); sc[j] = *((const f32x4*)(ad + 1024) + lane + 64 * j) + 1.0f; }
; #pragma unroll
;         for (int r = 0; r < 4; ++r) { unsigned long long* o8 = (unsigned long long*)(H + (size_t)(m + r) * D) + lane;
; #pragma unroll
;             for (int j = 0; j < 4; ++j) { const f32x4 h = v[r][j] * sc[j] + sh[j];
;                 o8[64 * j] = (unsigned long long)cvt_pk_bf16(h[0], h[1]) | ((unsigned long long)cvt_pk_bf16(h[2], h[3]) << 32);
;                 int w8 = 0; w8 = __builtin_amdgcn_cvt_pk_fp8_f32(h[0], h[1], w8, false); w8 = __builtin_amdgcn_cvt_pk_fp8_f32(h[2], h[3], w8, true);
;                 *((unsigned*)((unsigned char*)p.out + DO_H8 + (size_t)(m + r) * D) + lane + 64 * j) = (unsigned)w8; } }
	v_pk_add_f32 v[102:103], v[102:103], 1.0 op_sel_hi:[1,0]
	v_pk_fma_f32 v[18:19], v[98:99], v[18:19], v[82:83]
	v_cvt_pk_fp8_f32 v123, v14, v15
	v_pk_add_f32 v[0:1], v[92:93], 1.0 op_sel_hi:[1,0]
	v_pk_fma_f32 v[22:23], v[102:103], v[22:23], v[86:87]
	v_cvt_pk_fp8_f32 v124, v18, v19
	v_pk_add_f32 v[92:93], v[96:97], 1.0 op_sel_hi:[1,0]
	v_pk_fma_f32 v[12:13], v[0:1], v[12:13], v[76:77]
	v_pk_fma_f32 v[26:27], v[90:91], v[26:27], v[74:75]
	v_pk_fma_f32 v[30:31], v[94:95], v[30:31], v[78:79]
	v_pk_fma_f32 v[34:35], v[98:99], v[34:35], v[82:83]
	v_pk_fma_f32 v[38:39], v[102:103], v[38:39], v[86:87]
	v_pk_fma_f32 v[42:43], v[90:91], v[42:43], v[74:75]
	v_pk_fma_f32 v[46:47], v[94:95], v[46:47], v[78:79]
	v_pk_fma_f32 v[50:51], v[98:99], v[50:51], v[82:83]
	v_pk_fma_f32 v[54:55], v[102:103], v[54:55], v[86:87]
	v_pk_fma_f32 v[58:59], v[90:91], v[58:59], v[74:75]
	v_pk_fma_f32 v[62:63], v[94:95], v[62:63], v[78:79]
	v_pk_fma_f32 v[66:67], v[98:99], v[66:67], v[82:83]
	v_pk_fma_f32 v[70:71], v[102:103], v[70:71], v[86:87]
	v_cvt_pk_fp8_f32 v125, v22, v23
	v_pk_add_f32 v[96:97], v[100:101], 1.0 op_sel_hi:[1,0]
	v_pk_fma_f32 v[16:17], v[92:93], v[16:17], v[80:81]
	v_cvt_pk_fp8_f32 v126, v26, v27
	v_cvt_pk_fp8_f32 v127, v30, v31
	v_cvt_pk_fp8_f32 v128, v34, v35
	v_cvt_pk_fp8_f32 v129, v38, v39
	v_cvt_pk_fp8_f32 v130, v42, v43
	v_cvt_pk_fp8_f32 v131, v46, v47
	v_cvt_pk_fp8_f32 v132, v50, v51
	v_cvt_pk_fp8_f32 v133, v54, v55
	v_cvt_pk_fp8_f32 v134, v58, v59
	v_cvt_pk_fp8_f32 v135, v62, v63
	v_cvt_pk_fp8_f32 v136, v66, v67
	v_cvt_pk_fp8_f32 v137, v70, v71
	v_cvt_pk_fp8_f32 v122, v12, v13 op_sel:[0,0,1]
	v_pk_add_f32 v[100:101], v[104:105], 1.0 op_sel_hi:[1,0]
	v_pk_fma_f32 v[20:21], v[96:97], v[20:21], v[84:85]
	v_cvt_pk_fp8_f32 v123, v16, v17 op_sel:[0,0,1]
	v_pk_fma_f32 v[24:25], v[100:101], v[24:25], v[88:89]
	v_cvt_pk_fp8_f32 v124, v20, v21 op_sel:[0,0,1]
	v_pk_fma_f32 v[28:29], v[0:1], v[28:29], v[76:77]
	v_pk_fma_f32 v[32:33], v[92:93], v[32:33], v[80:81]
	v_pk_fma_f32 v[36:37], v[96:97], v[36:37], v[84:85]
	v_pk_fma_f32 v[40:41], v[100:101], v[40:41], v[88:89]
	v_pk_fma_f32 v[44:45], v[0:1], v[44:45], v[76:77]
	v_pk_fma_f32 v[48:49], v[92:93], v[48:49], v[80:81]
	v_pk_fma_f32 v[52:53], v[96:97], v[52:53], v[84:85]
	v_pk_fma_f32 v[56:57], v[100:101], v[56:57], v[88:89]
	v_pk_fma_f32 v[0:1], v[0:1], v[60:61], v[76:77]
	v_pk_fma_f32 v[60:61], v[92:93], v[64:65], v[80:81]
	v_pk_fma_f32 v[64:65], v[96:97], v[68:69], v[84:85]
	v_pk_fma_f32 v[68:69], v[100:101], v[72:73], v[88:89]
	v_cvt_pk_bf16_f32 v72, v10, v11
	v_cvt_pk_bf16_f32 v73, v12, v13
	v_cvt_pk_fp8_f32 v125, v24, v25 op_sel:[0,0,1]
	v_cvt_pk_bf16_f32 v10, v14, v15
	v_cvt_pk_bf16_f32 v11, v16, v17
	v_cvt_pk_bf16_f32 v14, v18, v19
	v_cvt_pk_bf16_f32 v15, v20, v21
	v_cvt_pk_bf16_f32 v18, v22, v23
	v_cvt_pk_bf16_f32 v19, v24, v25
	v_cvt_pk_bf16_f32 v22, v26, v27
	v_cvt_pk_bf16_f32 v23, v28, v29
	v_cvt_pk_bf16_f32 v26, v30, v31
	v_cvt_pk_bf16_f32 v27, v32, v33
	v_cvt_pk_bf16_f32 v30, v34, v35
	v_cvt_pk_bf16_f32 v31, v36, v37
	v_cvt_pk_bf16_f32 v34, v38, v39
	v_cvt_pk_bf16_f32 v35, v40, v41
	v_cvt_pk_bf16_f32 v38, v42, v43
	v_cvt_pk_bf16_f32 v39, v44, v45
	v_cvt_pk_bf16_f32 v42, v46, v47
	v_cvt_pk_bf16_f32 v43, v48, v49
	v_cvt_pk_bf16_f32 v46, v50, v51
	v_cvt_pk_bf16_f32 v47, v52, v53
	v_cvt_pk_bf16_f32 v50, v54, v55
	v_cvt_pk_bf16_f32 v51, v56, v57
	v_cvt_pk_bf16_f32 v54, v58, v59
	v_cvt_pk_bf16_f32 v55, v0, v1
	v_cvt_pk_bf16_f32 v58, v62, v63
	v_cvt_pk_bf16_f32 v59, v60, v61
	v_cvt_pk_bf16_f32 v62, v66, v67
	v_cvt_pk_bf16_f32 v63, v64, v65
	v_cvt_pk_bf16_f32 v66, v70, v71
	v_cvt_pk_bf16_f32 v67, v68, v69
	global_store_dwordx2 v[106:107], v[72:73], off
	global_store_dwordx2 v[106:107], v[10:11], off offset:512
	global_store_dwordx2 v[106:107], v[14:15], off offset:1024
	global_store_dwordx2 v[106:107], v[18:19], off offset:1536
	global_store_dwordx2 v[110:111], v[22:23], off
	global_store_dwordx2 v[110:111], v[26:27], off offset:512
	global_store_dwordx2 v[110:111], v[30:31], off offset:1024
	global_store_dwordx2 v[110:111], v[34:35], off offset:1536
	global_store_dwordx2 v[114:115], v[38:39], off
	global_store_dwordx2 v[114:115], v[42:43], off offset:512
	global_store_dwordx2 v[114:115], v[46:47], off offset:1024
	global_store_dwordx2 v[114:115], v[50:51], off offset:1536
	global_store_dwordx2 v[118:119], v[54:55], off
	global_store_dwordx2 v[118:119], v[58:59], off offset:512
	global_store_dwordx2 v[118:119], v[62:63], off offset:1024
	global_store_dwordx2 v[118:119], v[66:67], off offset:1536
	v_cvt_pk_fp8_f32 v126, v28, v29 op_sel:[0,0,1]
	v_cvt_pk_fp8_f32 v127, v32, v33 op_sel:[0,0,1]
	v_cvt_pk_fp8_f32 v128, v36, v37 op_sel:[0,0,1]
	v_cvt_pk_fp8_f32 v129, v40, v41 op_sel:[0,0,1]
	v_cvt_pk_fp8_f32 v130, v44, v45 op_sel:[0,0,1]
	v_cvt_pk_fp8_f32 v131, v48, v49 op_sel:[0,0,1]
	v_cvt_pk_fp8_f32 v132, v52, v53 op_sel:[0,0,1]
	v_cvt_pk_fp8_f32 v133, v56, v57 op_sel:[0,0,1]
	v_cvt_pk_fp8_f32 v134, v0, v1 op_sel:[0,0,1]
	v_cvt_pk_fp8_f32 v135, v60, v61 op_sel:[0,0,1]
	v_cvt_pk_fp8_f32 v136, v64, v65 op_sel:[0,0,1]
	v_cvt_pk_fp8_f32 v137, v68, v69 op_sel:[0,0,1]
	global_store_dword v[108:109], v122, off
	global_store_dword v[108:109], v123, off offset:256
	global_store_dword v[108:109], v124, off offset:512
	global_store_dword v[108:109], v125, off offset:768
	global_store_dword v[112:113], v126, off
	global_store_dword v[112:113], v127, off offset:256
	global_store_dword v[112:113], v128, off offset:512
	global_store_dword v[112:113], v129, off offset:768
	global_store_dword v[116:117], v130, off
	global_store_dword v[116:117], v131, off offset:256
	global_store_dword v[116:117], v132, off offset:512
	global_store_dword v[116:117], v133, off offset:768
	global_store_dword v[120:121], v134, off
	global_store_dword v[120:121], v135, off offset:256
	global_store_dword v[120:121], v136, off offset:512
	global_store_dword v[120:121], v137, off offset:768
	s_cbranch_scc0 .LBB0_54

; __device__ __forceinline__ unsigned cvt_pk_bf16(float lo, float hi) { f32x2_t v = {lo, hi}; bf16x2_t r = __builtin_convertvector(v, bf16x2_t); return __builtin_bit_cast(unsigned, r); }
; __device__ __forceinline__ float f8c(float v) { return fminf(fmaxf(v, -448.f), 448.f); }
;     __device__ __forceinline__ void operator()(const f32x4 (&acc)[2][2][4][2], const Unit& u, int wr, int wc, int fr, int fq) const {
;     ...
;             const int c0 = 128 * (pn - 26) + lc;
;             f32x4 bA[2], bB[2];
; #pragma unroll
;             for (int n = 0; n < 2; ++n) { bA[n] = *(const f32x4*)(bias + 6656 + c0 + 4 * n); bB[n] = *(const f32x4*)(bias + 7680 + c0 + 4 * n); }
; #pragma unroll
;             for (int ai = 0; ai < 2; ++ai)
; #pragma unroll
;                 for (int m = 0; m < 4; ++m) { const size_t off = (size_t)(row0 + ai * 128 + m * 16) * D + c0; f32x4 rh[2], sb[2];
; #pragma unroll
;                     for (int n = 0; n < 2; ++n) { const f32x4 a = acc[ai][0][m][n] * as + bA[n], b = acc[ai][1][m][n] * as + bB[n];
; #pragma unroll
;                         for (int j = 0; j < 4; ++j) { const float ea = 1.f + __builtin_amdgcn_exp2f(-a[j] * LOG2E), eb = 1.f + __builtin_amdgcn_exp2f(-b[j] * LOG2E); sb[n][j] = __builtin_amdgcn_rcpf(eb); rh[n][j] = eb * __builtin_amdgcn_rcpf(ea); } }
;                     int r0 = 0, r1 = 0; r0 = __builtin_amdgcn_cvt_pk_fp8_f32(f8c(rh[0][0]), f8c(rh[0][1]), r0, false); r0 = __builtin_amdgcn_cvt_pk_fp8_f32(f8c(rh[0][2]), f8c(rh[0][3]), r0, true);
;                     r1 = __builtin_amdgcn_cvt_pk_fp8_f32(f8c(rh[1][0]), f8c(rh[1][1]), r1, false); r1 = __builtin_amdgcn_cvt_pk_fp8_f32(f8c(rh[1][2]), f8c(rh[1][3]), r1, true);
;                     u32x2 w0; w0.x = (unsigned)r0; w0.y = (unsigned)r1; u32x4 w1;
;                     w1.x = cvt_pk_bf16(sb[0][0], sb[0][1]); w1.y = cvt_pk_bf16(sb[0][2], sb[0][3]); w1.z = cvt_pk_bf16(sb[1][0], sb[1][1]); w1.w = cvt_pk_bf16(sb[1][2], sb[1][3]);
;                     *(u32x2*)((unsigned char*)GA + off) = w0; *(u32x4*)(GB + off) = w1; }
.LBB0_186:
	s_cmp_lg_u32 s34, 9
	v_ashrrev_i32_e32 v155, 31, v154
	s_cbranch_scc0 .LBB0_188
	s_lshl_b32 s30, s34, 7
	s_addk_i32 s30, 0xf300
	v_add_u32_e32 v160, s30, v158
	v_ashrrev_i32_e32 v161, 31, v160
	v_lshlrev_b64 v[128:129], 2, v[160:161]
	v_lshl_add_u64 v[130:131], s[20:21], 0, v[128:129]
	v_lshl_add_u64 v[136:137], s[22:23], 0, v[128:129]
	global_load_dwordx4 v[132:135], v[130:131], off offset:16
	global_load_dwordx4 v[140:143], v[130:131], off
	s_nop 0
	global_load_dwordx4 v[128:131], v[136:137], off offset:16
	s_nop 0
	global_load_dwordx4 v[136:139], v[136:137], off
	v_lshlrev_b64 v[162:163], 10, v[154:155]
	v_lshl_add_u64 v[160:161], v[162:163], 0, v[160:161]
	v_readlane_b32 s36, v250, 22
	v_readlane_b32 s37, v250, 23
	v_readlane_b32 s38, v250, 24
	v_readlane_b32 s39, v250, 25
	s_mov_b64 s[30:31], 0x8000
	s_waitcnt vmcnt(0)
	v_fmamk_f32 v146, v120, 0x3d000000, v140
	v_mul_f32_e32 v146, 0xbfb8aa3b, v146
	v_exp_f32_e32 v146, v146
	v_fmamk_f32 v168, v119, 0x3d000000, v139
	v_mul_f32_e32 v168, 0xbfb8aa3b, v168
	v_exp_f32_e32 v168, v168
	v_add_f32_e32 v157, 1.0, v146
	v_fmamk_f32 v146, v116, 0x3d000000, v136
	v_mul_f32_e32 v146, 0xbfb8aa3b, v146
	v_exp_f32_e32 v146, v146
	v_rcp_f32_e32 v157, v157
	v_add_f32_e32 v168, 1.0, v168
	v_rcp_f32_e32 v180, v168
	v_add_f32_e32 v159, 1.0, v146
	v_rcp_f32_e32 v146, v159
	v_mul_f32_e32 v157, v159, v157
	v_fmamk_f32 v159, v121, 0x3d000000, v141
	v_mul_f32_e32 v159, 0xbfb8aa3b, v159
	v_exp_f32_e32 v159, v159
	v_fmamk_f32 v169, v112, 0x3d000000, v128
	v_mul_f32_e32 v169, 0xbfb8aa3b, v169
	v_exp_f32_e32 v169, v169
	v_add_f32_e32 v164, 1.0, v159
	v_fmamk_f32 v159, v117, 0x3d000000, v137
	v_mul_f32_e32 v159, 0xbfb8aa3b, v159
	v_exp_f32_e32 v159, v159
	v_rcp_f32_e32 v164, v164
	v_add_f32_e32 v169, 1.0, v169
	v_rcp_f32_e32 v181, v169
	v_add_f32_e32 v165, 1.0, v159
	v_rcp_f32_e32 v159, v165
	v_mul_f32_e32 v164, v165, v164
	v_fmamk_f32 v165, v122, 0x3d000000, v142
	v_mul_f32_e32 v165, 0xbfb8aa3b, v165
	v_exp_f32_e32 v165, v165
	v_fmamk_f32 v182, v113, 0x3d000000, v129
	v_mul_f32_e32 v182, 0xbfb8aa3b, v182
	v_exp_f32_e32 v182, v182
	v_add_f32_e32 v166, 1.0, v165
	v_fmamk_f32 v165, v118, 0x3d000000, v138
	v_mul_f32_e32 v165, 0xbfb8aa3b, v165
	v_exp_f32_e32 v165, v165
	v_rcp_f32_e32 v166, v166
	v_add_f32_e32 v182, 1.0, v182
	v_rcp_f32_e32 v183, v182
	v_add_f32_e32 v167, 1.0, v165
	v_rcp_f32_e32 v165, v167
	v_mul_f32_e32 v166, v167, v166
	v_fmamk_f32 v167, v123, 0x3d000000, v143
	v_mul_f32_e32 v167, 0xbfb8aa3b, v167
	v_exp_f32_e32 v167, v167
	v_fmamk_f32 v184, v114, 0x3d000000, v130
	v_mul_f32_e32 v184, 0xbfb8aa3b, v184
	v_exp_f32_e32 v184, v184
	v_add_f32_e32 v167, 1.0, v167
	v_rcp_f32_e32 v167, v167
	v_fmamk_f32 v186, v115, 0x3d000000, v131
	v_add_f32_e32 v184, 1.0, v184
	v_rcp_f32_e32 v185, v184
	v_mul_f32_e32 v167, v168, v167
	v_fmamk_f32 v168, v124, 0x3d000000, v132
	v_mul_f32_e32 v168, 0xbfb8aa3b, v168
	v_exp_f32_e32 v168, v168
	v_mul_f32_e32 v186, 0xbfb8aa3b, v186
	v_exp_f32_e32 v186, v186
	v_med3_f32 v157, v157, s66, v179
	v_add_f32_e32 v168, 1.0, v168
	v_rcp_f32_e32 v168, v168
	v_add_f32_e32 v186, 1.0, v186
	v_rcp_f32_e32 v187, v186
	v_med3_f32 v162, v164, s66, v179
	v_mul_f32_e32 v169, v169, v168
	v_fmamk_f32 v168, v125, 0x3d000000, v133
	v_mul_f32_e32 v168, 0xbfb8aa3b, v168
	v_exp_f32_e32 v168, v168
	v_cvt_pk_bf16_f32 v163, v165, v180
	v_cvt_pk_bf16_f32 v164, v181, v183
	v_cvt_pk_bf16_f32 v165, v185, v187
	v_add_f32_e32 v168, 1.0, v168
	v_rcp_f32_e32 v168, v168
	s_nop 0
	v_mul_f32_e32 v182, v182, v168
	v_fmamk_f32 v168, v126, 0x3d000000, v134
	v_mul_f32_e32 v168, 0xbfb8aa3b, v168
	v_exp_f32_e32 v168, v168
	s_nop 0
	v_add_f32_e32 v168, 1.0, v168
	v_rcp_f32_e32 v168, v168
	s_nop 0
	v_mul_f32_e32 v184, v184, v168
	v_fmamk_f32 v168, v127, 0x3d000000, v135
	v_mul_f32_e32 v168, 0xbfb8aa3b, v168
	v_exp_f32_e32 v168, v168
	s_nop 0
	v_add_f32_e32 v168, 1.0, v168
	v_rcp_f32_e32 v168, v168
	s_nop 0
	v_mul_f32_e32 v186, v186, v168
	v_cvt_pk_fp8_f32 v168, v157, v162
	v_med3_f32 v157, v166, s66, v179
	v_med3_f32 v162, v167, s66, v179
	v_lshl_add_u64 v[166:167], s[36:37], 0, v[160:161]
	v_cvt_pk_fp8_f32 v168, v157, v162 op_sel:[0,0,1]
	v_med3_f32 v157, v169, s66, v179
	v_med3_f32 v162, v182, s66, v179
	v_cvt_pk_fp8_f32 v169, v157, v162
	v_med3_f32 v157, v184, s66, v179
	v_med3_f32 v162, v186, s66, v179
	v_cvt_pk_fp8_f32 v169, v157, v162 op_sel:[0,0,1]
	v_cvt_pk_bf16_f32 v162, v146, v159
	v_fmamk_f32 v146, v108, 0x3d000000, v140
	v_mul_f32_e32 v146, 0xbfb8aa3b, v146
	v_exp_f32_e32 v146, v146
	v_fmamk_f32 v157, v100, 0x3d000000, v136
	v_mul_f32_e32 v157, 0xbfb8aa3b, v157
	v_exp_f32_e32 v157, v157
	v_add_f32_e32 v146, 1.0, v146
	v_rcp_f32_e32 v146, v146
	global_store_dwordx2 v[166:167], v[168:169], off
	v_add_f32_e32 v157, 1.0, v157
	v_rcp_f32_e32 v159, v157
	v_mul_f32_e32 v146, v157, v146
	v_fmamk_f32 v157, v109, 0x3d000000, v141
	v_mul_f32_e32 v157, 0xbfb8aa3b, v157
	v_exp_f32_e32 v157, v157
	v_lshl_add_u64 v[166:167], v[160:161], 1, s[38:39]
	global_store_dwordx4 v[166:167], v[162:165], off
	v_fmamk_f32 v166, v103, 0x3d000000, v139
	v_add_f32_e32 v157, 1.0, v157
	v_fmamk_f32 v162, v101, 0x3d000000, v137
	v_mul_f32_e32 v162, 0xbfb8aa3b, v162
	v_exp_f32_e32 v162, v162
	v_rcp_f32_e32 v157, v157
	v_fmamk_f32 v164, v102, 0x3d000000, v138
	v_mul_f32_e32 v164, 0xbfb8aa3b, v164
	v_add_f32_e32 v162, 1.0, v162
	v_rcp_f32_e32 v163, v162
	v_mul_f32_e32 v157, v162, v157
	v_fmamk_f32 v162, v110, 0x3d000000, v142
	v_mul_f32_e32 v162, 0xbfb8aa3b, v162
	v_exp_f32_e32 v162, v162
	v_exp_f32_e32 v164, v164
	v_mul_f32_e32 v166, 0xbfb8aa3b, v166
	v_exp_f32_e32 v166, v166
	v_add_f32_e32 v162, 1.0, v162
	v_rcp_f32_e32 v162, v162
; __device__ __forceinline__ unsigned cvt_pk_bf16(float lo, float hi) { f32x2_t v = {lo, hi}; bf16x2_t r = __builtin_convertvector(v, bf16x2_t); return __builtin_bit_cast(unsigned, r); }
; __device__ __forceinline__ float f8c(float v) { return fminf(fmaxf(v, -448.f), 448.f); }
;     __device__ __forceinline__ void operator()(const f32x4 (&acc)[2][2][4][2], const Unit& u, int wr, int wc, int fr, int fq) const {
;     ...
;             const int c0 = 128 * (pn - 26) + lc;
;             f32x4 bA[2], bB[2];
; #pragma unroll
;             for (int n = 0; n < 2; ++n) { bA[n] = *(const f32x4*)(bias + 6656 + c0 + 4 * n); bB[n] = *(const f32x4*)(bias + 7680 + c0 + 4 * n); }
; #pragma unroll
;             for (int ai = 0; ai < 2; ++ai)
; #pragma unroll
;                 for (int m = 0; m < 4; ++m) { const size_t off = (size_t)(row0 + ai * 128 + m * 16) * D + c0; f32x4 rh[2], sb[2];
; #pragma unroll
;                     for (int n = 0; n < 2; ++n) { const f32x4 a = acc[ai][0][m][n] * as + bA[n], b = acc[ai][1][m][n] * as + bB[n];
; #pragma unroll
;                         for (int j = 0; j < 4; ++j) { const float ea = 1.f + __builtin_amdgcn_exp2f(-a[j] * LOG2E), eb = 1.f + __builtin_amdgcn_exp2f(-b[j] * LOG2E); sb[n][j] = __builtin_amdgcn_rcpf(eb); rh[n][j] = eb * __builtin_amdgcn_rcpf(ea); } }
;                     int r0 = 0, r1 = 0; r0 = __builtin_amdgcn_cvt_pk_fp8_f32(f8c(rh[0][0]), f8c(rh[0][1]), r0, false); r0 = __builtin_amdgcn_cvt_pk_fp8_f32(f8c(rh[0][2]), f8c(rh[0][3]), r0, true);
;                     r1 = __builtin_amdgcn_cvt_pk_fp8_f32(f8c(rh[1][0]), f8c(rh[1][1]), r1, false); r1 = __builtin_amdgcn_cvt_pk_fp8_f32(f8c(rh[1][2]), f8c(rh[1][3]), r1, true);
;                     u32x2 w0; w0.x = (unsigned)r0; w0.y = (unsigned)r1; u32x4 w1;
;                     w1.x = cvt_pk_bf16(sb[0][0], sb[0][1]); w1.y = cvt_pk_bf16(sb[0][2], sb[0][3]); w1.z = cvt_pk_bf16(sb[1][0], sb[1][1]); w1.w = cvt_pk_bf16(sb[1][2], sb[1][3]);
;                     *(u32x2*)((unsigned char*)GA + off) = w0; *(u32x4*)(GB + off) = w1; }
	v_add_f32_e32 v164, 1.0, v164
	v_rcp_f32_e32 v165, v164
	v_add_f32_e32 v166, 1.0, v166
	v_mul_f32_e32 v162, v164, v162
	v_fmamk_f32 v164, v111, 0x3d000000, v143
	v_mul_f32_e32 v164, 0xbfb8aa3b, v164
	v_exp_f32_e32 v164, v164
	v_rcp_f32_e32 v180, v166
	v_fmamk_f32 v167, v96, 0x3d000000, v128
	v_mul_f32_e32 v167, 0xbfb8aa3b, v167
	v_add_f32_e32 v164, 1.0, v164
	v_rcp_f32_e32 v164, v164
	v_exp_f32_e32 v167, v167
	v_med3_f32 v146, v146, s66, v179
	v_med3_f32 v157, v157, s66, v179
	v_mul_f32_e32 v164, v166, v164
	v_fmamk_f32 v166, v104, 0x3d000000, v132
	v_mul_f32_e32 v166, 0xbfb8aa3b, v166
	v_exp_f32_e32 v166, v166
	v_add_f32_e32 v167, 1.0, v167
	v_rcp_f32_e32 v181, v167
	v_add_f32_e32 v166, 1.0, v166
	v_rcp_f32_e32 v166, v166
	v_cvt_pk_fp8_f32 v168, v146, v157
	v_med3_f32 v146, v162, s66, v179
	v_med3_f32 v157, v164, s66, v179
	v_mul_f32_e32 v169, v167, v166
	v_fmamk_f32 v166, v105, 0x3d000000, v133
	v_mul_f32_e32 v166, 0xbfb8aa3b, v166
	v_exp_f32_e32 v166, v166
	v_fmamk_f32 v167, v97, 0x3d000000, v129
	v_mul_f32_e32 v167, 0xbfb8aa3b, v167
	v_exp_f32_e32 v167, v167
	v_add_f32_e32 v166, 1.0, v166
	v_rcp_f32_e32 v166, v166
	v_cvt_pk_fp8_f32 v168, v146, v157 op_sel:[0,0,1]
	v_add_f32_e32 v167, 1.0, v167
	v_rcp_f32_e32 v182, v167
	v_mul_f32_e32 v183, v167, v166
	v_fmamk_f32 v166, v106, 0x3d000000, v134
	v_mul_f32_e32 v166, 0xbfb8aa3b, v166
	v_exp_f32_e32 v166, v166
	v_fmamk_f32 v167, v98, 0x3d000000, v130
	v_mul_f32_e32 v167, 0xbfb8aa3b, v167
	v_exp_f32_e32 v167, v167
	v_add_f32_e32 v166, 1.0, v166
	v_rcp_f32_e32 v166, v166
	v_med3_f32 v146, v169, s66, v179
	v_add_f32_e32 v167, 1.0, v167
	v_rcp_f32_e32 v184, v167
	v_mul_f32_e32 v185, v167, v166
	v_fmamk_f32 v166, v107, 0x3d000000, v135
	v_mul_f32_e32 v166, 0xbfb8aa3b, v166
	v_exp_f32_e32 v166, v166
	v_fmamk_f32 v167, v99, 0x3d000000, v131
	v_mul_f32_e32 v167, 0xbfb8aa3b, v167
	v_exp_f32_e32 v167, v167
	v_add_f32_e32 v166, 1.0, v166
	v_rcp_f32_e32 v166, v166
	v_med3_f32 v157, v183, s66, v179
	v_cvt_pk_fp8_f32 v169, v146, v157
	v_add_f32_e32 v167, 1.0, v167
	v_mul_f32_e32 v187, v167, v166
	v_med3_f32 v146, v185, s66, v179
	v_med3_f32 v157, v187, s66, v179
	v_cvt_pk_fp8_f32 v169, v146, v157 op_sel:[0,0,1]
	v_fmamk_f32 v146, v92, 0x3d000000, v140
	v_mul_f32_e32 v146, 0xbfb8aa3b, v146
	v_exp_f32_e32 v146, v146
	v_fmamk_f32 v157, v84, 0x3d000000, v136
	v_mul_f32_e32 v157, 0xbfb8aa3b, v157
	v_exp_f32_e32 v157, v157
	v_add_f32_e32 v146, 1.0, v146
	v_rcp_f32_e32 v146, v146
	v_rcp_f32_e32 v186, v167
	v_add_f32_e32 v157, 1.0, v157
	v_cvt_pk_bf16_f32 v162, v159, v163
	v_rcp_f32_e32 v159, v157
	v_mul_f32_e32 v146, v157, v146
	v_fmamk_f32 v157, v93, 0x3d000000, v141
	v_mul_f32_e32 v157, 0xbfb8aa3b, v157
	v_lshl_add_u64 v[166:167], v[160:161], 0, s[26:27]
	v_exp_f32_e32 v157, v157
	v_cvt_pk_bf16_f32 v163, v165, v180
	v_cvt_pk_bf16_f32 v164, v181, v182
	v_cvt_pk_bf16_f32 v165, v184, v186
	v_lshl_add_u64 v[180:181], s[36:37], 0, v[166:167]
	v_lshl_add_u64 v[166:167], v[166:167], 1, s[38:39]
	global_store_dwordx2 v[180:181], v[168:169], off
	global_store_dwordx4 v[166:167], v[162:165], off
	v_add_f32_e32 v157, 1.0, v157
	v_rcp_f32_e32 v157, v157
	v_fmamk_f32 v162, v85, 0x3d000000, v137
	v_mul_f32_e32 v162, 0xbfb8aa3b, v162
	v_exp_f32_e32 v162, v162
	v_fmamk_f32 v164, v86, 0x3d000000, v138
	v_mul_f32_e32 v164, 0xbfb8aa3b, v164
	v_exp_f32_e32 v164, v164
	v_add_f32_e32 v162, 1.0, v162
	v_rcp_f32_e32 v163, v162
	v_mul_f32_e32 v157, v162, v157
	v_fmamk_f32 v162, v94, 0x3d000000, v142
	v_mul_f32_e32 v162, 0xbfb8aa3b, v162
	v_exp_f32_e32 v162, v162
	v_add_f32_e32 v164, 1.0, v164
	v_rcp_f32_e32 v165, v164
	v_fmamk_f32 v166, v87, 0x3d000000, v139
	v_add_f32_e32 v162, 1.0, v162
	v_rcp_f32_e32 v162, v162
	v_mul_f32_e32 v166, 0xbfb8aa3b, v166
	v_exp_f32_e32 v166, v166
	v_fmamk_f32 v167, v80, 0x3d000000, v128
	v_mul_f32_e32 v162, v164, v162
	v_fmamk_f32 v164, v95, 0x3d000000, v143
	v_mul_f32_e32 v164, 0xbfb8aa3b, v164
	v_exp_f32_e32 v164, v164
	v_add_f32_e32 v166, 1.0, v166
	v_rcp_f32_e32 v180, v166
	v_mul_f32_e32 v167, 0xbfb8aa3b, v167
	v_add_f32_e32 v164, 1.0, v164
	v_rcp_f32_e32 v164, v164
	v_exp_f32_e32 v167, v167
	v_med3_f32 v146, v146, s66, v179
	v_med3_f32 v157, v157, s66, v179
	v_mul_f32_e32 v164, v166, v164
	v_fmamk_f32 v166, v88, 0x3d000000, v132
	v_mul_f32_e32 v166, 0xbfb8aa3b, v166
	v_exp_f32_e32 v166, v166
	v_add_f32_e32 v167, 1.0, v167
	v_rcp_f32_e32 v181, v167
	v_add_f32_e32 v166, 1.0, v166
	v_rcp_f32_e32 v166, v166
	v_cvt_pk_fp8_f32 v168, v146, v157
	v_med3_f32 v146, v162, s66, v179
	v_med3_f32 v157, v164, s66, v179
	v_mul_f32_e32 v169, v167, v166
	v_fmamk_f32 v166, v89, 0x3d000000, v133
	v_mul_f32_e32 v166, 0xbfb8aa3b, v166
	v_exp_f32_e32 v166, v166
	v_fmamk_f32 v167, v81, 0x3d000000, v129
	v_mul_f32_e32 v167, 0xbfb8aa3b, v167
	v_exp_f32_e32 v167, v167
	v_add_f32_e32 v166, 1.0, v166
	v_rcp_f32_e32 v166, v166
	v_cvt_pk_fp8_f32 v168, v146, v157 op_sel:[0,0,1]
	v_add_f32_e32 v167, 1.0, v167
	v_rcp_f32_e32 v182, v167
	v_mul_f32_e32 v183, v167, v166
	v_fmamk_f32 v166, v90, 0x3d000000, v134
	v_mul_f32_e32 v166, 0xbfb8aa3b, v166
	v_exp_f32_e32 v166, v166
	v_fmamk_f32 v167, v82, 0x3d000000, v130
	v_mul_f32_e32 v167, 0xbfb8aa3b, v167
	v_exp_f32_e32 v167, v167
	v_add_f32_e32 v166, 1.0, v166
	v_rcp_f32_e32 v166, v166
	v_med3_f32 v146, v169, s66, v179
	v_add_f32_e32 v167, 1.0, v167
	v_rcp_f32_e32 v184, v167
	v_mul_f32_e32 v185, v167, v166
	v_fmamk_f32 v166, v91, 0x3d000000, v135
	v_mul_f32_e32 v166, 0xbfb8aa3b, v166
	v_exp_f32_e32 v166, v166
	v_fmamk_f32 v167, v83, 0x3d000000, v131
	v_mul_f32_e32 v167, 0xbfb8aa3b, v167
	v_exp_f32_e32 v167, v167
	v_add_f32_e32 v166, 1.0, v166
	v_rcp_f32_e32 v166, v166
; __device__ __forceinline__ unsigned cvt_pk_bf16(float lo, float hi) { f32x2_t v = {lo, hi}; bf16x2_t r = __builtin_convertvector(v, bf16x2_t); return __builtin_bit_cast(unsigned, r); }
; __device__ __forceinline__ float f8c(float v) { return fminf(fmaxf(v, -448.f), 448.f); }
;     __device__ __forceinline__ void operator()(const f32x4 (&acc)[2][2][4][2], const Unit& u, int wr, int wc, int fr, int fq) const {
;     ...
;             const int c0 = 128 * (pn - 26) + lc;
;             f32x4 bA[2], bB[2];
; #pragma unroll
;             for (int n = 0; n < 2; ++n) { bA[n] = *(const f32x4*)(bias + 6656 + c0 + 4 * n); bB[n] = *(const f32x4*)(bias + 7680 + c0 + 4 * n); }
; #pragma unroll
;             for (int ai = 0; ai < 2; ++ai)
; #pragma unroll
;                 for (int m = 0; m < 4; ++m) { const size_t off = (size_t)(row0 + ai * 128 + m * 16) * D + c0; f32x4 rh[2], sb[2];
; #pragma unroll
;                     for (int n = 0; n < 2; ++n) { const f32x4 a = acc[ai][0][m][n] * as + bA[n], b = acc[ai][1][m][n] * as + bB[n];
; #pragma unroll
;                         for (int j = 0; j < 4; ++j) { const float ea = 1.f + __builtin_amdgcn_exp2f(-a[j] * LOG2E), eb = 1.f + __builtin_amdgcn_exp2f(-b[j] * LOG2E); sb[n][j] = __builtin_amdgcn_rcpf(eb); rh[n][j] = eb * __builtin_amdgcn_rcpf(ea); } }
;                     int r0 = 0, r1 = 0; r0 = __builtin_amdgcn_cvt_pk_fp8_f32(f8c(rh[0][0]), f8c(rh[0][1]), r0, false); r0 = __builtin_amdgcn_cvt_pk_fp8_f32(f8c(rh[0][2]), f8c(rh[0][3]), r0, true);
;                     r1 = __builtin_amdgcn_cvt_pk_fp8_f32(f8c(rh[1][0]), f8c(rh[1][1]), r1, false); r1 = __builtin_amdgcn_cvt_pk_fp8_f32(f8c(rh[1][2]), f8c(rh[1][3]), r1, true);
;                     u32x2 w0; w0.x = (unsigned)r0; w0.y = (unsigned)r1; u32x4 w1;
;                     w1.x = cvt_pk_bf16(sb[0][0], sb[0][1]); w1.y = cvt_pk_bf16(sb[0][2], sb[0][3]); w1.z = cvt_pk_bf16(sb[1][0], sb[1][1]); w1.w = cvt_pk_bf16(sb[1][2], sb[1][3]);
;                     *(u32x2*)((unsigned char*)GA + off) = w0; *(u32x4*)(GB + off) = w1; }
	v_med3_f32 v157, v183, s66, v179
	v_cvt_pk_fp8_f32 v169, v146, v157
	v_add_f32_e32 v167, 1.0, v167
	v_mul_f32_e32 v187, v167, v166
	v_med3_f32 v146, v185, s66, v179
	v_med3_f32 v157, v187, s66, v179
	v_cvt_pk_fp8_f32 v169, v146, v157 op_sel:[0,0,1]
	v_fmamk_f32 v146, v76, 0x3d000000, v140
	v_mul_f32_e32 v146, 0xbfb8aa3b, v146
	v_exp_f32_e32 v146, v146
	v_fmamk_f32 v157, v68, 0x3d000000, v136
	v_mul_f32_e32 v157, 0xbfb8aa3b, v157
	v_exp_f32_e32 v157, v157
	v_add_f32_e32 v146, 1.0, v146
	v_rcp_f32_e32 v146, v146
	v_rcp_f32_e32 v186, v167
	v_add_f32_e32 v157, 1.0, v157
	v_cvt_pk_bf16_f32 v162, v159, v163
	v_rcp_f32_e32 v159, v157
	v_mul_f32_e32 v146, v157, v146
	v_fmamk_f32 v157, v77, 0x3d000000, v141
	v_mul_f32_e32 v157, 0xbfb8aa3b, v157
	v_lshl_add_u64 v[166:167], v[160:161], 0, s[30:31]
	v_exp_f32_e32 v157, v157
	v_cvt_pk_bf16_f32 v163, v165, v180
	v_cvt_pk_bf16_f32 v164, v181, v182
	v_cvt_pk_bf16_f32 v165, v184, v186
	v_lshl_add_u64 v[180:181], s[36:37], 0, v[166:167]
	v_lshl_add_u64 v[166:167], v[166:167], 1, s[38:39]
	global_store_dwordx2 v[180:181], v[168:169], off
	global_store_dwordx4 v[166:167], v[162:165], off
	v_add_f32_e32 v157, 1.0, v157
	v_rcp_f32_e32 v157, v157
	v_fmamk_f32 v162, v69, 0x3d000000, v137
	v_mul_f32_e32 v162, 0xbfb8aa3b, v162
	v_exp_f32_e32 v162, v162
	v_fmamk_f32 v164, v70, 0x3d000000, v138
	v_mul_f32_e32 v164, 0xbfb8aa3b, v164
	v_exp_f32_e32 v164, v164
	v_add_f32_e32 v162, 1.0, v162
	v_rcp_f32_e32 v163, v162
	v_mul_f32_e32 v157, v162, v157
	v_fmamk_f32 v162, v78, 0x3d000000, v142
	v_mul_f32_e32 v162, 0xbfb8aa3b, v162
	v_exp_f32_e32 v162, v162
	v_add_f32_e32 v164, 1.0, v164
	v_rcp_f32_e32 v165, v164
	v_fmamk_f32 v166, v71, 0x3d000000, v139
	v_add_f32_e32 v162, 1.0, v162
	v_rcp_f32_e32 v162, v162
	v_mul_f32_e32 v166, 0xbfb8aa3b, v166
	v_exp_f32_e32 v166, v166
	v_fmamk_f32 v167, v64, 0x3d000000, v128
	v_mul_f32_e32 v162, v164, v162
	v_fmamk_f32 v164, v79, 0x3d000000, v143
	v_mul_f32_e32 v164, 0xbfb8aa3b, v164
	v_exp_f32_e32 v164, v164
	v_add_f32_e32 v166, 1.0, v166
	v_rcp_f32_e32 v180, v166
	v_mul_f32_e32 v167, 0xbfb8aa3b, v167
	v_add_f32_e32 v164, 1.0, v164
	v_rcp_f32_e32 v164, v164
	v_exp_f32_e32 v167, v167
	v_med3_f32 v146, v146, s66, v179
	v_med3_f32 v157, v157, s66, v179
	v_mul_f32_e32 v164, v166, v164
	v_fmamk_f32 v166, v72, 0x3d000000, v132
	v_mul_f32_e32 v166, 0xbfb8aa3b, v166
	v_exp_f32_e32 v166, v166
	v_add_f32_e32 v167, 1.0, v167
	v_rcp_f32_e32 v181, v167
	v_add_f32_e32 v166, 1.0, v166
	v_rcp_f32_e32 v166, v166
	v_cvt_pk_fp8_f32 v168, v146, v157
	v_med3_f32 v146, v162, s66, v179
	v_med3_f32 v157, v164, s66, v179
	v_mul_f32_e32 v169, v167, v166
	v_fmamk_f32 v166, v73, 0x3d000000, v133
	v_mul_f32_e32 v166, 0xbfb8aa3b, v166
	v_exp_f32_e32 v166, v166
	v_fmamk_f32 v167, v65, 0x3d000000, v129
	v_mul_f32_e32 v167, 0xbfb8aa3b, v167
	v_exp_f32_e32 v167, v167
	v_add_f32_e32 v166, 1.0, v166
	v_rcp_f32_e32 v166, v166
	v_cvt_pk_fp8_f32 v168, v146, v157 op_sel:[0,0,1]
	v_add_f32_e32 v167, 1.0, v167
	v_rcp_f32_e32 v182, v167
	v_mul_f32_e32 v183, v167, v166
	v_fmamk_f32 v166, v74, 0x3d000000, v134
	v_mul_f32_e32 v166, 0xbfb8aa3b, v166
	v_exp_f32_e32 v166, v166
	v_fmamk_f32 v167, v66, 0x3d000000, v130
	v_mul_f32_e32 v167, 0xbfb8aa3b, v167
	v_exp_f32_e32 v167, v167
	v_add_f32_e32 v166, 1.0, v166
	v_rcp_f32_e32 v166, v166
	v_med3_f32 v146, v169, s66, v179
	v_add_f32_e32 v167, 1.0, v167
	v_rcp_f32_e32 v184, v167
	v_mul_f32_e32 v185, v167, v166
	v_fmamk_f32 v166, v75, 0x3d000000, v135
	v_mul_f32_e32 v166, 0xbfb8aa3b, v166
	v_exp_f32_e32 v166, v166
	v_fmamk_f32 v167, v67, 0x3d000000, v131
	v_mul_f32_e32 v167, 0xbfb8aa3b, v167
	v_exp_f32_e32 v167, v167
	v_add_f32_e32 v166, 1.0, v166
	v_rcp_f32_e32 v166, v166
	v_med3_f32 v157, v183, s66, v179
	v_cvt_pk_fp8_f32 v169, v146, v157
	v_add_f32_e32 v167, 1.0, v167
	v_mul_f32_e32 v187, v167, v166
	v_med3_f32 v146, v185, s66, v179
	v_med3_f32 v157, v187, s66, v179
	v_cvt_pk_fp8_f32 v169, v146, v157 op_sel:[0,0,1]
	v_fmamk_f32 v146, v60, 0x3d000000, v140
	v_mul_f32_e32 v146, 0xbfb8aa3b, v146
	v_exp_f32_e32 v146, v146
	v_fmamk_f32 v157, v52, 0x3d000000, v136
	v_mul_f32_e32 v157, 0xbfb8aa3b, v157
	v_exp_f32_e32 v157, v157
	v_add_f32_e32 v146, 1.0, v146
	v_rcp_f32_e32 v146, v146
	v_rcp_f32_e32 v186, v167
	v_add_f32_e32 v157, 1.0, v157
	v_cvt_pk_bf16_f32 v162, v159, v163
	v_rcp_f32_e32 v159, v157
	v_mul_f32_e32 v146, v157, v146
	v_fmamk_f32 v157, v61, 0x3d000000, v141
	s_mov_b64 s[30:31], 0xc000
	v_mul_f32_e32 v157, 0xbfb8aa3b, v157
	v_lshl_add_u64 v[166:167], v[160:161], 0, s[30:31]
	v_exp_f32_e32 v157, v157
	v_cvt_pk_bf16_f32 v163, v165, v180
	v_cvt_pk_bf16_f32 v164, v181, v182
	v_cvt_pk_bf16_f32 v165, v184, v186
	v_lshl_add_u64 v[180:181], s[36:37], 0, v[166:167]
	v_lshl_add_u64 v[166:167], v[166:167], 1, s[38:39]
	global_store_dwordx2 v[180:181], v[168:169], off
	global_store_dwordx4 v[166:167], v[162:165], off
	v_add_f32_e32 v157, 1.0, v157
	v_rcp_f32_e32 v157, v157
	v_fmamk_f32 v162, v53, 0x3d000000, v137
	v_mul_f32_e32 v162, 0xbfb8aa3b, v162
	v_exp_f32_e32 v162, v162
	v_fmamk_f32 v164, v54, 0x3d000000, v138
	v_mul_f32_e32 v164, 0xbfb8aa3b, v164
	v_exp_f32_e32 v164, v164
	v_add_f32_e32 v162, 1.0, v162
	v_rcp_f32_e32 v163, v162
	v_mul_f32_e32 v157, v162, v157
	v_fmamk_f32 v162, v62, 0x3d000000, v142
	v_mul_f32_e32 v162, 0xbfb8aa3b, v162
	v_exp_f32_e32 v162, v162
	v_add_f32_e32 v164, 1.0, v164
	v_rcp_f32_e32 v165, v164
	v_fmamk_f32 v166, v55, 0x3d000000, v139
	v_add_f32_e32 v162, 1.0, v162
	v_rcp_f32_e32 v162, v162
	v_mul_f32_e32 v166, 0xbfb8aa3b, v166
	v_exp_f32_e32 v166, v166
	v_fmamk_f32 v167, v48, 0x3d000000, v128
	v_mul_f32_e32 v162, v164, v162
	v_fmamk_f32 v164, v63, 0x3d000000, v143
; __device__ __forceinline__ unsigned cvt_pk_bf16(float lo, float hi) { f32x2_t v = {lo, hi}; bf16x2_t r = __builtin_convertvector(v, bf16x2_t); return __builtin_bit_cast(unsigned, r); }
; __device__ __forceinline__ float f8c(float v) { return fminf(fmaxf(v, -448.f), 448.f); }
;     __device__ __forceinline__ void operator()(const f32x4 (&acc)[2][2][4][2], const Unit& u, int wr, int wc, int fr, int fq) const {
;     ...
;             const int c0 = 128 * (pn - 26) + lc;
;             f32x4 bA[2], bB[2];
; #pragma unroll
;             for (int n = 0; n < 2; ++n) { bA[n] = *(const f32x4*)(bias + 6656 + c0 + 4 * n); bB[n] = *(const f32x4*)(bias + 7680 + c0 + 4 * n); }
; #pragma unroll
;             for (int ai = 0; ai < 2; ++ai)
; #pragma unroll
;                 for (int m = 0; m < 4; ++m) { const size_t off = (size_t)(row0 + ai * 128 + m * 16) * D + c0; f32x4 rh[2], sb[2];
; #pragma unroll
;                     for (int n = 0; n < 2; ++n) { const f32x4 a = acc[ai][0][m][n] * as + bA[n], b = acc[ai][1][m][n] * as + bB[n];
; #pragma unroll
;                         for (int j = 0; j < 4; ++j) { const float ea = 1.f + __builtin_amdgcn_exp2f(-a[j] * LOG2E), eb = 1.f + __builtin_amdgcn_exp2f(-b[j] * LOG2E); sb[n][j] = __builtin_amdgcn_rcpf(eb); rh[n][j] = eb * __builtin_amdgcn_rcpf(ea); } }
;                     int r0 = 0, r1 = 0; r0 = __builtin_amdgcn_cvt_pk_fp8_f32(f8c(rh[0][0]), f8c(rh[0][1]), r0, false); r0 = __builtin_amdgcn_cvt_pk_fp8_f32(f8c(rh[0][2]), f8c(rh[0][3]), r0, true);
;                     r1 = __builtin_amdgcn_cvt_pk_fp8_f32(f8c(rh[1][0]), f8c(rh[1][1]), r1, false); r1 = __builtin_amdgcn_cvt_pk_fp8_f32(f8c(rh[1][2]), f8c(rh[1][3]), r1, true);
;                     u32x2 w0; w0.x = (unsigned)r0; w0.y = (unsigned)r1; u32x4 w1;
;                     w1.x = cvt_pk_bf16(sb[0][0], sb[0][1]); w1.y = cvt_pk_bf16(sb[0][2], sb[0][3]); w1.z = cvt_pk_bf16(sb[1][0], sb[1][1]); w1.w = cvt_pk_bf16(sb[1][2], sb[1][3]);
;                     *(u32x2*)((unsigned char*)GA + off) = w0; *(u32x4*)(GB + off) = w1; }
	v_mul_f32_e32 v164, 0xbfb8aa3b, v164
	v_exp_f32_e32 v164, v164
	v_add_f32_e32 v166, 1.0, v166
	v_rcp_f32_e32 v180, v166
	v_mul_f32_e32 v167, 0xbfb8aa3b, v167
	v_add_f32_e32 v164, 1.0, v164
	v_rcp_f32_e32 v164, v164
	v_exp_f32_e32 v167, v167
	v_med3_f32 v146, v146, s66, v179
	v_med3_f32 v157, v157, s66, v179
	v_mul_f32_e32 v164, v166, v164
	v_fmamk_f32 v166, v56, 0x3d000000, v132
	v_mul_f32_e32 v166, 0xbfb8aa3b, v166
	v_exp_f32_e32 v166, v166
	v_add_f32_e32 v167, 1.0, v167
	v_rcp_f32_e32 v181, v167
	v_add_f32_e32 v166, 1.0, v166
	v_rcp_f32_e32 v166, v166
	v_cvt_pk_fp8_f32 v168, v146, v157
	v_med3_f32 v146, v162, s66, v179
	v_med3_f32 v157, v164, s66, v179
	v_mul_f32_e32 v169, v167, v166
	v_fmamk_f32 v166, v57, 0x3d000000, v133
	v_mul_f32_e32 v166, 0xbfb8aa3b, v166
	v_exp_f32_e32 v166, v166
	v_fmamk_f32 v167, v49, 0x3d000000, v129
	v_mul_f32_e32 v167, 0xbfb8aa3b, v167
	v_exp_f32_e32 v167, v167
	v_add_f32_e32 v166, 1.0, v166
	v_rcp_f32_e32 v166, v166
	v_cvt_pk_fp8_f32 v168, v146, v157 op_sel:[0,0,1]
	v_add_f32_e32 v167, 1.0, v167
	v_rcp_f32_e32 v182, v167
	v_mul_f32_e32 v183, v167, v166
	v_fmamk_f32 v166, v58, 0x3d000000, v134
	v_mul_f32_e32 v166, 0xbfb8aa3b, v166
	v_exp_f32_e32 v166, v166
	v_fmamk_f32 v167, v50, 0x3d000000, v130
	v_mul_f32_e32 v167, 0xbfb8aa3b, v167
	v_exp_f32_e32 v167, v167
	v_add_f32_e32 v166, 1.0, v166
	v_rcp_f32_e32 v166, v166
	v_med3_f32 v146, v169, s66, v179
	v_add_f32_e32 v167, 1.0, v167
	v_rcp_f32_e32 v184, v167
	v_mul_f32_e32 v185, v167, v166
	v_fmamk_f32 v166, v59, 0x3d000000, v135
	v_mul_f32_e32 v166, 0xbfb8aa3b, v166
	v_exp_f32_e32 v166, v166
	v_fmamk_f32 v167, v51, 0x3d000000, v131
	v_mul_f32_e32 v167, 0xbfb8aa3b, v167
	v_exp_f32_e32 v167, v167
	v_add_f32_e32 v166, 1.0, v166
	v_rcp_f32_e32 v166, v166
	v_med3_f32 v157, v183, s66, v179
	v_cvt_pk_fp8_f32 v169, v146, v157
	v_add_f32_e32 v167, 1.0, v167
	v_mul_f32_e32 v187, v167, v166
	v_med3_f32 v146, v185, s66, v179
	v_med3_f32 v157, v187, s66, v179
	v_cvt_pk_fp8_f32 v169, v146, v157 op_sel:[0,0,1]
	v_fmamk_f32 v146, v44, 0x3d000000, v140
	v_mul_f32_e32 v146, 0xbfb8aa3b, v146
	v_exp_f32_e32 v146, v146
	v_fmamk_f32 v157, v36, 0x3d000000, v136
	v_mul_f32_e32 v157, 0xbfb8aa3b, v157
	v_exp_f32_e32 v157, v157
	v_add_f32_e32 v146, 1.0, v146
	v_rcp_f32_e32 v146, v146
	v_rcp_f32_e32 v186, v167
	v_add_f32_e32 v157, 1.0, v157
	v_cvt_pk_bf16_f32 v162, v159, v163
	v_rcp_f32_e32 v159, v157
	v_mul_f32_e32 v146, v157, v146
	v_fmamk_f32 v157, v45, 0x3d000000, v141
	s_mov_b64 s[30:31], 0x20000
	v_mul_f32_e32 v157, 0xbfb8aa3b, v157
	v_lshl_add_u64 v[166:167], v[160:161], 0, s[30:31]
	v_exp_f32_e32 v157, v157
	v_cvt_pk_bf16_f32 v163, v165, v180
	v_cvt_pk_bf16_f32 v164, v181, v182
	v_cvt_pk_bf16_f32 v165, v184, v186
	v_lshl_add_u64 v[180:181], s[36:37], 0, v[166:167]
	v_lshl_add_u64 v[166:167], v[166:167], 1, s[38:39]
	global_store_dwordx2 v[180:181], v[168:169], off
	global_store_dwordx4 v[166:167], v[162:165], off
	v_add_f32_e32 v157, 1.0, v157
	v_rcp_f32_e32 v157, v157
	v_fmamk_f32 v162, v37, 0x3d000000, v137
	v_mul_f32_e32 v162, 0xbfb8aa3b, v162
	v_exp_f32_e32 v162, v162
	v_fmamk_f32 v164, v38, 0x3d000000, v138
	v_mul_f32_e32 v164, 0xbfb8aa3b, v164
	v_exp_f32_e32 v164, v164
	v_add_f32_e32 v162, 1.0, v162
	v_rcp_f32_e32 v163, v162
	v_mul_f32_e32 v157, v162, v157
	v_fmamk_f32 v162, v46, 0x3d000000, v142
	v_mul_f32_e32 v162, 0xbfb8aa3b, v162
	v_exp_f32_e32 v162, v162
	v_add_f32_e32 v164, 1.0, v164
	v_rcp_f32_e32 v165, v164
	v_fmamk_f32 v166, v39, 0x3d000000, v139
	v_add_f32_e32 v162, 1.0, v162
	v_rcp_f32_e32 v162, v162
	v_mul_f32_e32 v166, 0xbfb8aa3b, v166
	v_exp_f32_e32 v166, v166
	v_fmamk_f32 v167, v32, 0x3d000000, v128
	v_mul_f32_e32 v162, v164, v162
	v_fmamk_f32 v164, v47, 0x3d000000, v143
	v_mul_f32_e32 v164, 0xbfb8aa3b, v164
	v_exp_f32_e32 v164, v164
	v_add_f32_e32 v166, 1.0, v166
	v_rcp_f32_e32 v180, v166
	v_mul_f32_e32 v167, 0xbfb8aa3b, v167
	v_add_f32_e32 v164, 1.0, v164
	v_rcp_f32_e32 v164, v164
	v_exp_f32_e32 v167, v167
	v_med3_f32 v146, v146, s66, v179
	v_med3_f32 v157, v157, s66, v179
	v_mul_f32_e32 v164, v166, v164
	v_fmamk_f32 v166, v40, 0x3d000000, v132
	v_mul_f32_e32 v166, 0xbfb8aa3b, v166
	v_exp_f32_e32 v166, v166
	v_add_f32_e32 v167, 1.0, v167
	v_rcp_f32_e32 v181, v167
	v_add_f32_e32 v166, 1.0, v166
	v_rcp_f32_e32 v166, v166
	v_cvt_pk_fp8_f32 v168, v146, v157
	v_med3_f32 v146, v162, s66, v179
	v_med3_f32 v157, v164, s66, v179
	v_mul_f32_e32 v169, v167, v166
	v_fmamk_f32 v166, v41, 0x3d000000, v133
	v_mul_f32_e32 v166, 0xbfb8aa3b, v166
	v_exp_f32_e32 v166, v166
	v_fmamk_f32 v167, v33, 0x3d000000, v129
	v_mul_f32_e32 v167, 0xbfb8aa3b, v167
	v_exp_f32_e32 v167, v167
	v_add_f32_e32 v166, 1.0, v166
	v_rcp_f32_e32 v166, v166
	v_cvt_pk_fp8_f32 v168, v146, v157 op_sel:[0,0,1]
	v_add_f32_e32 v167, 1.0, v167
	v_rcp_f32_e32 v182, v167
	v_mul_f32_e32 v183, v167, v166
	v_fmamk_f32 v166, v42, 0x3d000000, v134
	v_mul_f32_e32 v166, 0xbfb8aa3b, v166
	v_exp_f32_e32 v166, v166
	v_fmamk_f32 v167, v34, 0x3d000000, v130
	v_mul_f32_e32 v167, 0xbfb8aa3b, v167
	v_exp_f32_e32 v167, v167
	v_add_f32_e32 v166, 1.0, v166
	v_rcp_f32_e32 v166, v166
	v_med3_f32 v146, v169, s66, v179
	v_add_f32_e32 v167, 1.0, v167
	v_rcp_f32_e32 v184, v167
	v_mul_f32_e32 v185, v167, v166
	v_fmamk_f32 v166, v43, 0x3d000000, v135
	v_mul_f32_e32 v166, 0xbfb8aa3b, v166
	v_exp_f32_e32 v166, v166
	v_fmamk_f32 v167, v35, 0x3d000000, v131
	v_mul_f32_e32 v167, 0xbfb8aa3b, v167
	v_exp_f32_e32 v167, v167
	v_add_f32_e32 v166, 1.0, v166
	v_rcp_f32_e32 v166, v166
	v_med3_f32 v157, v183, s66, v179
	v_cvt_pk_fp8_f32 v169, v146, v157
	v_add_f32_e32 v167, 1.0, v167
	v_mul_f32_e32 v187, v167, v166
	v_med3_f32 v146, v185, s66, v179
; __device__ __forceinline__ unsigned cvt_pk_bf16(float lo, float hi) { f32x2_t v = {lo, hi}; bf16x2_t r = __builtin_convertvector(v, bf16x2_t); return __builtin_bit_cast(unsigned, r); }
; __device__ __forceinline__ float f8c(float v) { return fminf(fmaxf(v, -448.f), 448.f); }
;     __device__ __forceinline__ void operator()(const f32x4 (&acc)[2][2][4][2], const Unit& u, int wr, int wc, int fr, int fq) const {
;     ...
;             const int c0 = 128 * (pn - 26) + lc;
;             f32x4 bA[2], bB[2];
; #pragma unroll
;             for (int n = 0; n < 2; ++n) { bA[n] = *(const f32x4*)(bias + 6656 + c0 + 4 * n); bB[n] = *(const f32x4*)(bias + 7680 + c0 + 4 * n); }
; #pragma unroll
;             for (int ai = 0; ai < 2; ++ai)
; #pragma unroll
;                 for (int m = 0; m < 4; ++m) { const size_t off = (size_t)(row0 + ai * 128 + m * 16) * D + c0; f32x4 rh[2], sb[2];
; #pragma unroll
;                     for (int n = 0; n < 2; ++n) { const f32x4 a = acc[ai][0][m][n] * as + bA[n], b = acc[ai][1][m][n] * as + bB[n];
; #pragma unroll
;                         for (int j = 0; j < 4; ++j) { const float ea = 1.f + __builtin_amdgcn_exp2f(-a[j] * LOG2E), eb = 1.f + __builtin_amdgcn_exp2f(-b[j] * LOG2E); sb[n][j] = __builtin_amdgcn_rcpf(eb); rh[n][j] = eb * __builtin_amdgcn_rcpf(ea); } }
;                     int r0 = 0, r1 = 0; r0 = __builtin_amdgcn_cvt_pk_fp8_f32(f8c(rh[0][0]), f8c(rh[0][1]), r0, false); r0 = __builtin_amdgcn_cvt_pk_fp8_f32(f8c(rh[0][2]), f8c(rh[0][3]), r0, true);
;                     r1 = __builtin_amdgcn_cvt_pk_fp8_f32(f8c(rh[1][0]), f8c(rh[1][1]), r1, false); r1 = __builtin_amdgcn_cvt_pk_fp8_f32(f8c(rh[1][2]), f8c(rh[1][3]), r1, true);
;                     u32x2 w0; w0.x = (unsigned)r0; w0.y = (unsigned)r1; u32x4 w1;
;                     w1.x = cvt_pk_bf16(sb[0][0], sb[0][1]); w1.y = cvt_pk_bf16(sb[0][2], sb[0][3]); w1.z = cvt_pk_bf16(sb[1][0], sb[1][1]); w1.w = cvt_pk_bf16(sb[1][2], sb[1][3]);
;                     *(u32x2*)((unsigned char*)GA + off) = w0; *(u32x4*)(GB + off) = w1; }
	v_med3_f32 v157, v187, s66, v179
	v_cvt_pk_fp8_f32 v169, v146, v157 op_sel:[0,0,1]
	v_fmamk_f32 v146, v28, 0x3d000000, v140
	v_mul_f32_e32 v146, 0xbfb8aa3b, v146
	v_exp_f32_e32 v146, v146
	v_fmamk_f32 v157, v20, 0x3d000000, v136
	v_mul_f32_e32 v157, 0xbfb8aa3b, v157
	v_exp_f32_e32 v157, v157
	v_add_f32_e32 v146, 1.0, v146
	v_rcp_f32_e32 v146, v146
	v_rcp_f32_e32 v186, v167
	v_add_f32_e32 v157, 1.0, v157
	v_cvt_pk_bf16_f32 v162, v159, v163
	v_rcp_f32_e32 v159, v157
	v_mul_f32_e32 v146, v157, v146
	v_fmamk_f32 v157, v29, 0x3d000000, v141
	s_mov_b64 s[30:31], 0x24000
	v_mul_f32_e32 v157, 0xbfb8aa3b, v157
	v_lshl_add_u64 v[166:167], v[160:161], 0, s[30:31]
	v_exp_f32_e32 v157, v157
	v_cvt_pk_bf16_f32 v163, v165, v180
	v_cvt_pk_bf16_f32 v164, v181, v182
	v_cvt_pk_bf16_f32 v165, v184, v186
	v_lshl_add_u64 v[180:181], s[36:37], 0, v[166:167]
	v_lshl_add_u64 v[166:167], v[166:167], 1, s[38:39]
	global_store_dwordx2 v[180:181], v[168:169], off
	global_store_dwordx4 v[166:167], v[162:165], off
	v_add_f32_e32 v157, 1.0, v157
	v_rcp_f32_e32 v157, v157
	v_fmamk_f32 v162, v21, 0x3d000000, v137
	v_mul_f32_e32 v162, 0xbfb8aa3b, v162
	v_exp_f32_e32 v162, v162
	v_fmamk_f32 v164, v22, 0x3d000000, v138
	v_mul_f32_e32 v164, 0xbfb8aa3b, v164
	v_exp_f32_e32 v164, v164
	v_add_f32_e32 v162, 1.0, v162
	v_rcp_f32_e32 v163, v162
	v_mul_f32_e32 v157, v162, v157
	v_fmamk_f32 v162, v30, 0x3d000000, v142
	v_mul_f32_e32 v162, 0xbfb8aa3b, v162
	v_exp_f32_e32 v162, v162
	v_add_f32_e32 v164, 1.0, v164
	v_rcp_f32_e32 v165, v164
	v_fmamk_f32 v166, v23, 0x3d000000, v139
	v_add_f32_e32 v162, 1.0, v162
	v_rcp_f32_e32 v162, v162
	v_mul_f32_e32 v166, 0xbfb8aa3b, v166
	v_exp_f32_e32 v166, v166
	v_fmamk_f32 v167, v16, 0x3d000000, v128
	v_mul_f32_e32 v162, v164, v162
	v_fmamk_f32 v164, v31, 0x3d000000, v143
	v_mul_f32_e32 v164, 0xbfb8aa3b, v164
	v_exp_f32_e32 v164, v164
	v_add_f32_e32 v166, 1.0, v166
	v_rcp_f32_e32 v180, v166
	v_mul_f32_e32 v167, 0xbfb8aa3b, v167
	v_add_f32_e32 v164, 1.0, v164
	v_rcp_f32_e32 v164, v164
	v_exp_f32_e32 v167, v167
	v_fmamk_f32 v140, v12, 0x3d000000, v140
	v_med3_f32 v146, v146, s66, v179
	v_mul_f32_e32 v164, v166, v164
	v_fmamk_f32 v166, v24, 0x3d000000, v132
	v_mul_f32_e32 v166, 0xbfb8aa3b, v166
	v_exp_f32_e32 v166, v166
	v_add_f32_e32 v167, 1.0, v167
	v_rcp_f32_e32 v181, v167
	v_med3_f32 v157, v157, s66, v179
	v_add_f32_e32 v166, 1.0, v166
	v_rcp_f32_e32 v166, v166
	v_mul_f32_e32 v140, 0xbfb8aa3b, v140
	v_cvt_pk_fp8_f32 v168, v146, v157
	v_mul_f32_e32 v169, v167, v166
	v_fmamk_f32 v166, v25, 0x3d000000, v133
	v_mul_f32_e32 v166, 0xbfb8aa3b, v166
	v_exp_f32_e32 v166, v166
	v_fmamk_f32 v167, v17, 0x3d000000, v129
	v_mul_f32_e32 v167, 0xbfb8aa3b, v167
	v_exp_f32_e32 v167, v167
	v_add_f32_e32 v166, 1.0, v166
	v_rcp_f32_e32 v166, v166
	v_exp_f32_e32 v140, v140
	v_add_f32_e32 v167, 1.0, v167
	v_rcp_f32_e32 v182, v167
	v_mul_f32_e32 v183, v167, v166
	v_fmamk_f32 v166, v26, 0x3d000000, v134
	v_mul_f32_e32 v166, 0xbfb8aa3b, v166
	v_exp_f32_e32 v166, v166
	v_fmamk_f32 v167, v18, 0x3d000000, v130
	v_mul_f32_e32 v167, 0xbfb8aa3b, v167
	v_exp_f32_e32 v167, v167
	v_add_f32_e32 v166, 1.0, v166
	v_rcp_f32_e32 v166, v166
	v_fmamk_f32 v136, v4, 0x3d000000, v136
	v_add_f32_e32 v167, 1.0, v167
	v_rcp_f32_e32 v184, v167
	v_mul_f32_e32 v185, v167, v166
	v_fmamk_f32 v166, v27, 0x3d000000, v135
	v_mul_f32_e32 v166, 0xbfb8aa3b, v166
	v_exp_f32_e32 v166, v166
	v_fmamk_f32 v167, v19, 0x3d000000, v131
	v_mul_f32_e32 v167, 0xbfb8aa3b, v167
	v_exp_f32_e32 v167, v167
	v_add_f32_e32 v166, 1.0, v166
	v_rcp_f32_e32 v166, v166
	v_med3_f32 v146, v162, s66, v179
	v_med3_f32 v157, v164, s66, v179
	v_mul_f32_e32 v136, 0xbfb8aa3b, v136
	v_cvt_pk_fp8_f32 v168, v146, v157 op_sel:[0,0,1]
	v_med3_f32 v146, v169, s66, v179
	v_med3_f32 v157, v183, s66, v179
	v_add_f32_e32 v140, 1.0, v140
	v_exp_f32_e32 v136, v136
	v_cvt_pk_fp8_f32 v169, v146, v157
	v_rcp_f32_e32 v140, v140
	v_add_f32_e32 v167, 1.0, v167
	v_mul_f32_e32 v187, v167, v166
	v_med3_f32 v146, v185, s66, v179
; __device__ __forceinline__ unsigned cvt_pk_bf16(float lo, float hi) { f32x2_t v = {lo, hi}; bf16x2_t r = __builtin_convertvector(v, bf16x2_t); return __builtin_bit_cast(unsigned, r); }
; __device__ __forceinline__ float f8c(float v) { return fminf(fmaxf(v, -448.f), 448.f); }
;     __device__ __forceinline__ void operator()(const f32x4 (&acc)[2][2][4][2], const Unit& u, int wr, int wc, int fr, int fq) const {
;     ...
;             const int c0 = 128 * (pn - 26) + lc;
;             f32x4 bA[2], bB[2];
; #pragma unroll
;             for (int n = 0; n < 2; ++n) { bA[n] = *(const f32x4*)(bias + 6656 + c0 + 4 * n); bB[n] = *(const f32x4*)(bias + 7680 + c0 + 4 * n); }
; #pragma unroll
;             for (int ai = 0; ai < 2; ++ai)
; #pragma unroll
;                 for (int m = 0; m < 4; ++m) { const size_t off = (size_t)(row0 + ai * 128 + m * 16) * D + c0; f32x4 rh[2], sb[2];
; #pragma unroll
;                     for (int n = 0; n < 2; ++n) { const f32x4 a = acc[ai][0][m][n] * as + bA[n], b = acc[ai][1][m][n] * as + bB[n];
; #pragma unroll
;                         for (int j = 0; j < 4; ++j) { const float ea = 1.f + __builtin_amdgcn_exp2f(-a[j] * LOG2E), eb = 1.f + __builtin_amdgcn_exp2f(-b[j] * LOG2E); sb[n][j] = __builtin_amdgcn_rcpf(eb); rh[n][j] = eb * __builtin_amdgcn_rcpf(ea); } }
;                     int r0 = 0, r1 = 0; r0 = __builtin_amdgcn_cvt_pk_fp8_f32(f8c(rh[0][0]), f8c(rh[0][1]), r0, false); r0 = __builtin_amdgcn_cvt_pk_fp8_f32(f8c(rh[0][2]), f8c(rh[0][3]), r0, true);
;                     r1 = __builtin_amdgcn_cvt_pk_fp8_f32(f8c(rh[1][0]), f8c(rh[1][1]), r1, false); r1 = __builtin_amdgcn_cvt_pk_fp8_f32(f8c(rh[1][2]), f8c(rh[1][3]), r1, true);
;                     u32x2 w0; w0.x = (unsigned)r0; w0.y = (unsigned)r1; u32x4 w1;
;                     w1.x = cvt_pk_bf16(sb[0][0], sb[0][1]); w1.y = cvt_pk_bf16(sb[0][2], sb[0][3]); w1.z = cvt_pk_bf16(sb[1][0], sb[1][1]); w1.w = cvt_pk_bf16(sb[1][2], sb[1][3]);
;                     *(u32x2*)((unsigned char*)GA + off) = w0; *(u32x4*)(GB + off) = w1; }
	v_med3_f32 v157, v187, s66, v179
	v_add_f32_e32 v136, 1.0, v136
	v_cvt_pk_fp8_f32 v169, v146, v157 op_sel:[0,0,1]
	v_rcp_f32_e32 v146, v136
	v_mul_f32_e32 v136, v136, v140
	v_fmamk_f32 v140, v13, 0x3d000000, v141
	v_mul_f32_e32 v140, 0xbfb8aa3b, v140
	v_exp_f32_e32 v140, v140
	v_fmamk_f32 v137, v5, 0x3d000000, v137
	v_mul_f32_e32 v137, 0xbfb8aa3b, v137
	v_exp_f32_e32 v137, v137
	v_add_f32_e32 v140, 1.0, v140
	v_rcp_f32_e32 v140, v140
	v_fmamk_f32 v138, v6, 0x3d000000, v138
	v_add_f32_e32 v137, 1.0, v137
	v_rcp_f32_e32 v141, v137
	v_mul_f32_e32 v137, v137, v140
	v_fmamk_f32 v140, v14, 0x3d000000, v142
	v_mul_f32_e32 v140, 0xbfb8aa3b, v140
	v_exp_f32_e32 v140, v140
	v_mul_f32_e32 v138, 0xbfb8aa3b, v138
	v_exp_f32_e32 v138, v138
	v_fmac_f32_e32 v143, 0x3d000000, v15
	v_add_f32_e32 v140, 1.0, v140
	v_rcp_f32_e32 v140, v140
	v_add_f32_e32 v138, 1.0, v138
	v_fmamk_f32 v132, v8, 0x3d000000, v132
	v_rcp_f32_e32 v142, v138
	v_mul_f32_e32 v138, v138, v140
	v_mul_f32_e32 v140, 0xbfb8aa3b, v143
	v_mul_f32_e32 v132, 0xbfb8aa3b, v132
	v_exp_f32_e32 v140, v140
	v_exp_f32_e32 v132, v132
	v_fmac_f32_e32 v139, 0x3d000000, v7
	v_fmamk_f32 v128, v0, 0x3d000000, v128
	v_mul_f32_e32 v139, 0xbfb8aa3b, v139
	v_mul_f32_e32 v128, 0xbfb8aa3b, v128
	v_add_f32_e32 v140, 1.0, v140
	v_exp_f32_e32 v139, v139
	v_add_f32_e32 v132, 1.0, v132
	v_exp_f32_e32 v128, v128
	v_rcp_f32_e32 v140, v140
	v_rcp_f32_e32 v132, v132
	v_add_f32_e32 v139, 1.0, v139
	v_add_f32_e32 v128, 1.0, v128
	v_rcp_f32_e32 v143, v139
	v_mul_f32_e32 v139, v139, v140
	v_rcp_f32_e32 v140, v128
	v_mul_f32_e32 v128, v128, v132
	v_fmamk_f32 v132, v9, 0x3d000000, v133
	v_mul_f32_e32 v132, 0xbfb8aa3b, v132
	v_exp_f32_e32 v132, v132
	v_fmamk_f32 v129, v1, 0x3d000000, v129
	v_mul_f32_e32 v129, 0xbfb8aa3b, v129
	v_exp_f32_e32 v129, v129
	v_add_f32_e32 v132, 1.0, v132
	v_rcp_f32_e32 v132, v132
	v_fmamk_f32 v130, v2, 0x3d000000, v130
	v_add_f32_e32 v129, 1.0, v129
	v_rcp_f32_e32 v157, v129
	v_mul_f32_e32 v129, v129, v132
	v_fmamk_f32 v132, v10, 0x3d000000, v134
	v_mul_f32_e32 v132, 0xbfb8aa3b, v132
	v_exp_f32_e32 v132, v132
	v_mul_f32_e32 v130, 0xbfb8aa3b, v130
	v_exp_f32_e32 v130, v130
	v_fmac_f32_e32 v135, 0x3d000000, v11
	v_add_f32_e32 v132, 1.0, v132
	v_rcp_f32_e32 v132, v132
	v_add_f32_e32 v130, 1.0, v130
	v_cvt_pk_bf16_f32 v162, v159, v163
	v_rcp_f32_e32 v159, v130
	v_mul_f32_e32 v130, v130, v132
	v_mul_f32_e32 v132, 0xbfb8aa3b, v135
	v_exp_f32_e32 v132, v132
	v_med3_f32 v135, v136, s66, v179
	v_med3_f32 v136, v137, s66, v179
	v_fmac_f32_e32 v131, 0x3d000000, v3
	v_cvt_pk_fp8_f32 v134, v135, v136
	v_mul_f32_e32 v131, 0xbfb8aa3b, v131
	v_rcp_f32_e32 v186, v167
	v_add_f32_e32 v132, 1.0, v132
	v_exp_f32_e32 v131, v131
	v_rcp_f32_e32 v132, v132
	v_med3_f32 v135, v138, s66, v179
	v_med3_f32 v136, v139, s66, v179
	s_mov_b64 s[30:31], 0x28000
	v_cvt_pk_fp8_f32 v134, v135, v136 op_sel:[0,0,1]
	v_med3_f32 v128, v128, s66, v179
	v_med3_f32 v129, v129, s66, v179
	v_lshl_add_u64 v[166:167], v[160:161], 0, s[30:31]
	v_cvt_pk_fp8_f32 v135, v128, v129
	v_cvt_pk_bf16_f32 v163, v165, v180
	v_cvt_pk_bf16_f32 v164, v181, v182
	v_cvt_pk_bf16_f32 v165, v184, v186
	v_lshl_add_u64 v[180:181], s[36:37], 0, v[166:167]
	v_lshl_add_u64 v[166:167], v[166:167], 1, s[38:39]
	v_add_f32_e32 v131, 1.0, v131
	global_store_dwordx2 v[180:181], v[168:169], off
	global_store_dwordx4 v[166:167], v[162:165], off
	v_med3_f32 v128, v130, s66, v179
	s_mov_b64 s[30:31], 0x2c000
	v_rcp_f32_e32 v162, v131
	v_mul_f32_e32 v131, v131, v132
	v_med3_f32 v129, v131, s66, v179
	v_cvt_pk_fp8_f32 v135, v128, v129 op_sel:[0,0,1]
	v_lshl_add_u64 v[132:133], v[160:161], 0, s[30:31]
	v_cvt_pk_bf16_f32 v128, v146, v141
	v_cvt_pk_bf16_f32 v129, v142, v143
	v_cvt_pk_bf16_f32 v130, v140, v157
	v_cvt_pk_bf16_f32 v131, v159, v162
	v_lshl_add_u64 v[136:137], s[36:37], 0, v[132:133]
	v_lshl_add_u64 v[132:133], v[132:133], 1, s[38:39]
	global_store_dwordx2 v[136:137], v[134:135], off
	global_store_dwordx4 v[132:133], v[128:131], off
	s_mov_b64 s[30:31], 0

; __device__ __forceinline__ float f8c(float v) { return fminf(fmaxf(v, -448.f), 448.f); }
;     __device__ __forceinline__ void qkv_store(const f32x4 (&acc)[2][2][4][2], int pn, int wc, int fq, int bcol0, int row0, float sc) const {
;         const int which = pn / 3, dsh = 2 * (pn - which * 3);
;         f32x4 bv[2][2];
; #pragma unroll
;         for (int bj = 0; bj < 2; ++bj)
; #pragma unroll
;             for (int n = 0; n < 2; ++n) bv[bj][n] = *(const f32x4*)(bias + bcol0 + bj * 128 + 4 * n);
;         const int b = row0 >> 11, headb = (pn - which * 3) * 4 + (wc >> 1), dim = (wc & 1) * 32 + 8 * fq;
;         unsigned char* base = (unsigned char*)QKV + ((size_t)(which * BATCH + b) * 12 + headb) * (size_t)(SEQ * 64) + dim;
; #pragma unroll
;         for (int ai = 0; ai < 2; ++ai)
; #pragma unroll
;             for (int m = 0; m < 4; ++m) { const int t = (row0 + ai * 128 + m * 16) & (SEQ - 1), pos = ((t & ((1 << dsh) - 1)) << (11 - dsh)) + (t >> dsh);
; #pragma unroll
;                 for (int bj = 0; bj < 2; ++bj) { const f32x4 v0 = (acc[ai][bj][m][0] * as + bv[bj][0]) * sc, v1 = (acc[ai][bj][m][1] * as + bv[bj][1]) * sc;
;                     int w0 = 0, w1 = 0; w0 = __builtin_amdgcn_cvt_pk_fp8_f32(f8c(v0[0]), f8c(v0[1]), w0, false); w0 = __builtin_amdgcn_cvt_pk_fp8_f32(f8c(v0[2]), f8c(v0[3]), w0, true);
;                     w1 = __builtin_amdgcn_cvt_pk_fp8_f32(f8c(v1[0]), f8c(v1[1]), w1, false); w1 = __builtin_amdgcn_cvt_pk_fp8_f32(f8c(v1[2]), f8c(v1[3]), w1, true);
;                     u32x2 w; w.x = (unsigned)w0; w.y = (unsigned)w1;
;                     *(u32x2*)(base + (size_t)(bj * 2) * (SEQ * 64) + (size_t)pos * 64) = w; } }
;     }
.LBB0_191:
	v_ashrrev_i32_e32 v157, 31, v156
	v_lshl_add_u64 v[132:133], v[156:157], 2, s[86:87]
	global_load_dwordx4 v[136:139], v[132:133], off offset:16
	global_load_dwordx4 v[140:143], v[132:133], off
	global_load_dwordx4 v[128:131], v[132:133], off offset:528
	s_nop 0
	global_load_dwordx4 v[132:135], v[132:133], off offset:512
	s_mul_hi_i32 s30, s34, 0x55555556
	s_lshr_b32 s31, s30, 31
	s_add_i32 s31, s30, s31
	s_mul_i32 s30, s31, -3
	s_add_i32 s34, s30, s34
	s_lshl_b32 s30, s34, 1
	s_lshl_b32 s34, s34, 2
	v_ashrrev_i32_e32 v146, 11, v154
	s_or_b32 s34, s34, s59
	v_lshl_add_u32 v146, s31, 4, v146
	s_ashr_i32 s31, s34, 31
	v_mov_b32_e32 v156, s34
	v_mov_b32_e32 v157, s31
	s_sub_i32 s31, 11, s30
	v_mad_i64_i32 v[156:157], s[34:35], v146, 12, v[156:157]
	v_and_b32_e32 v146, 0x7ff, v154
	v_lshlrev_b32_e32 v155, s31, v154
	v_lshlrev_b64 v[156:157], 17, v[156:157]
	v_and_b32_e32 v155, 0x7fe, v155
	v_lshrrev_b32_e32 v146, s30, v146
	v_lshl_add_u64 v[156:157], v[148:149], 0, v[156:157]
	v_add_lshl_u32 v146, v155, v146, 6
	v_lshl_add_u64 v[158:159], v[156:157], 0, v[146:147]
	s_waitcnt vmcnt(0)
	v_pk_fma_f32 v[124:125], v[124:125], s[24:25], v[136:137] op_sel_hi:[1,0,1]
	v_pk_fma_f32 v[120:121], v[120:121], s[24:25], v[140:141] op_sel_hi:[1,0,1]
	v_pk_fma_f32 v[122:123], v[122:123], s[24:25], v[142:143] op_sel_hi:[1,0,1]
	v_med3_f32 v146, v120, s66, v179
	v_med3_f32 v121, v121, s66, v179
	v_cvt_pk_fp8_f32 v120, v146, v121
	v_med3_f32 v121, v122, s66, v179
	v_med3_f32 v122, v123, s66, v179
	v_med3_f32 v123, v125, s66, v179
	v_cvt_pk_fp8_f32 v120, v121, v122 op_sel:[0,0,1]
	v_med3_f32 v122, v124, s66, v179
	v_cvt_pk_fp8_f32 v121, v122, v123
	v_pk_fma_f32 v[126:127], v[126:127], s[24:25], v[138:139] op_sel_hi:[1,0,1]
	v_pk_fma_f32 v[116:117], v[116:117], s[24:25], v[132:133] op_sel_hi:[1,0,1]
	v_med3_f32 v122, v126, s66, v179
	v_med3_f32 v123, v127, s66, v179
	v_cvt_pk_fp8_f32 v121, v122, v123 op_sel:[0,0,1]
	v_med3_f32 v117, v117, s66, v179
	v_pk_fma_f32 v[118:119], v[118:119], s[24:25], v[134:135] op_sel_hi:[1,0,1]
	v_pk_fma_f32 v[112:113], v[112:113], s[24:25], v[128:129] op_sel_hi:[1,0,1]
	global_store_dwordx2 v[158:159], v[120:121], off
	v_med3_f32 v120, v116, s66, v179
	v_cvt_pk_fp8_f32 v116, v120, v117
	v_med3_f32 v117, v118, s66, v179
	v_med3_f32 v118, v119, s66, v179
	v_pk_fma_f32 v[114:115], v[114:115], s[24:25], v[130:131] op_sel_hi:[1,0,1]
	v_cvt_pk_fp8_f32 v116, v117, v118 op_sel:[0,0,1]
	v_med3_f32 v112, v112, s66, v179
	v_med3_f32 v113, v113, s66, v179
	v_pk_fma_f32 v[108:109], v[108:109], s[24:25], v[140:141] op_sel_hi:[1,0,1]
	v_cvt_pk_fp8_f32 v117, v112, v113
	v_med3_f32 v112, v114, s66, v179
	v_med3_f32 v113, v115, s66, v179
	v_pk_fma_f32 v[114:115], v[104:105], s[24:25], v[136:137] op_sel_hi:[1,0,1]
	v_med3_f32 v105, v108, s66, v179
	v_med3_f32 v108, v109, s66, v179
	v_cvt_pk_fp8_f32 v104, v105, v108
	v_pk_fma_f32 v[110:111], v[110:111], s[24:25], v[142:143] op_sel_hi:[1,0,1]
	v_cvt_pk_fp8_f32 v117, v112, v113 op_sel:[0,0,1]
	v_med3_f32 v105, v110, s66, v179
	v_med3_f32 v108, v111, s66, v179
	v_cvt_pk_fp8_f32 v104, v105, v108 op_sel:[0,0,1]
	v_med3_f32 v108, v114, s66, v179
	v_med3_f32 v109, v115, s66, v179
	v_cvt_pk_fp8_f32 v105, v108, v109
	v_add_co_u32_e32 v112, vcc, s67, v158
	v_pk_fma_f32 v[106:107], v[106:107], s[24:25], v[138:139] op_sel_hi:[1,0,1]
	s_nop 0
	v_addc_co_u32_e32 v113, vcc, 0, v159, vcc
	global_store_dwordx2 v[112:113], v[116:117], off
	v_add_u32_e32 v112, 16, v154
	v_med3_f32 v106, v106, s66, v179
	v_med3_f32 v107, v107, s66, v179
	v_and_b32_e32 v113, 0x7ff, v112
	v_lshlrev_b32_e32 v112, s31, v112
	v_cvt_pk_fp8_f32 v105, v106, v107 op_sel:[0,0,1]
	v_and_b32_e32 v112, 0x7fe, v112
	v_lshrrev_b32_e32 v113, s30, v113
	v_add_lshl_u32 v146, v112, v113, 6
	v_lshl_add_u64 v[112:113], v[156:157], 0, v[146:147]
	v_pk_fma_f32 v[100:101], v[100:101], s[24:25], v[132:133] op_sel_hi:[1,0,1]
	global_store_dwordx2 v[112:113], v[104:105], off
	v_med3_f32 v104, v100, s66, v179
	v_med3_f32 v101, v101, s66, v179
	v_cvt_pk_fp8_f32 v100, v104, v101
	v_pk_fma_f32 v[102:103], v[102:103], s[24:25], v[134:135] op_sel_hi:[1,0,1]
	v_pk_fma_f32 v[96:97], v[96:97], s[24:25], v[128:129] op_sel_hi:[1,0,1]
	v_med3_f32 v101, v102, s66, v179
	v_med3_f32 v102, v103, s66, v179
	v_pk_fma_f32 v[98:99], v[98:99], s[24:25], v[130:131] op_sel_hi:[1,0,1]
	v_cvt_pk_fp8_f32 v100, v101, v102 op_sel:[0,0,1]
	v_med3_f32 v96, v96, s66, v179
	v_med3_f32 v97, v97, s66, v179
	v_pk_fma_f32 v[92:93], v[92:93], s[24:25], v[140:141] op_sel_hi:[1,0,1]
	v_cvt_pk_fp8_f32 v101, v96, v97
	v_med3_f32 v96, v98, s66, v179
	v_med3_f32 v98, v92, s66, v179
	v_med3_f32 v93, v93, s66, v179
	v_cvt_pk_fp8_f32 v92, v98, v93
	v_pk_fma_f32 v[94:95], v[94:95], s[24:25], v[142:143] op_sel_hi:[1,0,1]
	v_pk_fma_f32 v[88:89], v[88:89], s[24:25], v[136:137] op_sel_hi:[1,0,1]
	v_med3_f32 v93, v94, s66, v179
	v_med3_f32 v94, v95, s66, v179
	v_cvt_pk_fp8_f32 v92, v93, v94 op_sel:[0,0,1]
	v_med3_f32 v88, v88, s66, v179
	v_med3_f32 v89, v89, s66, v179
	v_cvt_pk_fp8_f32 v93, v88, v89
	v_pk_fma_f32 v[90:91], v[90:91], s[24:25], v[138:139] op_sel_hi:[1,0,1]
	v_pk_fma_f32 v[84:85], v[84:85], s[24:25], v[132:133] op_sel_hi:[1,0,1]
	v_med3_f32 v88, v90, s66, v179
	v_med3_f32 v89, v91, s66, v179
	v_cvt_pk_fp8_f32 v93, v88, v89 op_sel:[0,0,1]
	v_med3_f32 v88, v84, s66, v179
	v_med3_f32 v85, v85, s66, v179
	v_cvt_pk_fp8_f32 v84, v88, v85
	v_pk_fma_f32 v[86:87], v[86:87], s[24:25], v[134:135] op_sel_hi:[1,0,1]
	v_pk_fma_f32 v[80:81], v[80:81], s[24:25], v[128:129] op_sel_hi:[1,0,1]
	v_med3_f32 v85, v86, s66, v179
	v_med3_f32 v86, v87, s66, v179
	v_pk_fma_f32 v[82:83], v[82:83], s[24:25], v[130:131] op_sel_hi:[1,0,1]
; __device__ __forceinline__ float f8c(float v) { return fminf(fmaxf(v, -448.f), 448.f); }
;     __device__ __forceinline__ void qkv_store(const f32x4 (&acc)[2][2][4][2], int pn, int wc, int fq, int bcol0, int row0, float sc) const {
;     ...
;         const int b = row0 >> 11, headb = (pn - which * 3) * 4 + (wc >> 1), dim = (wc & 1) * 32 + 8 * fq;
;         unsigned char* base = (unsigned char*)QKV + ((size_t)(which * BATCH + b) * 12 + headb) * (size_t)(SEQ * 64) + dim;
; #pragma unroll
;         for (int ai = 0; ai < 2; ++ai)
; #pragma unroll
;             for (int m = 0; m < 4; ++m) { const int t = (row0 + ai * 128 + m * 16) & (SEQ - 1), pos = ((t & ((1 << dsh) - 1)) << (11 - dsh)) + (t >> dsh);
; #pragma unroll
;                 for (int bj = 0; bj < 2; ++bj) { const f32x4 v0 = (acc[ai][bj][m][0] * as + bv[bj][0]) * sc, v1 = (acc[ai][bj][m][1] * as + bv[bj][1]) * sc;
;                     int w0 = 0, w1 = 0; w0 = __builtin_amdgcn_cvt_pk_fp8_f32(f8c(v0[0]), f8c(v0[1]), w0, false); w0 = __builtin_amdgcn_cvt_pk_fp8_f32(f8c(v0[2]), f8c(v0[3]), w0, true);
;                     w1 = __builtin_amdgcn_cvt_pk_fp8_f32(f8c(v1[0]), f8c(v1[1]), w1, false); w1 = __builtin_amdgcn_cvt_pk_fp8_f32(f8c(v1[2]), f8c(v1[3]), w1, true);
;                     u32x2 w; w.x = (unsigned)w0; w.y = (unsigned)w1;
;                     *(u32x2*)(base + (size_t)(bj * 2) * (SEQ * 64) + (size_t)pos * 64) = w; } }
;     }
	v_cvt_pk_fp8_f32 v84, v85, v86 op_sel:[0,0,1]
	v_med3_f32 v80, v80, s66, v179
	v_med3_f32 v81, v81, s66, v179
	v_pk_fma_f32 v[76:77], v[76:77], s[24:25], v[140:141] op_sel_hi:[1,0,1]
	v_cvt_pk_fp8_f32 v85, v80, v81
	v_med3_f32 v80, v82, s66, v179
	v_med3_f32 v82, v76, s66, v179
	v_med3_f32 v77, v77, s66, v179
	v_cvt_pk_fp8_f32 v76, v82, v77
	v_pk_fma_f32 v[78:79], v[78:79], s[24:25], v[142:143] op_sel_hi:[1,0,1]
	v_pk_fma_f32 v[72:73], v[72:73], s[24:25], v[136:137] op_sel_hi:[1,0,1]
	v_med3_f32 v77, v78, s66, v179
	v_med3_f32 v78, v79, s66, v179
	v_cvt_pk_fp8_f32 v76, v77, v78 op_sel:[0,0,1]
	v_med3_f32 v72, v72, s66, v179
	v_med3_f32 v73, v73, s66, v179
	v_cvt_pk_fp8_f32 v77, v72, v73
	v_pk_fma_f32 v[74:75], v[74:75], s[24:25], v[138:139] op_sel_hi:[1,0,1]
	v_pk_fma_f32 v[68:69], v[68:69], s[24:25], v[132:133] op_sel_hi:[1,0,1]
	v_med3_f32 v72, v74, s66, v179
	v_med3_f32 v73, v75, s66, v179
	v_cvt_pk_fp8_f32 v77, v72, v73 op_sel:[0,0,1]
	v_med3_f32 v72, v68, s66, v179
	v_med3_f32 v69, v69, s66, v179
	v_cvt_pk_fp8_f32 v68, v72, v69
	v_pk_fma_f32 v[70:71], v[70:71], s[24:25], v[134:135] op_sel_hi:[1,0,1]
	v_pk_fma_f32 v[64:65], v[64:65], s[24:25], v[128:129] op_sel_hi:[1,0,1]
	v_med3_f32 v69, v70, s66, v179
	v_med3_f32 v70, v71, s66, v179
	v_pk_fma_f32 v[66:67], v[66:67], s[24:25], v[130:131] op_sel_hi:[1,0,1]
	v_cvt_pk_fp8_f32 v68, v69, v70 op_sel:[0,0,1]
	v_med3_f32 v64, v64, s66, v179
	v_med3_f32 v65, v65, s66, v179
	v_pk_fma_f32 v[60:61], v[60:61], s[24:25], v[140:141] op_sel_hi:[1,0,1]
	v_cvt_pk_fp8_f32 v69, v64, v65
	v_med3_f32 v64, v66, s66, v179
	v_med3_f32 v66, v60, s66, v179
	v_med3_f32 v61, v61, s66, v179
	v_cvt_pk_fp8_f32 v60, v66, v61
	v_pk_fma_f32 v[62:63], v[62:63], s[24:25], v[142:143] op_sel_hi:[1,0,1]
	v_pk_fma_f32 v[56:57], v[56:57], s[24:25], v[136:137] op_sel_hi:[1,0,1]
	v_med3_f32 v61, v62, s66, v179
	v_med3_f32 v62, v63, s66, v179
	v_cvt_pk_fp8_f32 v60, v61, v62 op_sel:[0,0,1]
	v_med3_f32 v56, v56, s66, v179
	v_med3_f32 v57, v57, s66, v179
	v_cvt_pk_fp8_f32 v61, v56, v57
	v_pk_fma_f32 v[58:59], v[58:59], s[24:25], v[138:139] op_sel_hi:[1,0,1]
	v_pk_fma_f32 v[52:53], v[52:53], s[24:25], v[132:133] op_sel_hi:[1,0,1]
	v_med3_f32 v56, v58, s66, v179
	v_med3_f32 v57, v59, s66, v179
	v_cvt_pk_fp8_f32 v61, v56, v57 op_sel:[0,0,1]
	v_med3_f32 v56, v52, s66, v179
	v_med3_f32 v53, v53, s66, v179
	v_cvt_pk_fp8_f32 v52, v56, v53
	v_pk_fma_f32 v[54:55], v[54:55], s[24:25], v[134:135] op_sel_hi:[1,0,1]
	v_pk_fma_f32 v[48:49], v[48:49], s[24:25], v[128:129] op_sel_hi:[1,0,1]
	v_med3_f32 v53, v54, s66, v179
	v_med3_f32 v54, v55, s66, v179
	v_pk_fma_f32 v[50:51], v[50:51], s[24:25], v[130:131] op_sel_hi:[1,0,1]
	v_cvt_pk_fp8_f32 v52, v53, v54 op_sel:[0,0,1]
	v_med3_f32 v48, v48, s66, v179
	v_med3_f32 v49, v49, s66, v179
	v_pk_fma_f32 v[44:45], v[44:45], s[24:25], v[140:141] op_sel_hi:[1,0,1]
	v_cvt_pk_fp8_f32 v53, v48, v49
	v_med3_f32 v48, v50, s66, v179
	v_med3_f32 v50, v44, s66, v179
	v_med3_f32 v45, v45, s66, v179
	v_cvt_pk_fp8_f32 v44, v50, v45
	v_pk_fma_f32 v[46:47], v[46:47], s[24:25], v[142:143] op_sel_hi:[1,0,1]
	v_pk_fma_f32 v[40:41], v[40:41], s[24:25], v[136:137] op_sel_hi:[1,0,1]
	v_med3_f32 v45, v46, s66, v179
	v_med3_f32 v46, v47, s66, v179
	v_cvt_pk_fp8_f32 v44, v45, v46 op_sel:[0,0,1]
	v_med3_f32 v40, v40, s66, v179
	v_med3_f32 v41, v41, s66, v179
	v_cvt_pk_fp8_f32 v45, v40, v41
	v_pk_fma_f32 v[42:43], v[42:43], s[24:25], v[138:139] op_sel_hi:[1,0,1]
	v_med3_f32 v97, v99, s66, v179
	v_med3_f32 v40, v42, s66, v179
	v_med3_f32 v41, v43, s66, v179
	v_pk_fma_f32 v[36:37], v[36:37], s[24:25], v[132:133] op_sel_hi:[1,0,1]
	v_cvt_pk_fp8_f32 v101, v96, v97 op_sel:[0,0,1]
	v_cvt_pk_fp8_f32 v45, v40, v41 op_sel:[0,0,1]
	v_med3_f32 v40, v36, s66, v179
	v_med3_f32 v37, v37, s66, v179
	v_cvt_pk_fp8_f32 v36, v40, v37
	v_add_co_u32_e32 v96, vcc, s67, v112
	v_pk_fma_f32 v[38:39], v[38:39], s[24:25], v[134:135] op_sel_hi:[1,0,1]
	s_nop 0
	v_addc_co_u32_e32 v97, vcc, 0, v113, vcc
	global_store_dwordx2 v[96:97], v[100:101], off
	v_add_u32_e32 v96, 32, v154
	v_pk_fma_f32 v[32:33], v[32:33], s[24:25], v[128:129] op_sel_hi:[1,0,1]
	v_med3_f32 v37, v38, s66, v179
	v_med3_f32 v38, v39, s66, v179
	v_and_b32_e32 v97, 0x7ff, v96
	v_lshlrev_b32_e32 v96, s31, v96
	v_pk_fma_f32 v[34:35], v[34:35], s[24:25], v[130:131] op_sel_hi:[1,0,1]
	v_cvt_pk_fp8_f32 v36, v37, v38 op_sel:[0,0,1]
	v_med3_f32 v32, v32, s66, v179
	v_med3_f32 v33, v33, s66, v179
	v_pk_fma_f32 v[28:29], v[28:29], s[24:25], v[140:141] op_sel_hi:[1,0,1]
	v_and_b32_e32 v96, 0x7fe, v96
	v_lshrrev_b32_e32 v97, s30, v97
	v_med3_f32 v81, v83, s66, v179
	v_cvt_pk_fp8_f32 v37, v32, v33
	v_med3_f32 v32, v34, s66, v179
	v_med3_f32 v34, v28, s66, v179
	v_med3_f32 v29, v29, s66, v179
	v_add_lshl_u32 v146, v96, v97, 6
	v_cvt_pk_fp8_f32 v85, v80, v81 op_sel:[0,0,1]
	v_cvt_pk_fp8_f32 v28, v34, v29
	v_lshl_add_u64 v[96:97], v[156:157], 0, v[146:147]
	v_add_co_u32_e32 v80, vcc, s67, v96
	v_pk_fma_f32 v[30:31], v[30:31], s[24:25], v[142:143] op_sel_hi:[1,0,1]
	s_nop 0
	v_addc_co_u32_e32 v81, vcc, 0, v97, vcc
; __device__ __forceinline__ float f8c(float v) { return fminf(fmaxf(v, -448.f), 448.f); }
;     __device__ __forceinline__ void qkv_store(const f32x4 (&acc)[2][2][4][2], int pn, int wc, int fq, int bcol0, int row0, float sc) const {
;     ...
;         const int b = row0 >> 11, headb = (pn - which * 3) * 4 + (wc >> 1), dim = (wc & 1) * 32 + 8 * fq;
;         unsigned char* base = (unsigned char*)QKV + ((size_t)(which * BATCH + b) * 12 + headb) * (size_t)(SEQ * 64) + dim;
; #pragma unroll
;         for (int ai = 0; ai < 2; ++ai)
; #pragma unroll
;             for (int m = 0; m < 4; ++m) { const int t = (row0 + ai * 128 + m * 16) & (SEQ - 1), pos = ((t & ((1 << dsh) - 1)) << (11 - dsh)) + (t >> dsh);
; #pragma unroll
;                 for (int bj = 0; bj < 2; ++bj) { const f32x4 v0 = (acc[ai][bj][m][0] * as + bv[bj][0]) * sc, v1 = (acc[ai][bj][m][1] * as + bv[bj][1]) * sc;
;                     int w0 = 0, w1 = 0; w0 = __builtin_amdgcn_cvt_pk_fp8_f32(f8c(v0[0]), f8c(v0[1]), w0, false); w0 = __builtin_amdgcn_cvt_pk_fp8_f32(f8c(v0[2]), f8c(v0[3]), w0, true);
;                     w1 = __builtin_amdgcn_cvt_pk_fp8_f32(f8c(v1[0]), f8c(v1[1]), w1, false); w1 = __builtin_amdgcn_cvt_pk_fp8_f32(f8c(v1[2]), f8c(v1[3]), w1, true);
;                     u32x2 w; w.x = (unsigned)w0; w.y = (unsigned)w1;
;                     *(u32x2*)(base + (size_t)(bj * 2) * (SEQ * 64) + (size_t)pos * 64) = w; } }
;     }
	v_pk_fma_f32 v[24:25], v[24:25], s[24:25], v[136:137] op_sel_hi:[1,0,1]
	v_med3_f32 v29, v30, s66, v179
	v_med3_f32 v30, v31, s66, v179
	global_store_dwordx2 v[80:81], v[84:85], off
	v_add_u32_e32 v80, 48, v154
	v_cvt_pk_fp8_f32 v28, v29, v30 op_sel:[0,0,1]
	v_med3_f32 v24, v24, s66, v179
	v_med3_f32 v25, v25, s66, v179
	v_and_b32_e32 v81, 0x7ff, v80
	v_lshlrev_b32_e32 v80, s31, v80
	v_cvt_pk_fp8_f32 v29, v24, v25
	v_and_b32_e32 v80, 0x7fe, v80
	v_lshrrev_b32_e32 v81, s30, v81
	v_med3_f32 v65, v67, s66, v179
	v_add_lshl_u32 v146, v80, v81, 6
	v_cvt_pk_fp8_f32 v69, v64, v65 op_sel:[0,0,1]
	v_pk_fma_f32 v[26:27], v[26:27], s[24:25], v[138:139] op_sel_hi:[1,0,1]
	v_lshl_add_u64 v[80:81], v[156:157], 0, v[146:147]
	v_med3_f32 v24, v26, s66, v179
	v_med3_f32 v25, v27, s66, v179
	v_pk_fma_f32 v[20:21], v[20:21], s[24:25], v[132:133] op_sel_hi:[1,0,1]
	v_add_co_u32_e32 v64, vcc, s67, v80
	v_cvt_pk_fp8_f32 v29, v24, v25 op_sel:[0,0,1]
	v_med3_f32 v24, v20, s66, v179
	v_med3_f32 v21, v21, s66, v179
	v_addc_co_u32_e32 v65, vcc, 0, v81, vcc
	v_cvt_pk_fp8_f32 v20, v24, v21
	global_store_dwordx2 v[64:65], v[68:69], off
	v_add_u32_e32 v64, 0x80, v154
	v_and_b32_e32 v65, 0x7ff, v64
	v_lshlrev_b32_e32 v64, s31, v64
	v_pk_fma_f32 v[22:23], v[22:23], s[24:25], v[134:135] op_sel_hi:[1,0,1]
	v_and_b32_e32 v64, 0x7fe, v64
	v_lshrrev_b32_e32 v65, s30, v65
	v_med3_f32 v49, v51, s66, v179
	v_pk_fma_f32 v[16:17], v[16:17], s[24:25], v[128:129] op_sel_hi:[1,0,1]
	v_med3_f32 v21, v22, s66, v179
	v_med3_f32 v22, v23, s66, v179
	v_add_lshl_u32 v146, v64, v65, 6
	v_cvt_pk_fp8_f32 v53, v48, v49 op_sel:[0,0,1]
	v_pk_fma_f32 v[18:19], v[18:19], s[24:25], v[130:131] op_sel_hi:[1,0,1]
	v_cvt_pk_fp8_f32 v20, v21, v22 op_sel:[0,0,1]
	v_med3_f32 v16, v16, s66, v179
	v_med3_f32 v17, v17, s66, v179
	v_pk_fma_f32 v[12:13], v[12:13], s[24:25], v[140:141] op_sel_hi:[1,0,1]
	v_lshl_add_u64 v[64:65], v[156:157], 0, v[146:147]
	v_cvt_pk_fp8_f32 v21, v16, v17
	v_med3_f32 v16, v18, s66, v179
	v_med3_f32 v18, v12, s66, v179
	v_med3_f32 v13, v13, s66, v179
	v_add_co_u32_e32 v48, vcc, s67, v64
	v_cvt_pk_fp8_f32 v12, v18, v13
	s_nop 0
	v_addc_co_u32_e32 v49, vcc, 0, v65, vcc
	global_store_dwordx2 v[48:49], v[52:53], off
	v_add_u32_e32 v48, 0x90, v154
	v_pk_fma_f32 v[14:15], v[14:15], s[24:25], v[142:143] op_sel_hi:[1,0,1]
	v_and_b32_e32 v49, 0x7ff, v48
	v_lshlrev_b32_e32 v48, s31, v48
	v_pk_fma_f32 v[8:9], v[8:9], s[24:25], v[136:137] op_sel_hi:[1,0,1]
	v_med3_f32 v13, v14, s66, v179
	v_med3_f32 v14, v15, s66, v179
	v_and_b32_e32 v48, 0x7fe, v48
	v_lshrrev_b32_e32 v49, s30, v49
	v_med3_f32 v33, v35, s66, v179
	v_cvt_pk_fp8_f32 v12, v13, v14 op_sel:[0,0,1]
	v_med3_f32 v8, v8, s66, v179
	v_med3_f32 v9, v9, s66, v179
	v_add_lshl_u32 v146, v48, v49, 6
	v_cvt_pk_fp8_f32 v37, v32, v33 op_sel:[0,0,1]
	v_cvt_pk_fp8_f32 v13, v8, v9
	v_lshl_add_u64 v[48:49], v[156:157], 0, v[146:147]
	v_add_co_u32_e32 v32, vcc, s67, v48
	v_pk_fma_f32 v[10:11], v[10:11], s[24:25], v[138:139] op_sel_hi:[1,0,1]
	s_nop 0
	v_addc_co_u32_e32 v33, vcc, 0, v49, vcc
	v_med3_f32 v8, v10, s66, v179
	v_med3_f32 v9, v11, s66, v179
	v_pk_fma_f32 v[4:5], v[4:5], s[24:25], v[132:133] op_sel_hi:[1,0,1]
	global_store_dwordx2 v[32:33], v[36:37], off
	v_add_u32_e32 v32, 0xa0, v154
	v_cvt_pk_fp8_f32 v13, v8, v9 op_sel:[0,0,1]
	v_med3_f32 v8, v4, s66, v179
	v_med3_f32 v5, v5, s66, v179
	v_and_b32_e32 v33, 0x7ff, v32
	v_lshlrev_b32_e32 v32, s31, v32
	v_cvt_pk_fp8_f32 v4, v8, v5
	v_and_b32_e32 v32, 0x7fe, v32
	v_lshrrev_b32_e32 v33, s30, v33
	v_med3_f32 v17, v19, s66, v179
	v_add_lshl_u32 v146, v32, v33, 6
	v_cvt_pk_fp8_f32 v21, v16, v17 op_sel:[0,0,1]
	v_pk_fma_f32 v[6:7], v[6:7], s[24:25], v[134:135] op_sel_hi:[1,0,1]
	v_lshl_add_u64 v[32:33], v[156:157], 0, v[146:147]
	v_pk_fma_f32 v[0:1], v[0:1], s[24:25], v[128:129] op_sel_hi:[1,0,1]
	v_med3_f32 v5, v6, s66, v179
	v_med3_f32 v6, v7, s66, v179
	v_add_co_u32_e32 v16, vcc, s67, v32
	v_cvt_pk_fp8_f32 v4, v5, v6 op_sel:[0,0,1]
	v_med3_f32 v0, v0, s66, v179
	v_med3_f32 v1, v1, s66, v179
	v_addc_co_u32_e32 v17, vcc, 0, v33, vcc
	v_cvt_pk_fp8_f32 v5, v0, v1
	global_store_dwordx2 v[16:17], v[20:21], off
	v_add_u32_e32 v16, 0xb0, v154
	v_and_b32_e32 v17, 0x7ff, v16
	v_lshlrev_b32_e32 v16, s31, v16
	v_pk_fma_f32 v[2:3], v[2:3], s[24:25], v[130:131] op_sel_hi:[1,0,1]
	v_and_b32_e32 v16, 0x7fe, v16
	v_lshrrev_b32_e32 v17, s30, v17
	v_med3_f32 v0, v2, s66, v179
	v_med3_f32 v1, v3, s66, v179
	v_add_lshl_u32 v146, v16, v17, 6
	v_cvt_pk_fp8_f32 v5, v0, v1 op_sel:[0,0,1]
	v_lshl_add_u64 v[16:17], v[156:157], 0, v[146:147]
	v_add_co_u32_e32 v0, vcc, 0x40000, v16
	global_store_dwordx2 v[96:97], v[92:93], off
	s_nop 0
	v_addc_co_u32_e32 v1, vcc, 0, v17, vcc
	global_store_dwordx2 v[80:81], v[76:77], off
	global_store_dwordx2 v[64:65], v[60:61], off
	global_store_dwordx2 v[48:49], v[44:45], off
	global_store_dwordx2 v[32:33], v[28:29], off
	global_store_dwordx2 v[16:17], v[12:13], off
	global_store_dwordx2 v[0:1], v[4:5], off
	s_and_b64 vcc, exec, s[4:5]
	s_mov_b64 s[4:5], -1
	s_cbranch_vccnz .LBB0_170

; __device__ __forceinline__ void attn_load(const unsigned char* QKV, const AttnUnitGeo& u, int tid, int w, int fr, int quad, u32x4 (&kr)[2], u32x4 (&vr)[2], long& q0, long& q1) {
;     const size_t hs = (size_t)SEQ * 64;
;     const unsigned char* qh = QKV + ((size_t)(0 * BATCH + u.b) * 12 + u.head) * hs; const unsigned char* kh = qh + (size_t)BATCH * 12 * hs; const unsigned char* vh = kh + (size_t)BATCH * 12 * hs;
;     const int p0 = (u.r << (11 - u.dsh)) + u.nb * 128;
; #pragma unroll
;     for (int i = 0; i < 2; ++i) { const int c = tid + NTHREADS * i, row = c >> 2, part = c & 3;
;         kr[i] = (u32x4){0u, 0u, 0u, 0u}; if (u.nb > 0 || row >= 128) kr[i] = *(const u32x4*)(kh + (size_t)(p0 - 128 + row) * 64 + part * 16); }
; #pragma unroll
;     for (int i = 0; i < 2; ++i) { const int c = tid + NTHREADS * i, part = c >> 8, row = c & 255;
;         vr[i] = (u32x4){0u, 0u, 0u, 0u}; if (u.nb > 0 || row >= 128) vr[i] = *(const u32x4*)(vh + (size_t)(p0 - 128 + row) * 64 + part * 16); }
;     const unsigned char* qp = qh + (size_t)(p0 + 16 * w + fr) * 64 + quad * 8;
;     q0 = *(const long*)qp; q1 = *(const long*)(qp + 32);
; }
; __device__ __forceinline__ void attn_phase(const Params& p, LAS unsigned char* lds, int tid, int G, int bid) {
;     const int w = __builtin_amdgcn_readfirstlane(tid >> 6), lane = tid & 63, fr = lane & 15, quad = lane >> 4;
;     const unsigned char* QKV = p.ws + WS_QKV;
;     bf16_t* OG = (bf16_t*)((unsigned char*)p.out + DO_OG);
;     float* LSE = (float*)((unsigned char*)p.out + DO_LSE);
;     u32x4 kr[2], vr[2]; long nq0 = 0, nq1 = 0; int ucnt = 0;
;     u32x4 cuu[4], cgg[4], cum2 = {0u, 0u, 0u, 0u}, cum1 = cum2;
; #pragma unroll
;     for (int i = 0; i < 4; ++i) { cuu[i] = cum2; cgg[i] = cum2; }
;     for (int e = tid; e < 3 * D; e += NTHREADS) *(LAS float*)(lds + CW_OFF + e * 4) = p.conv_w[e];
;     if (bid < 3072) { const AttnUnitGeo u0 = attn_geo(bid); attn_load(QKV, u0, tid, w, fr, quad, kr, vr, nq0, nq1); }
;     for (int uid = bid; uid < 3072; uid += G) {
;         const AttnUnitGeo u = attn_geo(uid);
;     ...
; #pragma unroll
;         for (int i = 0; i < 2; ++i) { const int c = tid + NTHREADS * i, row = c >> 2, part = c & 3; *(LAS u32x4*)(lds + row * KS_PITCH + part * 16) = kr[i]; }
; #pragma unroll
;         for (int i = 0; i < 2; ++i) { const int c = tid + NTHREADS * i, part = c >> 8, row = c & 255; const u32x4 v = vr[i];
.LBB0_269:
	s_or_b64 exec, exec, s[4:5]
	s_ashr_i32 s4, s10, 6
	s_lshl_b32 s5, s4, 4
	v_and_b32_e32 v41, 15, v144
	s_add_i32 s6, s5, s8
	v_add_u32_e32 v20, s6, v41
	v_ashrrev_i32_e32 v21, 31, v20
	v_bfe_u32 v22, v144, 4, 2
	v_lshlrev_b64 v[20:21], 6, v[20:21]
	v_lshl_add_u64 v[20:21], s[0:1], 0, v[20:21]
	v_lshlrev_b32_e32 v90, 3, v22
	v_mov_b32_e32 v91, v8
	v_lshl_add_u64 v[20:21], v[20:21], 0, v[90:91]
	global_load_dwordx2 v[60:61], v[20:21], off offset:32
	global_load_dwordx2 v[62:63], v[20:21], off
	v_lshlrev_b32_e32 v20, 2, v22
	v_mbcnt_lo_u32_b32 v22, -1, 0
	v_mbcnt_hi_u32_b32 v22, -1, v22
	v_and_b32_e32 v27, 64, v22
	s_add_i32 s0, s4, s3
	v_xor_b32_e32 v23, 16, v22
	v_add_u32_e32 v27, 64, v27
	v_writelane_b32 v250, s0, 34
	s_lshl_b32 s0, s4, 9
	v_cmp_lt_i32_e32 vcc, v23, v27
	v_and_b32_e32 v24, 63, v144
	s_and_b32 s0, s0, 0x200
	v_cndmask_b32_e32 v23, v22, v23, vcc
	s_mulk_i32 s4, 0x900
	v_lshl_or_b32 v94, v24, 3, s0
	v_lshlrev_b32_e32 v122, 2, v23
	v_xor_b32_e32 v23, 32, v22
	s_add_i32 s0, s4, 0
	v_cmp_lt_i32_e32 vcc, v23, v27
	s_add_i32 s0, s0, 0x12000
	v_cmp_gt_u32_e64 s[6:7], 16, v24
	v_cndmask_b32_e32 v22, v22, v23, vcc
	v_mov_b32_e32 v23, s0
	s_movk_i32 s0, 0x110
	s_movk_i32 s1, 0x50
	v_bfe_u32 v27, v144, 2, 4
	v_writelane_b32 v250, s6, 35
	v_mul_lo_u32 v35, v86, s0
	v_mul_lo_u32 v36, v88, s0
	s_and_b32 s0, s5, 0xffffffe0
	v_or_b32_e32 v92, s5, v41
	v_lshlrev_b32_e32 v123, 2, v22
	v_mad_u32_u24 v22, v41, s1, v23
	v_or_b32_e32 v124, s5, v27
	v_mad_u32_u24 v23, v27, s1, v23
	v_writelane_b32 v250, s7, 36
	v_or_b32_e32 v27, s0, v41
	s_or_b32 s8, s5, 16
	s_add_i32 s9, s0, 32
	s_add_i32 s10, s0, 48
	s_add_i32 s11, s0, 64
	s_add_i32 s12, s0, 0x50
	s_add_i32 s13, s0, 0x60
	s_add_i32 s7, s0, 0x70
	s_add_i32 s6, s0, 0x80
	s_add_i32 s4, s0, 0x90
	v_add_u32_e32 v42, 0x80, v92
	v_mul_lo_u32 v29, v27, s1
	v_or_b32_e32 v27, s8, v41
	v_or_b32_e32 v28, s9, v41
	v_or_b32_e32 v30, s10, v41
	v_or_b32_e32 v31, s11, v41
	v_or_b32_e32 v32, s12, v41
	v_or_b32_e32 v37, s13, v41
	v_or_b32_e32 v38, s7, v41
	v_or_b32_e32 v39, s6, v41
	v_or_b32_e32 v40, s4, v41
	v_or_b32_e32 v44, s0, v20
	v_mul_lo_u32 v33, v120, s1
	v_mul_lo_u32 v34, v121, s1
	v_mul_lo_u32 v27, v27, s1
	v_mul_lo_u32 v28, v28, s1
	v_mul_lo_u32 v30, v30, s1
	v_mul_lo_u32 v31, v31, s1
	v_mul_lo_u32 v32, v32, s1
	v_mul_lo_u32 v37, v37, s1
	v_mul_lo_u32 v38, v38, s1
	v_mul_lo_u32 v39, v39, s1
	v_mul_lo_u32 v40, v40, s1
	v_sub_u32_e32 v45, v42, v44
	s_movk_i32 s1, 0x81
	v_cmp_gt_u32_e64 s[14:15], s1, v45
	s_movk_i32 s3, 0x7f
	v_cvt_f32_u32_e32 v125, v45
	v_writelane_b32 v250, s14, 37
	v_xad_u32 v45, v44, -1, v42
	s_movk_i32 s5, 0x7e
	v_writelane_b32 v250, s15, 38
	v_cmp_lt_i32_e64 s[14:15], s3, v44
	v_cvt_f32_u32_e32 v126, v45
	v_add_u32_e32 v21, 0, v90
	v_writelane_b32 v250, s14, 39
	v_sub_u32_e32 v43, v21, v20
	v_lshlrev_b32_e32 v24, 2, v94
	v_writelane_b32 v250, s15, 40
	v_cmp_gt_u32_e64 s[14:15], s1, v45
	v_or_b32_e32 v45, 2, v44
	v_sub_u32_e32 v46, v42, v45
	v_writelane_b32 v250, s14, 41
	v_cvt_f32_u32_e32 v127, v46
	v_ashrrev_i32_e32 v93, 31, v92
	v_writelane_b32 v250, s15, 42
	v_cmp_lt_i32_e64 s[14:15], s5, v44
	v_or_b32_e32 v44, 3, v44
	v_add_u32_e32 v26, 0, v84
	v_writelane_b32 v250, s14, 43
	v_add_u32_sdwa v25, v8, v144 dst_sel:DWORD dst_unused:UNUSED_PAD src0_sel:DWORD src1_sel:BYTE_0
	v_mul_u32_u24_e32 v41, 0x110, v41
	v_writelane_b32 v250, s15, 44
	v_cmp_gt_u32_e64 s[14:15], s1, v46
	v_add_u32_e32 v181, v22, v20
	v_add_u32_e32 v166, v26, v34
	v_writelane_b32 v250, s14, 45
	v_add_u32_e32 v167, v25, v35
	v_add_u32_e32 v168, v25, v36
	v_writelane_b32 v250, s15, 46
	v_cmp_lt_i32_e64 s[14:15], s3, v45
	v_sub_u32_e32 v45, v42, v44
	v_cvt_f32_u32_e32 v128, v45
	v_writelane_b32 v250, s14, 47
	v_add_u32_e32 v169, v21, v29
	v_add_u32_e32 v171, v21, v27
	v_writelane_b32 v250, s15, 48
	v_cmp_gt_u32_e64 s[14:15], s1, v45
	v_add_u32_e32 v172, v21, v28
	v_add_u32_e32 v173, v21, v30
	v_writelane_b32 v250, s14, 49
	v_add_u32_e32 v174, v21, v31
	v_add_u32_e32 v175, v21, v32
	v_writelane_b32 v250, s15, 50
	v_cmp_lt_i32_e64 s[14:15], s3, v44
	v_or_b32_e32 v44, s8, v20
	v_sub_u32_e32 v45, v42, v44
	v_writelane_b32 v250, s14, 51
	v_cvt_f32_u32_e32 v129, v45
	v_add_u32_e32 v176, v21, v37
	v_writelane_b32 v250, s15, 52
	v_cmp_gt_u32_e64 s[14:15], s1, v45
	v_xad_u32 v45, v44, -1, v42
	v_cvt_f32_u32_e32 v130, v45
	v_writelane_b32 v250, s14, 53
	v_add_u32_e32 v177, v21, v38
	v_add_u32_e32 v178, v21, v39
	v_writelane_b32 v250, s15, 54
	v_cmp_lt_i32_e64 s[14:15], s3, v44
	v_add_u32_e32 v179, v21, v40
	v_add_u32_e32 v182, v23, v84
	v_writelane_b32 v250, s14, 55
	v_mov_b64_e32 v[38:39], v[10:11]
	v_mov_b64_e32 v[30:31], v[10:11]
	v_writelane_b32 v250, s15, 56
	v_cmp_gt_u32_e64 s[14:15], s1, v45
	v_or_b32_e32 v45, 2, v44
	v_sub_u32_e32 v46, v42, v45
	v_writelane_b32 v250, s14, 57
	v_cvt_f32_u32_e32 v131, v46
	v_mov_b64_e32 v[50:51], v[10:11]
	v_writelane_b32 v250, s15, 58
	v_cmp_lt_i32_e64 s[14:15], s5, v44
	v_or_b32_e32 v44, 3, v44
	v_mov_b64_e32 v[58:59], v[10:11]
	v_writelane_b32 v250, s14, 59
	v_mov_b64_e32 v[54:55], v[10:11]
	v_mov_b32_e32 v95, v8
	v_writelane_b32 v250, s15, 60
	v_cmp_gt_u32_e64 s[14:15], s1, v46
	s_mov_b32 s80, 0x3e38aa3b
	s_mov_b32 s81, 0xc3e00000
	v_writelane_b32 v250, s14, 61
	v_mov_b32_e32 v184, 0xff800000
	v_mov_b32_e32 v185, 0x43e00000
	v_writelane_b32 v250, s15, 62
	v_cmp_lt_i32_e64 s[14:15], s3, v45
	v_sub_u32_e32 v45, v42, v44
	v_cvt_f32_u32_e32 v132, v45
	v_writelane_b32 v250, s14, 63
	v_mov_b64_e32 v[36:37], v[8:9]
	v_mov_b64_e32 v[28:29], v[8:9]
	v_writelane_b32 v249, s15, 0
	v_cmp_gt_u32_e64 s[14:15], s1, v45
	v_mov_b64_e32 v[48:49], v[8:9]
	v_mov_b64_e32 v[56:57], v[8:9]
	v_writelane_b32 v249, s14, 1
	v_mov_b64_e32 v[52:53], v[8:9]
	s_waitcnt vmcnt(0)
; __device__ __forceinline__ void attn_phase(const Params& p, LAS unsigned char* lds, int tid, int G, int bid) {
;     ...
;         for (int tt = 0; tt < 10; ++tt)
; #pragma unroll
;             for (int j = 0; j < 4; ++j) { const int kj = 16 * (tstart + tt) + 4 * quad + j, delta = qi + 128 - kj;
;                 const bool valid = (delta >= 0) && (delta <= 128) && (nb > 0 || kj >= 128);
;                 const float v = valid ? s[tt][j] - sl2 * (float)delta : -INFINITY; s[tt][j] = v; mx = fmaxf(mx, v); }
	v_mov_b64_e32 v[100:101], v[62:63]
	v_writelane_b32 v249, s15, 2
	v_cmp_lt_i32_e64 s[14:15], s3, v44
	v_or_b32_e32 v44, s9, v20
	v_sub_u32_e32 v45, v42, v44
	v_writelane_b32 v249, s14, 3
	v_cmp_gt_u32_e64 s[8:9], s1, v45
	v_cvt_f32_u32_e32 v133, v45
	v_writelane_b32 v249, s15, 4
	v_writelane_b32 v249, s8, 5
	v_xad_u32 v45, v44, -1, v42
	v_cvt_f32_u32_e32 v134, v45
	v_writelane_b32 v249, s9, 6
	v_cmp_lt_i32_e64 s[8:9], s3, v44
	v_mov_b64_e32 v[102:103], v[60:61]
	s_nop 0
	v_writelane_b32 v249, s8, 7
	s_nop 1
	v_writelane_b32 v249, s9, 8
	v_cmp_gt_u32_e64 s[8:9], s1, v45
	v_or_b32_e32 v45, 2, v44
	v_sub_u32_e32 v46, v42, v45
	v_writelane_b32 v249, s8, 9
	v_cvt_f32_u32_e32 v135, v46
	s_nop 0
	v_writelane_b32 v249, s9, 10
	v_cmp_lt_i32_e64 s[8:9], s5, v44
	v_or_b32_e32 v44, 3, v44
	s_nop 0
	v_writelane_b32 v249, s8, 11
	s_nop 1
	v_writelane_b32 v249, s9, 12
	v_cmp_gt_u32_e64 s[8:9], s1, v46
	s_nop 1
	v_writelane_b32 v249, s8, 13
	s_nop 1
	v_writelane_b32 v249, s9, 14
	v_cmp_lt_i32_e64 s[8:9], s3, v45
	v_sub_u32_e32 v45, v42, v44
	v_cvt_f32_u32_e32 v136, v45
	v_writelane_b32 v249, s8, 15
	s_nop 1
	v_writelane_b32 v249, s9, 16
	v_cmp_gt_u32_e64 s[8:9], s1, v45
	s_nop 1
	v_writelane_b32 v249, s8, 17
	s_nop 1
	v_writelane_b32 v249, s9, 18
	v_cmp_lt_i32_e64 s[8:9], s3, v44
	v_or_b32_e32 v44, s10, v20
	v_sub_u32_e32 v45, v42, v44
	v_writelane_b32 v249, s8, 19
	v_cvt_f32_u32_e32 v137, v45
	s_nop 0
	v_writelane_b32 v249, s9, 20
	v_cmp_gt_u32_e64 s[8:9], s1, v45
	v_xad_u32 v45, v44, -1, v42
	v_cvt_f32_u32_e32 v138, v45
	v_writelane_b32 v249, s8, 21
	s_nop 1
	v_writelane_b32 v249, s9, 22
	v_cmp_lt_i32_e64 s[8:9], s3, v44
	s_nop 1
	v_writelane_b32 v249, s8, 23
	s_nop 1
	v_writelane_b32 v249, s9, 24
	v_cmp_gt_u32_e64 s[8:9], s1, v45
	v_or_b32_e32 v45, 2, v44
	v_sub_u32_e32 v46, v42, v45
	v_writelane_b32 v249, s8, 25
	v_cvt_f32_u32_e32 v139, v46
	s_nop 0
	v_writelane_b32 v249, s9, 26
	v_cmp_lt_i32_e64 s[8:9], s5, v44
	v_or_b32_e32 v44, 3, v44
	s_nop 0
	v_writelane_b32 v249, s8, 27
	s_nop 1
	v_writelane_b32 v249, s9, 28
	v_cmp_gt_u32_e64 s[8:9], s1, v46
	s_nop 1
	v_writelane_b32 v249, s8, 29
	s_nop 1
	v_writelane_b32 v249, s9, 30
	v_cmp_lt_i32_e64 s[8:9], s3, v45
	v_sub_u32_e32 v45, v42, v44
	v_cvt_f32_u32_e32 v140, v45
	v_writelane_b32 v249, s8, 31
	s_nop 1
	v_writelane_b32 v249, s9, 32
	v_cmp_gt_u32_e64 s[8:9], s1, v45
	s_nop 1
	v_writelane_b32 v249, s8, 33
	s_nop 1
	v_writelane_b32 v249, s9, 34
	v_cmp_lt_i32_e64 s[8:9], s3, v44
	v_or_b32_e32 v44, s11, v20
	v_sub_u32_e32 v45, v42, v44
	v_writelane_b32 v249, s8, 35
	v_cvt_f32_u32_e32 v141, v45
	s_mov_b32 s11, s2
	v_writelane_b32 v249, s9, 36
	v_cmp_gt_u32_e64 s[8:9], s1, v45
	v_xad_u32 v45, v44, -1, v42
	v_cvt_f32_u32_e32 v142, v45
	v_writelane_b32 v249, s8, 37
	s_nop 1
	v_writelane_b32 v249, s9, 38
	v_cmp_lt_i32_e64 s[8:9], s3, v44
	s_nop 1
	v_writelane_b32 v249, s8, 39
	s_nop 1
	v_writelane_b32 v249, s9, 40
	v_cmp_gt_u32_e64 s[8:9], s1, v45
	v_or_b32_e32 v45, 2, v44
	v_sub_u32_e32 v46, v42, v45
	v_writelane_b32 v249, s8, 41
	v_cvt_f32_u32_e32 v143, v46
	s_nop 0
	v_writelane_b32 v249, s9, 42
	v_cmp_lt_i32_e64 s[8:9], s5, v44
	v_or_b32_e32 v44, 3, v44
	s_nop 0
	v_writelane_b32 v249, s8, 43
	s_nop 1
	v_writelane_b32 v249, s9, 44
	v_cmp_gt_u32_e64 s[8:9], s1, v46
	s_nop 1
	v_writelane_b32 v249, s8, 45
	s_nop 1
	v_writelane_b32 v249, s9, 46
	v_cmp_lt_i32_e64 s[8:9], s3, v45
	v_sub_u32_e32 v45, v42, v44
	v_cvt_f32_u32_e32 v145, v45
	v_writelane_b32 v249, s8, 47
	s_nop 1
	v_writelane_b32 v249, s9, 48
	v_cmp_gt_u32_e64 s[8:9], s1, v45
	s_nop 1
	v_writelane_b32 v249, s8, 49
	s_nop 1
	v_writelane_b32 v249, s9, 50
	v_cmp_lt_i32_e64 s[8:9], s3, v44
	v_or_b32_e32 v44, s12, v20
	v_sub_u32_e32 v45, v42, v44
	v_writelane_b32 v249, s8, 51
	v_cvt_f32_u32_e32 v146, v45
	s_nop 0
	v_writelane_b32 v249, s9, 52
	v_cmp_gt_u32_e64 s[8:9], s1, v45
	v_xad_u32 v45, v44, -1, v42
	v_cvt_f32_u32_e32 v147, v45
	v_writelane_b32 v249, s8, 53
	s_nop 1
	v_writelane_b32 v249, s9, 54
	v_cmp_lt_i32_e64 s[8:9], s3, v44
	s_nop 1
	v_writelane_b32 v249, s8, 55
	s_nop 1
	v_writelane_b32 v249, s9, 56
	v_cmp_gt_u32_e64 s[8:9], s1, v45
	v_or_b32_e32 v45, 2, v44
	v_sub_u32_e32 v46, v42, v45
	v_writelane_b32 v249, s8, 57
	v_cvt_f32_u32_e32 v148, v46
	s_nop 0
	v_writelane_b32 v249, s9, 58
	v_cmp_lt_i32_e64 s[8:9], s5, v44
	v_or_b32_e32 v44, 3, v44
	s_nop 0
	v_writelane_b32 v249, s8, 59
	s_nop 1
	v_writelane_b32 v249, s9, 60
	v_cmp_gt_u32_e64 s[8:9], s1, v46
	s_nop 1
	v_writelane_b32 v249, s8, 61
	s_nop 1
	v_writelane_b32 v249, s9, 62
	v_cmp_lt_i32_e64 s[8:9], s3, v45
	v_sub_u32_e32 v45, v42, v44
	v_cvt_f32_u32_e32 v149, v45
	v_writelane_b32 v249, s8, 63
	s_nop 1
	v_writelane_b32 v248, s9, 0
	v_cmp_gt_u32_e64 s[8:9], s1, v45
	s_nop 1
	v_writelane_b32 v248, s8, 1
	s_nop 1
	v_writelane_b32 v248, s9, 2
	v_cmp_lt_i32_e64 s[8:9], s3, v44
	v_or_b32_e32 v44, s13, v20
	v_sub_u32_e32 v45, v42, v44
	v_writelane_b32 v248, s8, 3
	v_cvt_f32_u32_e32 v150, v45
	v_cmp_lt_i32_e64 s[16:17], s5, v44
	v_writelane_b32 v248, s9, 4
	v_cmp_gt_u32_e64 s[8:9], s1, v45
	v_xad_u32 v45, v44, -1, v42
	v_cmp_gt_u32_e64 s[14:15], s1, v45
	v_writelane_b32 v248, s8, 5
	v_cvt_f32_u32_e32 v151, v45
	v_or_b32_e32 v45, 2, v44
	v_writelane_b32 v248, s9, 6
	v_cmp_lt_i32_e64 s[8:9], s3, v44
	v_or_b32_e32 v44, 3, v44
	v_sub_u32_e32 v46, v42, v45
	v_cmp_lt_i32_e64 s[20:21], s3, v45
	v_sub_u32_e32 v45, v42, v44
	v_cmp_lt_i32_e64 s[24:25], s3, v44
	v_or_b32_e32 v44, s7, v20
	v_cmp_gt_u32_e64 s[22:23], s1, v45
	v_cvt_f32_u32_e32 v153, v45
	v_sub_u32_e32 v45, v42, v44
	v_cmp_gt_u32_e64 s[26:27], s1, v45
	v_cvt_f32_u32_e32 v154, v45
	v_xad_u32 v45, v44, -1, v42
	v_cmp_lt_i32_e64 s[28:29], s3, v44
; #define LAS __attribute__((address_space(3)))
; __device__ __forceinline__ void attn_phase(const Params& p, LAS unsigned char* lds, int tid, int G, int bid) {
;     ...
;         for (int i = 0; i < 2; ++i) { const int c = tid + NTHREADS * i, row = c >> 2, part = c & 3; *(LAS u32x4*)(lds + row * KS_PITCH + part * 16) = kr[i]; }
; #pragma unroll
;         for (int i = 0; i < 2; ++i) { const int c = tid + NTHREADS * i, part = c >> 8, row = c & 255; const u32x4 v = vr[i];
;             LAS unsigned char* vt = lds + VT_OFF + (part * 16) * VT_PITCH + row;
; #pragma unroll
;             for (int e = 0; e < 16; ++e) vt[e * VT_PITCH] = (unsigned char)((v[e >> 2] >> (8 * (e & 3))) & 0xffu); }
;     ...
;         for (int tt = 0; tt < 10; ++tt)
; #pragma unroll
;             for (int j = 0; j < 4; ++j) { const int kj = 16 * (tstart + tt) + 4 * quad + j, delta = qi + 128 - kj;
;                 const bool valid = (delta >= 0) && (delta <= 128) && (nb > 0 || kj >= 128);
;                 const float v = valid ? s[tt][j] - sl2 * (float)delta : -INFINITY; s[tt][j] = v; mx = fmaxf(mx, v); }
	v_cmp_gt_u32_e64 s[30:31], s1, v45
	v_cmp_lt_i32_e64 s[34:35], s5, v44
	v_cvt_f32_u32_e32 v155, v45
	v_or_b32_e32 v45, 2, v44
	v_or_b32_e32 v44, 3, v44
	v_cmp_gt_u32_e64 s[18:19], s1, v46
	v_cvt_f32_u32_e32 v152, v46
	v_sub_u32_e32 v46, v42, v45
	v_cmp_lt_i32_e64 s[38:39], s3, v45
	v_sub_u32_e32 v45, v42, v44
	v_cmp_lt_i32_e64 s[42:43], s3, v44
	v_or_b32_e32 v44, s6, v20
	v_cmp_gt_u32_e64 s[40:41], s1, v45
	v_cvt_f32_u32_e32 v157, v45
	v_sub_u32_e32 v45, v42, v44
	v_cmp_gt_u32_e64 s[44:45], s1, v45
	v_cvt_f32_u32_e32 v158, v45
	v_xad_u32 v45, v44, -1, v42
	v_cmp_lt_i32_e64 s[46:47], s3, v44
	v_cmp_gt_u32_e64 s[48:49], s1, v45
	v_cmp_lt_i32_e64 s[50:51], s5, v44
	v_cvt_f32_u32_e32 v159, v45
	v_or_b32_e32 v45, 2, v44
	v_or_b32_e32 v44, 3, v44
	v_cmp_gt_u32_e64 s[36:37], s1, v46
	v_cvt_f32_u32_e32 v156, v46
	v_sub_u32_e32 v46, v42, v45
	v_cmp_lt_i32_e64 s[54:55], s3, v45
	v_sub_u32_e32 v45, v42, v44
	v_cmp_lt_i32_e64 s[58:59], s3, v44
	v_or_b32_e32 v44, s4, v20
	v_cmp_gt_u32_e64 s[56:57], s1, v45
	v_cvt_f32_u32_e32 v161, v45
	v_sub_u32_e32 v45, v42, v44
	v_cmp_gt_u32_e64 s[60:61], s1, v45
	v_cvt_f32_u32_e32 v162, v45
	v_xad_u32 v45, v44, -1, v42
	v_cmp_lt_i32_e64 s[62:63], s3, v44
	v_cmp_gt_u32_e64 s[64:65], s1, v45
	v_cmp_lt_i32_e64 s[66:67], s5, v44
	v_cvt_f32_u32_e32 v163, v45
	v_or_b32_e32 v45, 2, v44
	v_or_b32_e32 v44, 3, v44
	v_cmp_gt_u32_e64 s[52:53], s1, v46
	v_cvt_f32_u32_e32 v160, v46
	v_sub_u32_e32 v46, v42, v45
	v_cmp_lt_i32_e64 s[70:71], s3, v45
	v_sub_u32_e32 v42, v42, v44
	v_cmp_lt_i32_e64 s[74:75], s3, v44
	s_ashr_i32 s3, s2, 31
	v_cmp_gt_u32_e64 s[68:69], s1, v46
	v_cmp_gt_u32_e64 s[72:73], s1, v42
	v_add_u32_e32 v44, s0, v43
	s_lshl_b64 s[0:1], s[2:3], 9
	s_add_u32 s0, s94, s0
	v_cvt_f32_u32_e32 v164, v46
	v_cvt_f32_u32_e32 v165, v42
	v_lshlrev_b32_e32 v42, 1, v94
	v_mov_b32_e32 v43, v8
	s_addc_u32 s1, s95, s1
	v_lshl_add_u64 v[96:97], s[90:91], 0, v[42:43]
	v_lshl_add_u64 v[42:43], v[92:93], 2, s[0:1]
	s_mov_b64 s[0:1], 0x4000000
	v_add_u32_e32 v20, 0, v24
	v_writelane_b32 v248, s8, 7
	v_lshl_add_u64 v[98:99], v[42:43], 0, s[0:1]
	s_ashr_i32 s1, s98, 31
	s_mov_b32 s0, s98
	v_add_u32_e32 v93, v26, v33
	v_add_u32_e32 v180, v44, v41
	v_add_u32_e32 v183, 0x16800, v20
	v_mov_b64_e32 v[46:47], v[10:11]
	v_mov_b64_e32 v[22:23], v[10:11]
	v_mov_b64_e32 v[42:43], v[10:11]
	v_mov_b64_e32 v[34:35], v[10:11]
	v_mov_b64_e32 v[26:27], v[10:11]
	v_writelane_b32 v248, s9, 8
	s_lshl_b64 s[88:89], s[0:1], 9
	s_mov_b32 s3, 0x41400000
	s_mov_b32 s8, 0
	v_mov_b64_e32 v[44:45], v[8:9]
	v_mov_b64_e32 v[20:21], v[8:9]
	v_mov_b64_e32 v[40:41], v[8:9]
	v_mov_b64_e32 v[32:33], v[8:9]
	v_mov_b64_e32 v[24:25], v[8:9]
	v_mov_b32_e32 v213, 0x7f800000
	v_cmp_lt_f32_e32 vcc, 0x43000000, v125
	v_cndmask_b32_e32 v125, v125, v213, vcc
	v_cmp_lt_f32_e32 vcc, 0x43000000, v126
	v_cndmask_b32_e32 v126, v126, v213, vcc
	v_cmp_lt_f32_e32 vcc, 0x43000000, v127
	v_cndmask_b32_e32 v127, v127, v213, vcc
	v_cmp_lt_f32_e32 vcc, 0x43000000, v128
	v_cndmask_b32_e32 v128, v128, v213, vcc
	v_cmp_lt_f32_e32 vcc, 0x43000000, v129
	v_cndmask_b32_e32 v129, v129, v213, vcc
	v_cmp_lt_f32_e32 vcc, 0x43000000, v130
	v_cndmask_b32_e32 v130, v130, v213, vcc
	v_cmp_lt_f32_e32 vcc, 0x43000000, v131
	v_cndmask_b32_e32 v131, v131, v213, vcc
	v_cmp_lt_f32_e32 vcc, 0x43000000, v132
	v_cndmask_b32_e32 v132, v132, v213, vcc
	v_cmp_lt_f32_e32 vcc, 0x43000000, v133
	v_cndmask_b32_e32 v133, v133, v213, vcc
	v_cmp_lt_f32_e32 vcc, 0x43000000, v134
	v_cndmask_b32_e32 v134, v134, v213, vcc
	v_cmp_lt_f32_e32 vcc, 0x43000000, v135
	v_cndmask_b32_e32 v135, v135, v213, vcc
	v_cmp_lt_f32_e32 vcc, 0x43000000, v136
	v_cndmask_b32_e32 v136, v136, v213, vcc
	v_cmp_lt_f32_e32 vcc, 0x43000000, v137
	v_cndmask_b32_e32 v137, v137, v213, vcc
	v_cmp_lt_f32_e32 vcc, 0x43000000, v138
	v_cndmask_b32_e32 v138, v138, v213, vcc
	v_cmp_lt_f32_e32 vcc, 0x43000000, v139
	v_cndmask_b32_e32 v139, v139, v213, vcc
	v_cmp_lt_f32_e32 vcc, 0x43000000, v140
	v_cndmask_b32_e32 v140, v140, v213, vcc
	v_cmp_lt_f32_e32 vcc, 0x43000000, v141
	v_cndmask_b32_e32 v141, v141, v213, vcc
	v_cmp_lt_f32_e32 vcc, 0x43000000, v142
	v_cndmask_b32_e32 v142, v142, v213, vcc
	v_cmp_lt_f32_e32 vcc, 0x43000000, v143
	v_cndmask_b32_e32 v143, v143, v213, vcc
	v_cmp_lt_f32_e32 vcc, 0x43000000, v145
	v_cndmask_b32_e32 v145, v145, v213, vcc
	v_cmp_lt_f32_e32 vcc, 0x43000000, v146
	v_cndmask_b32_e32 v146, v146, v213, vcc
	v_cmp_lt_f32_e32 vcc, 0x43000000, v147
	v_cndmask_b32_e32 v147, v147, v213, vcc
	v_cmp_lt_f32_e32 vcc, 0x43000000, v148
	v_cndmask_b32_e32 v148, v148, v213, vcc
	v_cmp_lt_f32_e32 vcc, 0x43000000, v149
	v_cndmask_b32_e32 v149, v149, v213, vcc
	v_cmp_lt_f32_e32 vcc, 0x43000000, v150
	v_cndmask_b32_e32 v150, v150, v213, vcc
	v_cmp_lt_f32_e32 vcc, 0x43000000, v151
	v_cndmask_b32_e32 v151, v151, v213, vcc
	v_cmp_lt_f32_e32 vcc, 0x43000000, v152
	v_cndmask_b32_e32 v152, v152, v213, vcc
	v_cmp_lt_f32_e32 vcc, 0x43000000, v153
	v_cndmask_b32_e32 v153, v153, v213, vcc
	v_cmp_lt_f32_e32 vcc, 0x43000000, v154
	v_cndmask_b32_e32 v154, v154, v213, vcc
	v_cmp_lt_f32_e32 vcc, 0x43000000, v155
	v_cndmask_b32_e32 v155, v155, v213, vcc
	v_cmp_lt_f32_e32 vcc, 0x43000000, v156
	v_cndmask_b32_e32 v156, v156, v213, vcc
	v_cmp_lt_f32_e32 vcc, 0x43000000, v157
	v_cndmask_b32_e32 v157, v157, v213, vcc
	v_cmp_lt_f32_e32 vcc, 0x43000000, v158
	v_cndmask_b32_e32 v158, v158, v213, vcc
	v_cmp_lt_f32_e32 vcc, 0x43000000, v159
	v_cndmask_b32_e32 v159, v159, v213, vcc
	v_cmp_lt_f32_e32 vcc, 0x43000000, v160
	v_cndmask_b32_e32 v160, v160, v213, vcc
	v_cmp_lt_f32_e32 vcc, 0x43000000, v161
	v_cndmask_b32_e32 v161, v161, v213, vcc
	v_cmp_lt_f32_e32 vcc, 0x43000000, v162
	v_cndmask_b32_e32 v162, v162, v213, vcc
	v_cmp_lt_f32_e32 vcc, 0x43000000, v163
	v_cndmask_b32_e32 v163, v163, v213, vcc
	v_cmp_lt_f32_e32 vcc, 0x43000000, v164
	v_cndmask_b32_e32 v164, v164, v213, vcc
	v_cmp_lt_f32_e32 vcc, 0x43000000, v165
	v_cndmask_b32_e32 v165, v165, v213, vcc
	v_and_b32_e32 v244, 63, v170
	v_bfe_u32 v245, v244, 1, 3
	v_and_b32_e32 v243, 1, v244
	v_lshrrev_b32_e32 v244, 4, v244
	v_and_b32_e32 v242, 3, v245
	v_lshrrev_b32_e32 v245, 2, v245
	v_lshl_add_u32 v242, v244, 2, v242
	v_lshl_add_u32 v242, v245, 4, v242
	v_lshrrev_b32_e32 v244, 2, v170
	v_and_b32_e32 v244, 0x60, v244
	v_add_u32_e32 v242, v242, v244
	v_mul_u32_u24_e32 v242, 0x50, v242
	v_lshl_add_u32 v246, v243, 3, v242
	v_add_u32_e32 v246, 0x5000, v246
	v_and_b32_e32 v244, 0xff, v170
	v_mul_u32_u24_e32 v244, 0x50, v244
	v_lshrrev_b32_e32 v245, 8, v170
	v_lshl_add_u32 v247, v245, 4, v244
	s_mov_b32 s9, 0
	s_branch .LBB0_271

; #define LAS __attribute__((address_space(3)))
; __device__ __forceinline__ void attn_phase(const Params& p, LAS unsigned char* lds, int tid, int G, int bid) {
;     ...
;         const AttnUnitGeo u = attn_geo(uid);
;     ...
; #pragma unroll
;         for (int i = 0; i < 2; ++i) { const int c = tid + NTHREADS * i, row = c >> 2, part = c & 3; *(LAS u32x4*)(lds + row * KS_PITCH + part * 16) = kr[i]; }
; #pragma unroll
;         for (int i = 0; i < 2; ++i) { const int c = tid + NTHREADS * i, part = c >> 8, row = c & 255; const u32x4 v = vr[i];
;             LAS unsigned char* vt = lds + VT_OFF + (part * 16) * VT_PITCH + row;
; #pragma unroll
;             for (int e = 0; e < 16; ++e) vt[e * VT_PITCH] = (unsigned char)((v[e >> 2] >> (8 * (e & 3))) & 0xffu); }
;         const long q0 = nq0, q1 = nq1;
;         const int qi = 16 * w + fr, tq = ((nb * 128 + qi) << dsh) + r;
;         __syncthreads();
;         if (uid + G < 3072) { const AttnUnitGeo un = attn_geo(uid + G); attn_load(QKV, un, tid, w, fr, quad, kr, vr, nq0, nq1); }
.LBB0_271:
	ds_write_b128 v93, v[4:7]
	ds_write_b128 v166, v[0:3]
	ds_write_b128 v247, v[16:19] offset:20480
	ds_write_b128 v247, v[12:15] offset:20512
	s_add_i32 s10, s11, s98
	s_cmpk_gt_i32 s10, 0xbff
	s_cselect_b64 s[82:83], -1, 0
	s_and_b64 vcc, exec, s[82:83]
	s_waitcnt lgkmcnt(0)
	s_barrier
	s_cbranch_vccnz .LBB0_279
	s_mul_hi_i32 s0, s10, 0x2aaaaaab
	s_lshr_b32 s1, s0, 31
	s_ashr_i32 s0, s0, 5
	s_add_i32 s0, s0, s1
	s_mul_i32 s1, s0, 0xffffff40
	s_add_i32 s1, s10, s1
	s_ashr_i32 s1, s1, 6
	s_bfe_u32 s4, s10, 0x20004
	s_mul_i32 s0, s0, 12
	s_lshl_b32 s6, s1, 1
	s_lshl_b32 s1, s1, 2
	s_or_b32 s0, s0, s4
	s_add_i32 s0, s0, s1
	s_and_b32 s5, s10, 15
	s_ashr_i32 s1, s0, 31
	s_lshr_b32 s7, s5, s6
	s_lshl_b64 s[0:1], s[0:1], 17
	v_readlane_b32 s12, v250, 18
	v_readlane_b32 s13, v250, 19
	s_add_u32 s0, s12, s0
	s_addc_u32 s1, s13, s1
	s_sub_i32 s4, 11, s6
	s_lshl_b32 s4, s5, s4
	s_and_b32 s84, s4, 0x7fe
	s_lshl_b32 s4, s7, 7
	s_add_i32 s84, s84, s4
	s_add_i32 s85, s84, 0xffffff80
	v_lshl_add_u64 v[0:1], s[0:1], 0, v[84:85]
	s_mov_b64 s[4:5], 0x1800000
	s_cmp_lg_u32 s7, 0
	v_readlane_b32 s6, v250, 26
	v_mov_b32_e32 v2, v8
	v_mov_b32_e32 v3, v8
	v_lshl_add_u64 v[10:11], v[0:1], 0, s[4:5]
	s_cselect_b64 s[4:5], -1, 0
	v_readlane_b32 s7, v250, 27
	v_mov_b32_e32 v0, 0
	v_mov_b32_e32 v1, v8
	v_mov_b64_e32 v[6:7], v[2:3]
	s_or_b64 vcc, s[6:7], s[4:5]
	v_mov_b64_e32 v[4:5], v[0:1]
	s_and_saveexec_b64 s[6:7], vcc
	s_cbranch_execz .LBB0_274
	v_add_u32_e32 v4, s85, v120
	v_ashrrev_i32_e32 v5, 31, v4
	v_lshlrev_b64 v[4:5], 6, v[4:5]
	v_lshl_add_u64 v[4:5], v[10:11], 0, v[4:5]
	global_load_dwordx4 v[4:7], v[4:5], off

; #define LAS __attribute__((address_space(3)))
; __device__ __forceinline__ void attn_phase(const Params& p, LAS unsigned char* lds, int tid, int G, int bid) {
;     ...
; #pragma unroll
;         for (int tt = 0; tt < 10; ++tt) { const LAS unsigned char* kp = lds + (16 * (tstart + tt) + fr) * KS_PITCH + quad * 8;
;             const long k0 = *(const LAS long*)kp, k1 = *(const LAS long*)(kp + 32);
;             f32x4 a = {0.f, 0.f, 0.f, 0.f};
;             a = __builtin_amdgcn_mfma_f32_16x16x32_fp8_fp8(k0, q0, a, 0, 0, 0);
;             s[tt] = __builtin_amdgcn_mfma_f32_16x16x32_fp8_fp8(k1, q1, a, 0, 0, 0) * C2; }
;         const float sl2 = __builtin_amdgcn_exp2f(-8.0f * (float)(head + 1) / 12.0f) * (float)d * LOG2E;
;         float mx = -INFINITY;
; #pragma unroll
;         for (int tt = 0; tt < 10; ++tt)
; #pragma unroll
;             for (int j = 0; j < 4; ++j) { const int kj = 16 * (tstart + tt) + 4 * quad + j, delta = qi + 128 - kj;
;                 const bool valid = (delta >= 0) && (delta <= 128) && (nb > 0 || kj >= 128);
;                 const float v = valid ? s[tt][j] - sl2 * (float)delta : -INFINITY; s[tt][j] = v; mx = fmaxf(mx, v); }
.LBB0_284:
	ds_read2_b64 v[214:217], v169 offset1:4
	ds_read2_b64 v[218:221], v171 offset1:4
	ds_read2_b64 v[222:225], v172 offset1:4
	ds_read2_b64 v[226:229], v173 offset1:4
	ds_read2_b64 v[230:233], v174 offset1:4
	ds_read2_b64 v[234:237], v175 offset1:4
	ds_read2_b64 v[238:241], v176 offset1:4
	ds_read2_b64 v[242:245], v177 offset1:4
	ds_read2_b64 v[186:189], v178 offset1:4
	ds_read2_b64 v[252:255], v179 offset1:4
	s_mul_hi_i32 s0, s11, 0x2aaaaaab
	s_lshr_b32 s1, s0, 31
	s_ashr_i32 s0, s0, 5
	s_add_i32 s0, s0, s1
	s_mul_i32 s1, s0, 0xffffff40
	s_add_i32 s1, s11, s1
	s_ashr_i32 s4, s1, 6
	s_and_b32 s6, s11, 15
	s_lshl_b32 s7, s4, 2
	s_bfe_u32 s11, s11, 0x20004
	s_or_b32 s7, s11, s7
	s_add_i32 s7, s7, 1
	v_cvt_f32_i32_e32 v9, s7
	s_lshl_b32 s1, s4, 1
	s_lshl_b32 s5, -1, s1
	s_andn2_b32 s5, s6, s5
	v_mul_f32_e32 v9, 0xc1000000, v9
	s_lshr_b32 s86, s6, s1
	s_lshl_b32 s6, 1, s1
	s_cmp_lg_u32 s86, 0
	s_waitcnt lgkmcnt(9)
	v_mfma_f32_16x16x32_fp8_fp8 v[68:71], v[214:215], v[62:63], 0
	v_mfma_f32_16x16x32_fp8_fp8 v[214:217], v[216:217], v[60:61], v[68:71]
	s_waitcnt lgkmcnt(8)
	v_mfma_f32_16x16x32_fp8_fp8 v[190:193], v[218:219], v[62:63], 0
	v_mfma_f32_16x16x32_fp8_fp8 v[218:221], v[220:221], v[60:61], v[190:193]
	s_waitcnt lgkmcnt(7)
	v_mfma_f32_16x16x32_fp8_fp8 v[68:71], v[222:223], v[62:63], 0
	v_mfma_f32_16x16x32_fp8_fp8 v[222:225], v[224:225], v[60:61], v[68:71]
	s_waitcnt lgkmcnt(6)
	v_mfma_f32_16x16x32_fp8_fp8 v[190:193], v[226:227], v[62:63], 0
	v_mfma_f32_16x16x32_fp8_fp8 v[226:229], v[228:229], v[60:61], v[190:193]
	s_waitcnt lgkmcnt(5)
	v_mfma_f32_16x16x32_fp8_fp8 v[68:71], v[230:231], v[62:63], 0
	v_mfma_f32_16x16x32_fp8_fp8 v[230:233], v[232:233], v[60:61], v[68:71]
	s_waitcnt lgkmcnt(4)
	v_mfma_f32_16x16x32_fp8_fp8 v[190:193], v[234:235], v[62:63], 0
	v_mfma_f32_16x16x32_fp8_fp8 v[234:237], v[236:237], v[60:61], v[190:193]
	s_waitcnt lgkmcnt(3)
	v_mfma_f32_16x16x32_fp8_fp8 v[68:71], v[238:239], v[62:63], 0
	v_mfma_f32_16x16x32_fp8_fp8 v[238:241], v[240:241], v[60:61], v[68:71]
	s_waitcnt lgkmcnt(2)
	v_mfma_f32_16x16x32_fp8_fp8 v[190:193], v[242:243], v[62:63], 0
	v_mfma_f32_16x16x32_fp8_fp8 v[242:245], v[244:245], v[60:61], v[190:193]
	s_waitcnt lgkmcnt(1)
	v_mfma_f32_16x16x32_fp8_fp8 v[68:71], v[186:187], v[62:63], 0
	v_mfma_f32_16x16x32_fp8_fp8 v[186:189], v[188:189], v[60:61], v[68:71]
	s_waitcnt lgkmcnt(0)
	v_mfma_f32_16x16x32_fp8_fp8 v[190:193], v[252:253], v[62:63], 0
	v_mfma_f32_16x16x32_fp8_fp8 v[252:255], v[254:255], v[60:61], v[190:193]
	s_nop 7
	v_pk_mul_f32 v[116:117], v[216:217], s[80:81] op_sel_hi:[1,0]
	v_pk_mul_f32 v[118:119], v[214:215], s[80:81] op_sel_hi:[1,0]
	v_pk_mul_f32 v[112:113], v[220:221], s[80:81] op_sel_hi:[1,0]
	v_pk_mul_f32 v[114:115], v[218:219], s[80:81] op_sel_hi:[1,0]
	v_pk_mul_f32 v[108:109], v[224:225], s[80:81] op_sel_hi:[1,0]
	v_pk_mul_f32 v[110:111], v[222:223], s[80:81] op_sel_hi:[1,0]
	v_pk_mul_f32 v[104:105], v[228:229], s[80:81] op_sel_hi:[1,0]
	v_pk_mul_f32 v[106:107], v[226:227], s[80:81] op_sel_hi:[1,0]
	v_pk_mul_f32 v[80:81], v[232:233], s[80:81] op_sel_hi:[1,0]
	v_pk_mul_f32 v[82:83], v[230:231], s[80:81] op_sel_hi:[1,0]
	v_pk_mul_f32 v[76:77], v[236:237], s[80:81] op_sel_hi:[1,0]
	v_pk_mul_f32 v[78:79], v[234:235], s[80:81] op_sel_hi:[1,0]
	v_pk_mul_f32 v[72:73], v[240:241], s[80:81] op_sel_hi:[1,0]
	v_pk_mul_f32 v[74:75], v[238:239], s[80:81] op_sel_hi:[1,0]
	v_pk_mul_f32 v[68:69], v[244:245], s[80:81] op_sel_hi:[1,0]
	v_pk_mul_f32 v[70:71], v[242:243], s[80:81] op_sel_hi:[1,0]
	v_pk_mul_f32 v[64:65], v[188:189], s[80:81] op_sel_hi:[1,0]
	v_pk_mul_f32 v[66:67], v[186:187], s[80:81] op_sel_hi:[1,0]
	v_pk_mul_f32 v[10:11], v[254:255], s[80:81] op_sel_hi:[1,0]
	v_div_scale_f32 v62, vcc, s3, s3, v9
	v_rcp_f32_e32 v63, v62
	v_pk_mul_f32 v[60:61], v[252:253], s[80:81] op_sel_hi:[1,0]
	v_fma_f32 v186, -v62, v63, 1.0
	v_fmac_f32_e32 v63, v186, v63
	v_div_scale_f32 v186, vcc, v9, s3, v9
	v_mul_f32_e32 v187, v186, v63
	v_fma_f32 v188, -v62, v187, v186
	v_fmac_f32_e32 v187, v188, v63
	v_fma_f32 v62, -v62, v187, v186
	v_div_fmas_f32 v62, v62, v63, v187
	v_div_fixup_f32 v9, v62, s3, v9
	v_exp_f32_e32 v9, v9
	v_cvt_f32_u32_e32 v62, s6
	s_cselect_b64 s[6:7], -1, 0
	v_mul_f32_e32 v9, v9, v62
	v_mul_f32_e32 v9, 0xbfb8aa3b, v9
	v_fma_f32 v62, v9, v125, v118
	v_fma_f32 v63, v9, v126, v119
	v_fmac_f32_e32 v116, v9, v127
	v_fmac_f32_e32 v117, v9, v128
	v_fmac_f32_e32 v114, v9, v129
	v_fmac_f32_e32 v115, v9, v130
	v_fmac_f32_e32 v112, v9, v131
	v_fmac_f32_e32 v113, v9, v132
	v_fmac_f32_e32 v110, v9, v133
	v_fmac_f32_e32 v111, v9, v134
	v_fmac_f32_e32 v108, v9, v135
	v_fmac_f32_e32 v109, v9, v136
	v_fmac_f32_e32 v106, v9, v137
	v_fmac_f32_e32 v107, v9, v138
	v_fmac_f32_e32 v104, v9, v139
	v_fmac_f32_e32 v105, v9, v140
	v_fmac_f32_e32 v82, v9, v141
	v_fmac_f32_e32 v83, v9, v142
	v_fmac_f32_e32 v80, v9, v143
	v_fmac_f32_e32 v81, v9, v145
	v_fmac_f32_e32 v78, v9, v146
	v_fmac_f32_e32 v79, v9, v147
	v_fmac_f32_e32 v76, v9, v148
	v_fmac_f32_e32 v77, v9, v149
	v_fmac_f32_e32 v74, v9, v150
	v_fmac_f32_e32 v75, v9, v151
	v_fmac_f32_e32 v72, v9, v152
	v_fmac_f32_e32 v73, v9, v153
	v_fmac_f32_e32 v70, v9, v154
	v_fmac_f32_e32 v71, v9, v155
	v_fmac_f32_e32 v68, v9, v156
	v_fmac_f32_e32 v69, v9, v157
	v_fmac_f32_e32 v66, v9, v158
	v_fmac_f32_e32 v67, v9, v159
	v_fmac_f32_e32 v64, v9, v160
	v_fmac_f32_e32 v65, v9, v161
	v_fmac_f32_e32 v60, v9, v162
	v_fmac_f32_e32 v61, v9, v163
	v_fmac_f32_e32 v10, v9, v164
	v_fmac_f32_e32 v11, v9, v165
	s_cmp_lg_u32 s6, 0
	s_cbranch_scc1 .Lattn_nb_ok
	v_readfirstlane_b32 s100, v170
	s_lshr_b32 s100, s100, 6
	s_and_b32 s100, s100, 6
	s_sub_i32 s100, 8, s100
	v_mov_b32_e32 v62, v184
	v_mov_b32_e32 v63, v184
	v_mov_b32_e32 v116, v184
	v_mov_b32_e32 v117, v184
	v_mov_b32_e32 v114, v184
	v_mov_b32_e32 v115, v184
	v_mov_b32_e32 v112, v184
	v_mov_b32_e32 v113, v184
	s_cmp_lt_u32 s100, 3
	s_cbranch_scc1 .Lattn_nb_ok
	v_mov_b32_e32 v110, v184
	v_mov_b32_e32 v111, v184
	v_mov_b32_e32 v108, v184
	v_mov_b32_e32 v109, v184
	v_mov_b32_e32 v106, v184
	v_mov_b32_e32 v107, v184
	v_mov_b32_e32 v104, v184
	v_mov_b32_e32 v105, v184
	s_cmp_lt_u32 s100, 5
	s_cbranch_scc1 .Lattn_nb_ok
	v_mov_b32_e32 v82, v184
	v_mov_b32_e32 v83, v184
	v_mov_b32_e32 v80, v184
	v_mov_b32_e32 v81, v184
	v_mov_b32_e32 v78, v184
	v_mov_b32_e32 v79, v184
	v_mov_b32_e32 v76, v184
	v_mov_b32_e32 v77, v184
	s_cmp_lt_u32 s100, 7
	s_cbranch_scc1 .Lattn_nb_ok
	v_mov_b32_e32 v74, v184
	v_mov_b32_e32 v75, v184
	v_mov_b32_e32 v72, v184
	v_mov_b32_e32 v73, v184
	v_mov_b32_e32 v70, v184
	v_mov_b32_e32 v71, v184
	v_mov_b32_e32 v68, v184
	v_mov_b32_e32 v69, v184
; #define LAS __attribute__((address_space(3)))
; __device__ __forceinline__ void attn_phase(const Params& p, LAS unsigned char* lds, int tid, int G, int bid) {
;     ...
;         float mx = -INFINITY;
; #pragma unroll
;         for (int tt = 0; tt < 10; ++tt)
; #pragma unroll
;             for (int j = 0; j < 4; ++j) { const int kj = 16 * (tstart + tt) + 4 * quad + j, delta = qi + 128 - kj;
;                 const bool valid = (delta >= 0) && (delta <= 128) && (nb > 0 || kj >= 128);
;                 const float v = valid ? s[tt][j] - sl2 * (float)delta : -INFINITY; s[tt][j] = v; mx = fmaxf(mx, v); }
;         mx = fmaxf(mx, __shfl_xor(mx, 16)); mx = fmaxf(mx, __shfl_xor(mx, 32));
;         float den = 0.f;
; #pragma unroll
;         for (int tt = 0; tt < 10; ++tt)
; #pragma unroll
;             for (int j = 0; j < 4; ++j) { const float e = __builtin_amdgcn_exp2f(s[tt][j] - mx); s[tt][j] = e; den += e; }
;         den += __shfl_xor(den, 16); den += __shfl_xor(den, 32);
;         f32x4 o[4];
; #pragma unroll
;         for (int dt = 0; dt < 4; ++dt) o[dt] = (f32x4){0.f, 0.f, 0.f, 0.f};
; #pragma unroll
;         for (int c = 0; c < 5; ++c) {
;             int p0_ = 0, p1_ = 0;
;             p0_ = __builtin_amdgcn_cvt_pk_fp8_f32(s[2 * c][0], s[2 * c][1], p0_, false); p0_ = __builtin_amdgcn_cvt_pk_fp8_f32(s[2 * c][2], s[2 * c][3], p0_, true);
;             p1_ = __builtin_amdgcn_cvt_pk_fp8_f32(s[2 * c + 1][0], s[2 * c + 1][1], p1_, false); p1_ = __builtin_amdgcn_cvt_pk_fp8_f32(s[2 * c + 1][2], s[2 * c + 1][3], p1_, true);
;             const long pf = (long)(((unsigned long long)(unsigned)p1_ << 32) | (unsigned long long)(unsigned)p0_);
; #pragma unroll
;             for (int dt = 0; dt < 4; ++dt) { const LAS unsigned char* vp = lds + VT_OFF + (16 * dt + fr) * VT_PITCH + 16 * (tstart + 2 * c) + 4 * quad;
;                 const unsigned lo = *(const LAS unsigned*)vp, hi = *(const LAS unsigned*)(vp + 16);
;                 const long vf = (long)(((unsigned long long)hi << 32) | (unsigned long long)lo);
;                 o[dt] = __builtin_amdgcn_mfma_f32_16x16x32_fp8_fp8(vf, pf, o[dt], 0, 0, 0); }
;         }
.Lattn_nb_ok:
	s_mov_b32 s12, 0xff800000
	v_max3_f32 v118, v62, s12, v63
	v_max3_f32 v118, v118, v116, v117
	v_max3_f32 v118, v118, v114, v115
	v_max3_f32 v118, v118, v112, v113
	v_max3_f32 v118, v118, v110, v111
	v_max3_f32 v118, v118, v108, v109
	v_max3_f32 v118, v118, v106, v107
	v_max3_f32 v118, v118, v104, v105
	v_max3_f32 v118, v118, v82, v83
	v_max3_f32 v118, v118, v80, v81
	v_max3_f32 v118, v118, v78, v79
	v_max3_f32 v118, v118, v76, v77
	v_max3_f32 v118, v118, v74, v75
	v_max3_f32 v118, v118, v72, v73
	v_max3_f32 v118, v118, v70, v71
	v_max3_f32 v118, v118, v68, v69
	v_max3_f32 v118, v118, v66, v67
	v_max3_f32 v118, v118, v64, v65
	v_max3_f32 v118, v118, v60, v61
	v_max3_f32 v9, v118, v10, v11
	ds_bpermute_b32 v118, v122, v9
	s_waitcnt lgkmcnt(0)
	v_max_f32_e32 v118, v118, v118
	v_max_f32_e32 v9, v9, v118
	ds_bpermute_b32 v118, v123, v9
	s_waitcnt lgkmcnt(0)
	v_max_f32_e32 v118, v118, v118
	v_max_f32_e32 v9, v9, v118
	v_sub_f32_e32 v62, v62, v9
	v_exp_f32_e32 v62, v62
	v_sub_f32_e32 v63, v63, v9
	v_exp_f32_e32 v63, v63
	v_sub_f32_e32 v116, v116, v9
	v_exp_f32_e32 v116, v116
	v_sub_f32_e32 v117, v117, v9
	v_exp_f32_e32 v117, v117
	v_sub_f32_e32 v114, v114, v9
	v_add_f32_e32 v118, 0, v62
	v_exp_f32_e32 v114, v114
	v_sub_f32_e32 v115, v115, v9
	v_add_f32_e32 v118, v63, v118
	v_exp_f32_e32 v115, v115
	v_sub_f32_e32 v112, v112, v9
	v_add_f32_e32 v118, v116, v118
	v_exp_f32_e32 v112, v112
	v_sub_f32_e32 v113, v113, v9
	v_add_f32_e32 v118, v117, v118
	v_exp_f32_e32 v113, v113
	v_sub_f32_e32 v110, v110, v9
	v_add_f32_e32 v118, v114, v118
	v_exp_f32_e32 v110, v110
	v_sub_f32_e32 v111, v111, v9
	v_add_f32_e32 v118, v115, v118
	v_exp_f32_e32 v111, v111
	v_sub_f32_e32 v108, v108, v9
	v_add_f32_e32 v118, v112, v118
	v_exp_f32_e32 v108, v108
	v_sub_f32_e32 v109, v109, v9
	v_add_f32_e32 v118, v113, v118
	v_exp_f32_e32 v109, v109
	v_sub_f32_e32 v106, v106, v9
	v_add_f32_e32 v118, v110, v118
	v_exp_f32_e32 v106, v106
	v_sub_f32_e32 v107, v107, v9
	v_add_f32_e32 v118, v111, v118
	v_exp_f32_e32 v107, v107
	v_sub_f32_e32 v104, v104, v9
	v_add_f32_e32 v118, v108, v118
	v_exp_f32_e32 v104, v104
	v_sub_f32_e32 v105, v105, v9
	v_add_f32_e32 v118, v109, v118
	v_exp_f32_e32 v105, v105
	v_sub_f32_e32 v82, v82, v9
	v_add_f32_e32 v118, v106, v118
	v_exp_f32_e32 v82, v82
	v_sub_f32_e32 v83, v83, v9
	v_add_f32_e32 v118, v107, v118
	v_exp_f32_e32 v83, v83
	v_sub_f32_e32 v80, v80, v9
	v_add_f32_e32 v118, v104, v118
	v_exp_f32_e32 v80, v80
	v_sub_f32_e32 v81, v81, v9
	v_add_f32_e32 v118, v105, v118
	v_exp_f32_e32 v81, v81
	v_sub_f32_e32 v78, v78, v9
	v_add_f32_e32 v118, v82, v118
	v_exp_f32_e32 v78, v78
	v_sub_f32_e32 v79, v79, v9
	v_add_f32_e32 v118, v83, v118
	v_exp_f32_e32 v79, v79
	v_sub_f32_e32 v76, v76, v9
	v_add_f32_e32 v118, v80, v118
	v_exp_f32_e32 v119, v76
	v_add_f32_e32 v118, v81, v118
	v_add_f32_e32 v118, v78, v118
	v_add_f32_e32 v118, v79, v118
	v_sub_f32_e32 v77, v77, v9
	v_add_f32_e32 v76, v119, v118
	v_exp_f32_e32 v118, v77
	v_sub_f32_e32 v74, v74, v9
	v_exp_f32_e32 v186, v74
	v_sub_f32_e32 v75, v75, v9
	v_exp_f32_e32 v187, v75
	v_sub_f32_e32 v72, v72, v9
	v_exp_f32_e32 v188, v72
	v_sub_f32_e32 v73, v73, v9
	v_add_f32_e32 v76, v118, v76
	v_exp_f32_e32 v189, v73
	v_sub_f32_e32 v70, v70, v9
	v_add_f32_e32 v74, v186, v76
	v_exp_f32_e32 v190, v70
	v_sub_f32_e32 v71, v71, v9
	v_add_f32_e32 v74, v187, v74
	v_exp_f32_e32 v191, v71
	v_sub_f32_e32 v68, v68, v9
	v_add_f32_e32 v72, v188, v74
	v_exp_f32_e32 v192, v68
	v_sub_f32_e32 v69, v69, v9
	v_add_f32_e32 v72, v189, v72
	v_exp_f32_e32 v193, v69
	v_sub_f32_e32 v66, v66, v9
	v_add_f32_e32 v70, v190, v72
	v_exp_f32_e32 v194, v66
	v_sub_f32_e32 v67, v67, v9
	v_add_f32_e32 v70, v191, v70
	v_exp_f32_e32 v195, v67
	v_sub_f32_e32 v64, v64, v9
	v_add_f32_e32 v68, v192, v70
	v_exp_f32_e32 v196, v64
	v_sub_f32_e32 v65, v65, v9
	v_add_f32_e32 v68, v193, v68
	v_exp_f32_e32 v197, v65
	v_sub_f32_e32 v60, v60, v9
	v_add_f32_e32 v66, v194, v68
	v_exp_f32_e32 v198, v60
	v_sub_f32_e32 v61, v61, v9
	v_add_f32_e32 v66, v195, v66
	v_exp_f32_e32 v199, v61
	v_sub_f32_e32 v10, v10, v9
	v_add_f32_e32 v64, v196, v66
	v_exp_f32_e32 v200, v10
	v_sub_f32_e32 v11, v11, v9
	v_add_f32_e32 v64, v197, v64
	v_exp_f32_e32 v201, v11
	v_add_f32_e32 v60, v198, v64
	v_add_f32_e32 v60, v199, v60
	v_add_f32_e32 v10, v200, v60
	v_add_f32_e32 v10, v201, v10
	ds_bpermute_b32 v11, v122, v10
	s_waitcnt lgkmcnt(0)
	v_add_f32_e32 v202, v10, v11
	v_cvt_pk_fp8_f32 v11, v114, v115
	v_cvt_pk_fp8_f32 v11, v112, v113 op_sel:[0,0,1]
	ds_read_b64_tr_b8 v[60:61], v246 offset:0
	ds_read_b64_tr_b8 v[64:65], v246 offset:16
	ds_read_b64_tr_b8 v[68:69], v246 offset:32
	ds_read_b64_tr_b8 v[72:73], v246 offset:48
	ds_read_b64_tr_b8 v[214:215], v246 offset:2560
	ds_read_b64_tr_b8 v[216:217], v246 offset:2576
	ds_read_b64_tr_b8 v[218:219], v246 offset:2592
	ds_read_b64_tr_b8 v[220:221], v246 offset:2608
	ds_read_b64_tr_b8 v[222:223], v246 offset:5120
	ds_read_b64_tr_b8 v[224:225], v246 offset:5136
	ds_read_b64_tr_b8 v[226:227], v246 offset:5152
	ds_read_b64_tr_b8 v[228:229], v246 offset:5168
	v_cvt_pk_fp8_f32 v10, v62, v63
	ds_bpermute_b32 v203, v123, v202
	v_cvt_pk_fp8_f32 v10, v116, v117 op_sel:[0,0,1]
	s_waitcnt lgkmcnt(9)
	s_nop 0
	v_mfma_f32_16x16x32_fp8_fp8 v[60:63], v[60:61], v[10:11], 0
	v_mfma_f32_16x16x32_fp8_fp8 v[64:67], v[64:65], v[10:11], 0
	v_mfma_f32_16x16x32_fp8_fp8 v[68:71], v[68:69], v[10:11], 0
	v_mfma_f32_16x16x32_fp8_fp8 v[72:75], v[72:73], v[10:11], 0
	ds_read_b64_tr_b8 v[230:231], v246 offset:7680
	ds_read_b64_tr_b8 v[232:233], v246 offset:7696
	ds_read_b64_tr_b8 v[234:235], v246 offset:7712
	ds_read_b64_tr_b8 v[236:237], v246 offset:7728
	v_cvt_pk_fp8_f32 v10, v110, v111
	v_cvt_pk_fp8_f32 v11, v106, v107
	v_cvt_pk_fp8_f32 v10, v108, v109 op_sel:[0,0,1]
	v_cvt_pk_fp8_f32 v11, v104, v105 op_sel:[0,0,1]
	s_waitcnt lgkmcnt(9)
; #define LAS __attribute__((address_space(3)))
; __device__ __forceinline__ float f8c(float v) { return fminf(fmaxf(v, -448.f), 448.f); }
; __device__ __forceinline__ void attn_phase(const Params& p, LAS unsigned char* lds, int tid, int G, int bid) {
;     ...
;         den += __shfl_xor(den, 16); den += __shfl_xor(den, 32);
;         f32x4 o[4];
; #pragma unroll
;         for (int dt = 0; dt < 4; ++dt) o[dt] = (f32x4){0.f, 0.f, 0.f, 0.f};
; #pragma unroll
;         for (int c = 0; c < 5; ++c) {
;             int p0_ = 0, p1_ = 0;
;             p0_ = __builtin_amdgcn_cvt_pk_fp8_f32(s[2 * c][0], s[2 * c][1], p0_, false); p0_ = __builtin_amdgcn_cvt_pk_fp8_f32(s[2 * c][2], s[2 * c][3], p0_, true);
;             p1_ = __builtin_amdgcn_cvt_pk_fp8_f32(s[2 * c + 1][0], s[2 * c + 1][1], p1_, false); p1_ = __builtin_amdgcn_cvt_pk_fp8_f32(s[2 * c + 1][2], s[2 * c + 1][3], p1_, true);
;             const long pf = (long)(((unsigned long long)(unsigned)p1_ << 32) | (unsigned long long)(unsigned)p0_);
; #pragma unroll
;             for (int dt = 0; dt < 4; ++dt) { const LAS unsigned char* vp = lds + VT_OFF + (16 * dt + fr) * VT_PITCH + 16 * (tstart + 2 * c) + 4 * quad;
;                 const unsigned lo = *(const LAS unsigned*)vp, hi = *(const LAS unsigned*)(vp + 16);
;                 const long vf = (long)(((unsigned long long)hi << 32) | (unsigned long long)lo);
;                 o[dt] = __builtin_amdgcn_mfma_f32_16x16x32_fp8_fp8(vf, pf, o[dt], 0, 0, 0); }
;         }
;         const float inv = 1.0f / den;
;         { LAS unsigned char* ost = lds + OST_OFF + w * 2304;
; #pragma unroll
;           for (int dt = 0; dt < 4; ++dt) { int wv = 0; wv = __builtin_amdgcn_cvt_pk_fp8_f32(f8c(o[dt][0] * inv), f8c(o[dt][1] * inv), wv, false); wv = __builtin_amdgcn_cvt_pk_fp8_f32(f8c(o[dt][2] * inv), f8c(o[dt][3] * inv), wv, true);
;               *(LAS unsigned*)(ost + fr * 80 + 16 * dt + 4 * quad) = (unsigned)wv; }
;           LDS_WAIT();
;           const int q2 = lane >> 2, ck = lane & 3, tq2 = ((nb * 128 + 16 * w + q2) << dsh) + r;
;           const u32x4 r0 = *(const LAS u32x4*)(ost + q2 * 80 + ck * 16);
;           unsigned char* op = (unsigned char*)OG + ((size_t)g * M + (size_t)b * SEQ + tq2) * AOW + hh * 64 + ck * 16;
;           *(u32x4*)op = r0; }
;         if (quad == 0) LSE[(size_t)uid * 128 + qi] = (mx + __builtin_amdgcn_logf(den)) * LN2F;
	s_nop 0
	v_mfma_f32_16x16x32_fp8_fp8 v[60:63], v[214:215], v[10:11], v[60:63]
	v_mfma_f32_16x16x32_fp8_fp8 v[64:67], v[216:217], v[10:11], v[64:67]
	v_mfma_f32_16x16x32_fp8_fp8 v[68:71], v[218:219], v[10:11], v[68:71]
	v_mfma_f32_16x16x32_fp8_fp8 v[72:75], v[220:221], v[10:11], v[72:75]
	ds_read_b64_tr_b8 v[238:239], v246 offset:10240
	ds_read_b64_tr_b8 v[240:241], v246 offset:10256
	ds_read_b64_tr_b8 v[242:243], v246 offset:10272
	ds_read_b64_tr_b8 v[244:245], v246 offset:10288
	v_cvt_pk_fp8_f32 v10, v82, v83
	v_cvt_pk_fp8_f32 v11, v78, v79
	v_cvt_pk_fp8_f32 v10, v80, v81 op_sel:[0,0,1]
	v_cvt_pk_fp8_f32 v11, v119, v118 op_sel:[0,0,1]
	s_waitcnt lgkmcnt(9)
	s_nop 0
	v_mfma_f32_16x16x32_fp8_fp8 v[60:63], v[222:223], v[10:11], v[60:63]
	v_mfma_f32_16x16x32_fp8_fp8 v[64:67], v[224:225], v[10:11], v[64:67]
	v_mfma_f32_16x16x32_fp8_fp8 v[68:71], v[226:227], v[10:11], v[68:71]
	v_mfma_f32_16x16x32_fp8_fp8 v[72:75], v[228:229], v[10:11], v[72:75]
	v_cvt_pk_fp8_f32 v10, v186, v187
	v_cvt_pk_fp8_f32 v11, v190, v191
	v_cvt_pk_fp8_f32 v10, v188, v189 op_sel:[0,0,1]
	v_cvt_pk_fp8_f32 v11, v192, v193 op_sel:[0,0,1]
	s_waitcnt lgkmcnt(4)
	s_nop 0
	v_mfma_f32_16x16x32_fp8_fp8 v[60:63], v[230:231], v[10:11], v[60:63]
	v_mfma_f32_16x16x32_fp8_fp8 v[64:67], v[232:233], v[10:11], v[64:67]
	v_mfma_f32_16x16x32_fp8_fp8 v[68:71], v[234:235], v[10:11], v[68:71]
	v_mfma_f32_16x16x32_fp8_fp8 v[72:75], v[236:237], v[10:11], v[72:75]
	v_cvt_pk_fp8_f32 v10, v194, v195
	v_cvt_pk_fp8_f32 v11, v198, v199
	v_cvt_pk_fp8_f32 v10, v196, v197 op_sel:[0,0,1]
	v_cvt_pk_fp8_f32 v11, v200, v201 op_sel:[0,0,1]
	s_waitcnt lgkmcnt(0)
	s_nop 0
	v_mfma_f32_16x16x32_fp8_fp8 v[60:63], v[238:239], v[10:11], v[60:63]
	v_mfma_f32_16x16x32_fp8_fp8 v[76:79], v[240:241], v[10:11], v[64:67]
	v_mfma_f32_16x16x32_fp8_fp8 v[214:217], v[242:243], v[10:11], v[68:71]
	v_mfma_f32_16x16x32_fp8_fp8 v[218:221], v[244:245], v[10:11], v[72:75]
	v_add_f32_e32 v64, v202, v203
	v_div_scale_f32 v10, s[6:7], v64, v64, 1.0
	v_rcp_f32_e32 v11, v10
	s_nop 0
	v_fma_f32 v65, -v10, v11, 1.0
	v_fmac_f32_e32 v11, v65, v11
	v_div_scale_f32 v65, vcc, 1.0, v64, 1.0
	v_mul_f32_e32 v74, v65, v11
	v_fma_f32 v75, -v10, v74, v65
	v_fmac_f32_e32 v74, v75, v11
	v_fma_f32 v10, -v10, v74, v65
	v_div_fmas_f32 v10, v10, v11, v74
	v_div_fixup_f32 v10, v10, v64, 1.0
	v_mul_f32_e32 v11, v10, v60
	v_mul_f32_e32 v60, v10, v61
	v_med3_f32 v11, v11, s81, v185
	v_med3_f32 v60, v60, s81, v185
	v_cvt_pk_fp8_f32 v61, v11, v60
	v_mul_f32_e32 v11, v10, v62
	v_mul_f32_e32 v60, v10, v63
	v_med3_f32 v11, v11, s81, v185
	v_med3_f32 v60, v60, s81, v185
	v_cvt_pk_fp8_f32 v61, v11, v60 op_sel:[0,0,1]
	v_mul_f32_e32 v11, v10, v76
	v_mul_f32_e32 v60, v10, v77
	v_med3_f32 v11, v11, s81, v185
	v_med3_f32 v60, v60, s81, v185
	v_cvt_pk_fp8_f32 v62, v11, v60
	v_mul_f32_e32 v11, v10, v78
	v_mul_f32_e32 v60, v10, v79
	v_med3_f32 v11, v11, s81, v185
	v_med3_f32 v60, v60, s81, v185
	v_cvt_pk_fp8_f32 v62, v11, v60 op_sel:[0,0,1]
	v_mul_f32_e32 v11, v10, v214
	v_mul_f32_e32 v60, v10, v215
	v_med3_f32 v11, v11, s81, v185
	ds_write2_b32 v181, v61, v62 offset1:4
	v_med3_f32 v60, v60, s81, v185
	v_cvt_pk_fp8_f32 v61, v11, v60
	v_mul_f32_e32 v11, v10, v216
	v_mul_f32_e32 v60, v10, v217
	v_med3_f32 v11, v11, s81, v185
	v_med3_f32 v60, v60, s81, v185
	v_cvt_pk_fp8_f32 v61, v11, v60 op_sel:[0,0,1]
	v_mul_f32_e32 v11, v10, v218
	v_mul_f32_e32 v60, v10, v219
	v_med3_f32 v11, v11, s81, v185
	v_med3_f32 v60, v60, s81, v185
	v_cvt_pk_fp8_f32 v62, v11, v60
	v_mul_f32_e32 v11, v10, v220
	v_mul_f32_e32 v10, v10, v221
	v_med3_f32 v11, v11, s81, v185
	v_med3_f32 v10, v10, s81, v185
	v_cvt_pk_fp8_f32 v62, v11, v10 op_sel:[0,0,1]
	v_lshl_add_u32 v10, s86, 7, v124
	v_lshlrev_b32_e32 v10, s1, v10
	v_add_u32_e32 v10, s5, v10
	s_ashr_i32 s5, s4, 31
	s_ashr_i32 s1, s0, 31
	s_lshl_b64 s[4:5], s[4:5], 15
	s_lshl_b64 s[0:1], s[0:1], 11
	ds_write2_b32 v181, v61, v62 offset0:8 offset1:12
	s_add_u32 s0, s4, s0
	s_waitcnt lgkmcnt(0)
	s_addc_u32 s1, s5, s1
	v_ashrrev_i32_e32 v11, 31, v10
	ds_read_b128 v[60:63], v182
	v_lshl_add_u64 v[10:11], s[0:1], 0, v[10:11]
	v_lshlrev_b64 v[10:11], 8, v[10:11]
	v_lshl_add_u64 v[10:11], s[94:95], 0, v[10:11]
	s_lshl_b32 s86, s11, 6
	v_lshl_add_u64 v[10:11], v[10:11], 0, s[86:87]
	v_lshl_add_u64 v[10:11], v[10:11], 0, v[84:85]
	s_waitcnt lgkmcnt(0)
	global_store_dwordx4 v[10:11], v[60:63], off
	s_mov_b64 s[0:1], exec
	v_readlane_b32 s4, v250, 35
	v_readlane_b32 s5, v250, 36
	s_and_b64 s[4:5], s[0:1], s[4:5]
	s_mov_b64 exec, s[4:5]
	s_cbranch_execz .LBB0_286
	v_log_f32_e32 v10, v64
	s_nop 0
	v_add_f32_e32 v9, v9, v10
	v_mul_f32_e32 v9, 0x3f317218, v9
	global_store_dword v[98:99], v9, off
; #define LAS __attribute__((address_space(3)))
; __device__ __forceinline__ float f8c(float v) { return fminf(fmaxf(v, -448.f), 448.f); }
; __device__ __forceinline__ float bf_lo(unsigned u) { return __uint_as_float(u << 16); }
; __device__ __forceinline__ float bf_hi(unsigned u) { return __uint_as_float(u & 0xffff0000u); }
; __device__ __forceinline__ void attn_phase(const Params& p, LAS unsigned char* lds, int tid, int G, int bid) {
;     ...
;         if (ucnt < 8) { const int it = (bid * NWAVES + w) + (ucnt >= 4 ? G * NWAVES : 0), m0 = (it >> 1) * 16 + (ucnt & 3) * 4, ch = (it & 1) * 512 + lane * 8;
;             bf16_t* CV = (bf16_t*)(p.ws + WS_H); f32x4 ccw[6];
; #pragma unroll
;             for (int k = 0; k < 3; ++k) { ccw[2 * k] = *(const LAS f32x4*)(lds + CW_OFF + (k * D + ch) * 4); ccw[2 * k + 1] = *(const LAS f32x4*)(lds + CW_OFF + (k * D + ch + 4) * 4); }
; #pragma unroll
;             for (int i = 0; i < 4; ++i) { const u32x4 u0 = cuu[i], gz = cgg[i]; u32x4 o;
; #pragma unroll
;                 for (int j = 0; j < 4; ++j) { const float lo = bf_lo(gz[j]) * (ccw[0 + (j >> 1)][2 * (j & 1)] * bf_lo(cum2[j]) + ccw[2 + (j >> 1)][2 * (j & 1)] * bf_lo(cum1[j]) + ccw[4 + (j >> 1)][2 * (j & 1)] * bf_lo(u0[j]));
;                     const float hi = bf_hi(gz[j]) * (ccw[0 + (j >> 1)][2 * (j & 1) + 1] * bf_hi(cum2[j]) + ccw[2 + (j >> 1)][2 * (j & 1) + 1] * bf_hi(cum1[j]) + ccw[4 + (j >> 1)][2 * (j & 1) + 1] * bf_hi(u0[j]));
;                     o[j >> 1] = (j & 1) ? (unsigned)__builtin_amdgcn_cvt_pk_fp8_f32(f8c(lo), f8c(hi), (int)o[j >> 1], true) : (unsigned)__builtin_amdgcn_cvt_pk_fp8_f32(f8c(lo), f8c(hi), 0, false); }
;                 { u32x2 o2; o2.x = o[0]; o2.y = o[1]; *(u32x2*)((unsigned char*)CV + (size_t)(m0 + i) * KC + AOW + ch) = o2; } cum2 = cum1; cum1 = u0; } }
.LBB0_286:
	s_or_b64 exec, exec, s[0:1]
	s_andn2_b64 vcc, exec, s[84:85]
	v_readlane_b32 s86, v250, 15
	s_cbranch_vccnz .LBB0_270
	ds_read_b128 v[72:75], v183
	ds_read_b128 v[64:67], v183 offset:16
	ds_read_b128 v[76:79], v183 offset:4096
	ds_read_b128 v[60:63], v183 offset:4112
	ds_read_b128 v[80:83], v183 offset:8192
	ds_read_b128 v[68:71], v183 offset:8208
	s_waitcnt vmcnt(8)
	v_and_b32_e32 v113, 0xffff0000, v22
	s_waitcnt vmcnt(2)
	v_and_b32_e32 v112, 0xffff0000, v58
	s_waitcnt lgkmcnt(4)
	v_mov_b32_e32 v110, v65
	s_waitcnt vmcnt(1)
	v_and_b32_e32 v210, 0xffff0000, v54
	s_waitcnt lgkmcnt(0)
	v_mov_b32_e32 v111, v69
	v_pk_mul_f32 v[10:11], v[110:111], v[112:113]
	v_lshlrev_b32_e32 v109, 16, v22
	v_fma_f32 v10, v61, v210, v10
	v_add_f32_e32 v10, v10, v11
	v_and_b32_e32 v11, 0xffff0000, v26
	v_lshlrev_b32_e32 v108, 16, v58
	v_mov_b32_e32 v106, v64
	v_mov_b32_e32 v107, v68
	v_lshlrev_b32_e32 v209, 16, v54
	v_mul_f32_e32 v54, v10, v11
	v_pk_mul_f32 v[10:11], v[106:107], v[108:109]
	v_and_b32_e32 v114, 0xffff0000, v56
	v_fma_f32 v10, v60, v209, v10
	v_add_f32_e32 v10, v10, v11
	v_lshlrev_b32_e32 v11, 16, v26
	v_mul_f32_e32 v10, v10, v11
	v_lshlrev_b32_e32 v186, 16, v56
	v_lshlrev_b32_e32 v192, 16, v57
	v_and_b32_e32 v198, 0xffff0000, v57
	v_med3_f32 v10, v10, s81, v185
	v_med3_f32 v11, v54, s81, v185
	v_lshlrev_b32_e32 v105, 16, v23
	v_lshlrev_b32_e32 v104, 16, v59
	v_mov_b32_e32 v56, v66
	v_mov_b32_e32 v57, v70
	v_cvt_pk_fp8_f32 v205, v10, v11
	v_lshlrev_b32_e32 v211, 16, v55
	v_pk_mul_f32 v[10:11], v[56:57], v[104:105]
	v_and_b32_e32 v212, 0xffff0000, v55
	v_fma_f32 v10, v62, v211, v10
	v_add_f32_e32 v10, v10, v11
	v_lshlrev_b32_e32 v11, 16, v27
	v_mul_f32_e32 v10, v10, v11
	v_med3_f32 v104, v10, s81, v185
	v_and_b32_e32 v55, 0xffff0000, v23
	v_and_b32_e32 v54, 0xffff0000, v59
	v_mov_b32_e32 v10, v67
	v_mov_b32_e32 v11, v71
	v_pk_mul_f32 v[58:59], v[10:11], v[54:55]
	v_and_b32_e32 v115, 0xffff0000, v20
	v_fma_f32 v58, v63, v212, v58
	v_add_f32_e32 v58, v58, v59
	v_and_b32_e32 v59, 0xffff0000, v27
	v_mov_b32_e32 v116, v73
	v_mov_b32_e32 v117, v81
	v_mul_f32_e32 v58, v58, v59
	v_pk_mul_f32 v[118:119], v[116:117], v[114:115]
	v_med3_f32 v58, v58, s81, v185
	v_and_b32_e32 v206, 0xffff0000, v52
	v_cvt_pk_fp8_f32 v205, v104, v58 op_sel:[0,0,1]
	v_and_b32_e32 v207, 0xffff0000, v28
	v_fma_f32 v104, v77, v206, v118
	v_and_b32_e32 v9, 0xffff0000, v24
	v_lshlrev_b32_e32 v187, 16, v20
	v_mov_b32_e32 v188, v72
	v_mov_b32_e32 v189, v80
	v_add_f32_e32 v104, v104, v119
	v_pk_mul_f32 v[118:119], v[116:117], v[206:207]
	v_pk_mul_f32 v[190:191], v[188:189], v[186:187]
	v_mul_f32_e32 v9, v104, v9
	v_fma_f32 v104, v77, v115, v118
	v_lshlrev_b32_e32 v118, 16, v52
	v_fma_f32 v52, v76, v118, v190
	v_lshlrev_b32_e32 v186, 16, v24
	v_add_f32_e32 v52, v52, v191
	v_add_f32_e32 v104, v104, v119
	v_lshlrev_b32_e32 v119, 16, v28
	v_mul_f32_e32 v52, v52, v186
	v_med3_f32 v9, v9, s81, v185
	v_med3_f32 v52, v52, s81, v185
	v_pk_mul_f32 v[190:191], v[188:189], v[118:119]
	v_cvt_pk_fp8_f32 v204, v52, v9
	v_fma_f32 v9, v76, v187, v190
	v_and_b32_e32 v108, 0xffff0000, v32
	v_add_f32_e32 v9, v9, v191
	v_lshlrev_b32_e32 v52, 16, v32
	v_lshlrev_b32_e32 v193, 16, v21
	v_mov_b32_e32 v194, v74
	v_mov_b32_e32 v195, v82
	v_mul_f32_e32 v104, v104, v108
	v_mul_f32_e32 v9, v9, v52
	v_pk_mul_f32 v[196:197], v[194:195], v[192:193]
	v_med3_f32 v9, v9, s81, v185
	v_med3_f32 v104, v104, s81, v185
	v_lshlrev_b32_e32 v190, 16, v53
	v_cvt_pk_fp8_f32 v52, v9, v104
	v_lshlrev_b32_e32 v191, 16, v29
	v_fma_f32 v9, v78, v190, v196
	v_and_b32_e32 v199, 0xffff0000, v21
	v_mov_b32_e32 v200, v75
	v_mov_b32_e32 v201, v83
	v_add_f32_e32 v9, v9, v197
	v_pk_mul_f32 v[196:197], v[194:195], v[190:191]
	v_pk_mul_f32 v[202:203], v[200:201], v[198:199]
	v_fma_f32 v104, v78, v193, v196
	v_and_b32_e32 v196, 0xffff0000, v53
	v_fma_f32 v53, v79, v196, v202
	v_lshlrev_b32_e32 v192, 16, v25
	v_and_b32_e32 v208, 0xffff0000, v25
	v_add_f32_e32 v53, v53, v203
	v_mul_f32_e32 v9, v9, v192
	v_add_f32_e32 v104, v104, v197
	v_and_b32_e32 v197, 0xffff0000, v29
	v_mul_f32_e32 v53, v53, v208
	v_med3_f32 v9, v9, s81, v185
	v_med3_f32 v53, v53, s81, v185
	v_pk_mul_f32 v[202:203], v[200:201], v[196:197]
	v_cvt_pk_fp8_f32 v204, v9, v53 op_sel:[0,0,1]
	v_fma_f32 v9, v79, v199, v202
	v_add_f32_e32 v9, v9, v203
	v_and_b32_e32 v203, 0xffff0000, v44
	v_and_b32_e32 v202, 0xffff0000, v36
	v_pk_mov_b32 v[114:115], v[114:115], v[202:203] op_sel:[1,0]
	v_lshlrev_b32_e32 v108, 16, v33
	v_pk_mul_f32 v[114:115], v[116:117], v[114:115]
	v_mul_f32_e32 v104, v104, v108
	v_fma_f32 v108, v77, v207, v114
	v_add_f32_e32 v108, v108, v115
	v_mov_b32_e32 v114, v77
	v_mov_b32_e32 v115, v81
	v_pk_mul_f32 v[114:115], v[114:115], v[202:203]
	v_and_b32_e32 v53, 0xffff0000, v33
	v_fma_f32 v73, v73, v207, v114
	v_add_f32_e32 v73, v73, v115
	v_lshlrev_b32_e32 v114, 16, v36
	v_lshlrev_b32_e32 v115, 16, v44
	v_pk_mov_b32 v[116:117], v[186:187], v[114:115] op_sel:[1,0]
	v_mul_f32_e32 v9, v9, v53
	v_and_b32_e32 v77, 0xffff0000, v48
	v_pk_mul_f32 v[116:117], v[188:189], v[116:117]
	v_med3_f32 v104, v104, s81, v185
	v_med3_f32 v9, v9, s81, v185
	v_mul_f32_e32 v73, v73, v77
	v_fma_f32 v77, v76, v119, v116
	v_cvt_pk_fp8_f32 v52, v104, v9 op_sel:[0,0,1]
	v_and_b32_e32 v9, 0xffff0000, v40
	v_lshlrev_b32_e32 v53, 16, v40
	v_add_f32_e32 v77, v77, v117
	v_mul_f32_e32 v9, v108, v9
	v_mul_f32_e32 v53, v77, v53
	v_mov_b32_e32 v77, v80
	v_med3_f32 v9, v9, s81, v185
	v_med3_f32 v53, v53, s81, v185
	v_pk_mul_f32 v[76:77], v[76:77], v[114:115]
	v_cvt_pk_fp8_f32 v108, v53, v9
	v_fma_f32 v9, v72, v119, v76
	v_add_f32_e32 v9, v9, v77
	v_lshlrev_b32_e32 v53, 16, v48
; #define LAS __attribute__((address_space(3)))
; __device__ __forceinline__ float f8c(float v) { return fminf(fmaxf(v, -448.f), 448.f); }
; __device__ __forceinline__ float bf_lo(unsigned u) { return __uint_as_float(u << 16); }
; __device__ __forceinline__ float bf_hi(unsigned u) { return __uint_as_float(u & 0xffff0000u); }
; __device__ __forceinline__ void attn_phase(const Params& p, LAS unsigned char* lds, int tid, int G, int bid) {
;     ...
;         if (ucnt < 8) { const int it = (bid * NWAVES + w) + (ucnt >= 4 ? G * NWAVES : 0), m0 = (it >> 1) * 16 + (ucnt & 3) * 4, ch = (it & 1) * 512 + lane * 8;
;             bf16_t* CV = (bf16_t*)(p.ws + WS_H); f32x4 ccw[6];
; #pragma unroll
;             for (int k = 0; k < 3; ++k) { ccw[2 * k] = *(const LAS f32x4*)(lds + CW_OFF + (k * D + ch) * 4); ccw[2 * k + 1] = *(const LAS f32x4*)(lds + CW_OFF + (k * D + ch + 4) * 4); }
; #pragma unroll
;             for (int i = 0; i < 4; ++i) { const u32x4 u0 = cuu[i], gz = cgg[i]; u32x4 o;
; #pragma unroll
;                 for (int j = 0; j < 4; ++j) { const float lo = bf_lo(gz[j]) * (ccw[0 + (j >> 1)][2 * (j & 1)] * bf_lo(cum2[j]) + ccw[2 + (j >> 1)][2 * (j & 1)] * bf_lo(cum1[j]) + ccw[4 + (j >> 1)][2 * (j & 1)] * bf_lo(u0[j]));
;                     const float hi = bf_hi(gz[j]) * (ccw[0 + (j >> 1)][2 * (j & 1) + 1] * bf_hi(cum2[j]) + ccw[2 + (j >> 1)][2 * (j & 1) + 1] * bf_hi(cum1[j]) + ccw[4 + (j >> 1)][2 * (j & 1) + 1] * bf_hi(u0[j]));
;                     o[j >> 1] = (j & 1) ? (unsigned)__builtin_amdgcn_cvt_pk_fp8_f32(f8c(lo), f8c(hi), (int)o[j >> 1], true) : (unsigned)__builtin_amdgcn_cvt_pk_fp8_f32(f8c(lo), f8c(hi), 0, false); }
;                 { u32x2 o2; o2.x = o[0]; o2.y = o[1]; *(u32x2*)((unsigned char*)CV + (size_t)(m0 + i) * KC + AOW + ch) = o2; } cum2 = cum1; cum1 = u0; } }
;         ++ucnt;
;         __syncthreads();
	v_lshlrev_b32_e32 v76, 16, v37
	v_lshlrev_b32_e32 v77, 16, v45
	v_mul_f32_e32 v9, v9, v53
	v_pk_mov_b32 v[80:81], v[192:193], v[76:77] op_sel:[1,0]
	v_med3_f32 v9, v9, s81, v185
	v_med3_f32 v53, v73, s81, v185
	v_pk_mul_f32 v[80:81], v[194:195], v[80:81]
	v_cvt_pk_fp8_f32 v72, v9, v53
	v_fma_f32 v9, v78, v191, v80
	v_add_f32_e32 v9, v9, v81
	v_mov_b32_e32 v80, v78
	v_mov_b32_e32 v81, v82
	v_pk_mul_f32 v[76:77], v[80:81], v[76:77]
	v_lshlrev_b32_e32 v73, 16, v49
	v_fma_f32 v53, v74, v191, v76
	v_add_f32_e32 v53, v53, v77
	v_and_b32_e32 v77, 0xffff0000, v45
	v_and_b32_e32 v76, 0xffff0000, v37
	v_pk_mov_b32 v[80:81], v[198:199], v[76:77] op_sel:[1,0]
	v_mul_f32_e32 v53, v53, v73
	v_pk_mul_f32 v[80:81], v[200:201], v[80:81]
	v_lshlrev_b32_e32 v104, 16, v41
	v_fma_f32 v73, v79, v197, v80
	v_and_b32_e32 v118, 0xffff0000, v41
	v_add_f32_e32 v73, v73, v81
	v_mul_f32_e32 v9, v9, v104
	v_mul_f32_e32 v73, v73, v118
	v_mov_b32_e32 v82, v79
	v_med3_f32 v9, v9, s81, v185
	v_med3_f32 v73, v73, s81, v185
	v_pk_mul_f32 v[76:77], v[82:83], v[76:77]
	v_cvt_pk_fp8_f32 v108, v9, v73 op_sel:[0,0,1]
	v_fma_f32 v9, v75, v197, v76
	v_and_b32_e32 v189, 0xffff0000, v46
	v_and_b32_e32 v188, 0xffff0000, v30
	v_add_f32_e32 v9, v9, v77
	v_and_b32_e32 v73, 0xffff0000, v49
	v_mov_b32_e32 v76, v113
	v_mov_b32_e32 v190, v61
	v_mov_b32_e32 v191, v69
	v_pk_mov_b32 v[112:113], v[112:113], v[188:189] op_sel:[1,0]
	v_mul_f32_e32 v9, v9, v73
	v_pk_mul_f32 v[112:113], v[190:191], v[112:113]
	v_med3_f32 v53, v53, s81, v185
	v_med3_f32 v9, v9, s81, v185
	v_and_b32_e32 v77, 0xffff0000, v38
	v_fma_f32 v65, v65, v210, v112
	v_cvt_pk_fp8_f32 v72, v53, v9 op_sel:[0,0,1]
	v_and_b32_e32 v9, 0xffff0000, v34
	v_pk_mul_f32 v[78:79], v[110:111], v[76:77]
	v_add_f32_e32 v65, v65, v113
	v_mul_f32_e32 v9, v65, v9
	v_fma_f32 v65, v61, v188, v78
	v_add_f32_e32 v65, v65, v79
	v_pk_mul_f32 v[78:79], v[110:111], v[188:189]
	v_and_b32_e32 v73, 0xffff0000, v42
	v_fma_f32 v61, v61, v77, v78
	v_add_f32_e32 v61, v61, v79
	v_and_b32_e32 v69, 0xffff0000, v50
	v_lshlrev_b32_e32 v76, 16, v30
	v_lshlrev_b32_e32 v77, 16, v46
	v_mul_f32_e32 v65, v65, v73
	v_mul_f32_e32 v73, v61, v69
	v_mov_b32_e32 v61, v68
	v_pk_mov_b32 v[68:69], v[108:109], v[76:77] op_sel:[1,0]
	v_lshlrev_b32_e32 v53, 16, v34
	v_pk_mul_f32 v[68:69], v[60:61], v[68:69]
	v_lshlrev_b32_e32 v75, 16, v38
	v_fma_f32 v61, v64, v209, v68
	v_add_f32_e32 v61, v61, v69
	v_mov_b32_e32 v74, v109
	v_mul_f32_e32 v53, v61, v53
	v_pk_mul_f32 v[80:81], v[106:107], v[74:75]
	v_med3_f32 v9, v9, s81, v185
	v_med3_f32 v61, v53, s81, v185
	v_cvt_pk_fp8_f32 v53, v61, v9
	v_fma_f32 v9, v60, v76, v80
	v_lshlrev_b32_e32 v74, 16, v42
	v_add_f32_e32 v9, v9, v81
	v_mul_f32_e32 v9, v9, v74
	v_med3_f32 v65, v65, s81, v185
	v_med3_f32 v9, v9, s81, v185
	v_cvt_pk_fp8_f32 v109, v9, v65
	v_pk_mul_f32 v[64:65], v[106:107], v[76:77]
	s_cmp_gt_u32 s9, 3
	v_fma_f32 v9, v60, v75, v64
	v_add_f32_e32 v9, v9, v65
	v_lshlrev_b32_e32 v60, 16, v50
	v_mul_f32_e32 v9, v9, v60
	v_med3_f32 v9, v9, s81, v185
	v_med3_f32 v60, v73, s81, v185
	s_cselect_b32 s0, s86, 0
	v_readlane_b32 s1, v250, 34
	v_lshlrev_b32_e32 v83, 16, v39
	v_mov_b32_e32 v82, v105
	v_cvt_pk_fp8_f32 v73, v9, v60
	v_lshlrev_b32_e32 v60, 16, v31
	v_lshlrev_b32_e32 v61, 16, v47
	s_add_i32 s0, s0, s1
	v_pk_mul_f32 v[116:117], v[56:57], v[82:83]
	v_pk_mul_f32 v[56:57], v[56:57], v[60:61]
	s_lshl_b32 s0, s0, 3
	v_lshlrev_b32_e32 v104, 16, v35
	v_fma_f32 v56, v62, v83, v56
	s_and_b32 s1, s8, 12
	s_and_b32 s0, s0, -16
	v_mov_b32_e32 v64, v62
	v_mov_b32_e32 v65, v70
	v_pk_mov_b32 v[68:69], v[104:105], v[60:61] op_sel:[1,0]
	v_add_f32_e32 v56, v56, v57
	v_lshlrev_b32_e32 v57, 16, v51
	s_or_b32 s0, s0, s1
	v_pk_mul_f32 v[64:65], v[64:65], v[68:69]
	v_mul_f32_e32 v56, v56, v57
	s_mul_i32 s4, s0, 0x500
	v_fma_f32 v9, v66, v211, v64
	v_fma_f32 v64, v62, v60, v116
	v_med3_f32 v60, v56, s81, v185
	v_and_b32_e32 v57, 0xffff0000, v47
	v_and_b32_e32 v56, 0xffff0000, v31
	s_mul_hi_i32 s1, s0, 0x500
	s_add_u32 s4, s96, s4
	v_mov_b32_e32 v114, v55
	v_mov_b32_e32 v70, v63
	v_pk_mov_b32 v[54:55], v[54:55], v[56:57] op_sel:[1,0]
	s_addc_u32 s5, s97, s1
	s_or_b32 s1, s0, 1
	v_pk_mul_f32 v[54:55], v[70:71], v[54:55]
	v_lshl_add_u64 v[58:59], s[4:5], 0, v[94:95]
	s_brev_b32 s6, 64
	s_mul_hi_i32 s5, s1, 0x500
	s_mulk_i32 s1, 0x500
	v_and_b32_e32 v115, 0xffff0000, v39
	v_fma_f32 v54, v67, v212, v54
	v_add_co_u32_e32 v58, vcc, s6, v58
	v_and_b32_e32 v192, 0xffff0000, v35
	s_add_u32 s4, s96, s1
	v_pk_mul_f32 v[118:119], v[10:11], v[114:115]
	v_add_f32_e32 v9, v9, v65
	v_add_f32_e32 v54, v54, v55
	v_addc_co_u32_e32 v59, vcc, 0, v59, vcc
	s_addc_u32 s5, s97, s5
	s_or_b32 s1, s0, 2
	v_mul_f32_e32 v9, v9, v104
	v_mul_f32_e32 v54, v54, v192
	v_fma_f32 v55, v63, v56, v118
	global_store_dwordx2 v[58:59], v[204:205], off offset:256
	v_lshl_add_u64 v[58:59], s[4:5], 0, v[94:95]
	v_lshlrev_b32_e32 v82, 16, v43
	v_and_b32_e32 v114, 0xffff0000, v43
	s_mul_hi_i32 s5, s1, 0x500
	s_mulk_i32 s1, 0x500
	v_med3_f32 v9, v9, s81, v185
	v_add_f32_e32 v64, v64, v117
	v_med3_f32 v54, v54, s81, v185
	v_add_f32_e32 v55, v55, v119
	v_pk_mul_f32 v[10:11], v[10:11], v[56:57]
	s_add_u32 s4, s96, s1
	v_mul_f32_e32 v64, v64, v82
	v_mul_f32_e32 v55, v55, v114
	v_cvt_pk_fp8_f32 v53, v9, v54 op_sel:[0,0,1]
	v_fma_f32 v9, v63, v115, v10
	s_addc_u32 s5, s97, s5
	v_med3_f32 v64, v64, s81, v185
	v_med3_f32 v61, v55, s81, v185
	v_add_f32_e32 v9, v9, v11
	v_and_b32_e32 v10, 0xffff0000, v51
	s_or_b32 s0, s0, 3
	v_add_co_u32_e32 v54, vcc, s6, v58
	v_cvt_pk_fp8_f32 v109, v64, v61 op_sel:[0,0,1]
	v_mul_f32_e32 v9, v9, v10
	s_mul_hi_i32 s1, s0, 0x500
	s_mulk_i32 s0, 0x500
	v_lshl_add_u64 v[186:187], s[4:5], 0, v[94:95]
	v_addc_co_u32_e32 v55, vcc, 0, v59, vcc
	v_med3_f32 v9, v9, s81, v185
	s_add_u32 s0, s96, s0
	global_store_dwordx2 v[54:55], v[52:53], off offset:256
	v_add_co_u32_e32 v52, vcc, s6, v186
	v_cvt_pk_fp8_f32 v73, v60, v9 op_sel:[0,0,1]
	s_addc_u32 s1, s97, s1
	v_addc_co_u32_e32 v53, vcc, 0, v187, vcc
	v_lshl_add_u64 v[10:11], s[0:1], 0, v[94:95]
	global_store_dwordx2 v[52:53], v[108:109], off offset:256
	v_add_co_u32_e32 v10, vcc, 0x2000000, v10
	v_mov_b64_e32 v[54:55], v[46:47]
	v_mov_b64_e32 v[58:59], v[38:39]
	v_addc_co_u32_e32 v11, vcc, 0, v11, vcc
	v_mov_b64_e32 v[52:53], v[44:45]
	v_mov_b64_e32 v[56:57], v[36:37]
	global_store_dwordx2 v[10:11], v[72:73], off offset:256
	s_branch .LBB0_270

; __device__ __forceinline__ f32x4 f8x4(unsigned u) { const f32x2u a = __builtin_amdgcn_cvt_pk_f32_fp8((int)u, false), b = __builtin_amdgcn_cvt_pk_f32_fp8((int)u, true); return (f32x4){a.x, a.y, b.x, b.y}; }
; __device__ __forceinline__ float bf_lo(unsigned u) { return __uint_as_float(u << 16); }
; __device__ __forceinline__ float bf_hi(unsigned u) { return __uint_as_float(u & 0xffff0000u); }
; __device__ __forceinline__ void ew_phase(const Params& p, int gw, int NGW, int lane) {
;     ...
;     for (int it = gw; it < M / 4; it += NGW) {
;         u32x2 a0[2], a1[2], a2[2]; u32x4 z[2]; float l0[2], l1[2], l2[2]; size_t off[2], offz[2];
; #pragma unroll
;         for (int q = 0; q < 2; ++q) {
;             const int m = it * 4 + q * 2 + (lane >> 5), ci = (lane & 31) * 8, hh = ci >> 6;
;             const int bb = m >> 11, t = m & (SEQ - 1), ub = bb * 192 + hh * 16;
;             l0[q] = LSE[(size_t)(ub + (t >> 7)) * 128 + (t & 127)];
;             l1[q] = LSE[(size_t)(ub + 64 + (t & 3) + ((t >> 9) << 2)) * 128 + ((t >> 2) & 127)];
;             l2[q] = LSE[(size_t)(ub + 128 + (t & 15)) * 128 + (t >> 4)];
;             off[q] = (size_t)m * AOW + ci; offz[q] = (size_t)m * KC + ci;
;             a0[q] = __builtin_nontemporal_load((const u32x2*)((const unsigned char*)OG + off[q])); a1[q] = __builtin_nontemporal_load((const u32x2*)((const unsigned char*)OG + (size_t)M * AOW + off[q])); a2[q] = __builtin_nontemporal_load((const u32x2*)((const unsigned char*)OG + (size_t)2 * M * AOW + off[q])); z[q] = __builtin_nontemporal_load((const u32x4*)(ZA + off[q]));
;         }
; #pragma unroll
;         for (int q = 0; q < 2; ++q) {
;             const float mx = fmaxf(l0[q], fmaxf(l1[q], l2[q]));
;             float e0 = __builtin_amdgcn_exp2f((l0[q] - mx) * LOG2E), e1 = __builtin_amdgcn_exp2f((l1[q] - mx) * LOG2E), e2 = __builtin_amdgcn_exp2f((l2[q] - mx) * LOG2E);
;             const float inv = 1.0f / (e0 + e1 + e2); e0 *= inv; e1 *= inv; e2 *= inv;
;             int w8[2] = {0, 0};
; #pragma unroll
;             for (int hj = 0; hj < 2; ++hj) { const f32x4 x0 = f8x4(a0[q][hj]), x1 = f8x4(a1[q][hj]), x2 = f8x4(a2[q][hj]);
;                 const float v0 = (e0 * x0[0] + e1 * x1[0] + e2 * x2[0]) * bf_lo(z[q][2 * hj]), v1 = (e0 * x0[1] + e1 * x1[1] + e2 * x2[1]) * bf_hi(z[q][2 * hj]);
.LBB0_343:
	s_ashr_i32 s0, s33, 9
	v_add_u32_e32 v8, s3, v16
	s_mul_i32 s14, s0, 0xc0
	s_lshr_b32 s1, s3, 7
	v_lshrrev_b32_e32 v19, 7, v8
	v_ashrrev_i32_e32 v9, 31, v8
	v_add_u32_e32 v20, 2, v8
	v_or_b32_e32 v25, s14, v17
	s_and_b32 s16, s1, 12
	v_lshlrev_b64 v[22:23], 8, v[8:9]
	v_lshrrev_b32_e32 v9, 7, v20
	v_ashrrev_i32_e32 v21, 31, v20
	v_add_u32_e32 v41, 0x80, v25
	v_and_or_b32 v24, v19, 15, v25
	s_and_b32 s13, s33, 0x7f
	v_and_b32_e32 v2, 0x7d, v8
	v_lshrrev_b32_e32 v52, 2, v8
	v_mad_i64_i32 v[12:13], s[0:1], v8, s12, v[4:5]
	v_add3_u32 v31, v25, s16, 64
	v_or_b32_e32 v22, v22, v0
	v_and_or_b32 v26, v9, 15, v25
	v_lshlrev_b64 v[28:29], 8, v[20:21]
	v_ashrrev_i32_e32 v25, 31, v24
	v_and_or_b32 v8, v8, 13, v41
	s_lshl_b32 s13, s13, 2
	v_or_b32_e32 v30, v31, v16
	v_lshl_add_u64 v[34:35], s[6:7], 0, v[22:23]
	v_lshl_add_u64 v[36:37], s[8:9], 0, v[22:23]
	v_lshl_add_u64 v[38:39], v[22:23], 1, s[18:19]
	v_ashrrev_i32_e32 v27, 31, v26
	v_or_b32_e32 v40, v31, v18
	v_and_or_b32 v42, v20, 15, v41
	v_or_b32_e32 v28, v28, v0
	v_lshlrev_b64 v[24:25], 9, v[24:25]
	v_ashrrev_i32_e32 v9, 31, v8
	s_add_u32 s0, s4, s13
	v_lshlrev_b32_e32 v2, 2, v2
	v_and_b32_e32 v53, 0x7f, v20
	v_lshrrev_b32_e32 v54, 2, v20
	v_mad_i64_i32 v[14:15], s[14:15], v20, s12, v[4:5]
	v_lshl_add_u64 v[32:33], s[94:95], 0, v[22:23]
	global_load_dwordx2 v[44:45], v[34:35], off nt
	global_load_dwordx2 v[46:47], v[36:37], off nt
	global_load_dwordx4 v[20:23], v[38:39], off nt
	v_ashrrev_i32_e32 v31, 31, v30
	v_lshlrev_b64 v[34:35], 9, v[26:27]
	v_ashrrev_i32_e32 v41, 31, v40
	v_ashrrev_i32_e32 v43, 31, v42
	v_lshl_add_u64 v[26:27], s[94:95], 0, v[28:29]
	v_lshl_add_u64 v[36:37], s[6:7], 0, v[28:29]
	v_lshl_add_u64 v[38:39], s[8:9], 0, v[28:29]
	v_lshl_add_u64 v[28:29], v[28:29], 1, s[18:19]
	v_lshl_add_u64 v[50:51], s[4:5], 0, v[24:25]
	v_lshlrev_b64 v[8:9], 9, v[8:9]
	s_addc_u32 s1, s5, 0
	global_load_dwordx2 v[48:49], v[26:27], off nt
	v_lshlrev_b64 v[30:31], 9, v[30:31]
	global_load_dwordx2 v[36:37], v[36:37], off nt
	v_lshl_add_u64 v[8:9], s[4:5], 0, v[8:9]
	global_load_dwordx2 v[38:39], v[38:39], off nt
	v_lshl_add_u64 v[30:31], s[0:1], 0, v[30:31]
	global_load_dwordx4 v[24:27], v[28:29], off nt
	v_lshl_add_u64 v[28:29], s[4:5], 0, v[34:35]
	v_lshlrev_b64 v[34:35], 9, v[40:41]
	v_lshlrev_b64 v[40:41], 9, v[42:43]
	v_lshl_add_u64 v[42:43], v[50:51], 0, v[2:3]
	v_and_b32_e32 v2, 0x1fc, v52
	v_lshl_add_u64 v[8:9], v[8:9], 0, v[2:3]
	v_lshlrev_b32_e32 v2, 2, v53
	global_load_dword v19, v[42:43], off
	global_load_dword v66, v[30:31], off
	global_load_dword v68, v[8:9], off
	global_load_dwordx2 v[50:51], v[32:33], off nt
	v_lshl_add_u64 v[40:41], s[4:5], 0, v[40:41]
	v_lshl_add_u64 v[8:9], v[28:29], 0, v[2:3]
	v_and_b32_e32 v2, 0x1fc, v54
	v_lshl_add_u64 v[34:35], s[0:1], 0, v[34:35]
	v_lshl_add_u64 v[28:29], v[40:41], 0, v[2:3]
	global_load_dword v2, v[8:9], off
	global_load_dword v70, v[34:35], off
	global_load_dword v72, v[28:29], off
	s_add_i32 s33, s33, s86
	s_add_i32 s3, s3, s10
	s_cmpk_lt_i32 s33, 0x2000
	s_waitcnt vmcnt(13)
	v_cvt_pk_f32_fp8_e32 v[8:9], v44
	s_waitcnt vmcnt(12)
	v_cvt_pk_f32_fp8_e32 v[30:31], v46
	v_cvt_pk_f32_fp8_sdwa v[32:33], v46 src0_sel:WORD_1
	v_cvt_pk_f32_fp8_e32 v[40:41], v47
	v_cvt_pk_f32_fp8_sdwa v[28:29], v44 src0_sel:WORD_1
	s_waitcnt vmcnt(11)
	v_lshlrev_b32_e32 v76, 16, v20
	v_and_b32_e32 v77, 0xffff0000, v20
	v_lshlrev_b32_e32 v78, 16, v21
	v_and_b32_e32 v79, 0xffff0000, v21
	v_cvt_pk_f32_fp8_e32 v[20:21], v45
	v_cvt_pk_f32_fp8_sdwa v[34:35], v45 src0_sel:WORD_1
	v_lshlrev_b32_e32 v80, 16, v22
	v_and_b32_e32 v81, 0xffff0000, v22
	v_lshlrev_b32_e32 v82, 16, v23
	v_and_b32_e32 v83, 0xffff0000, v23
	s_waitcnt vmcnt(10)
	v_cvt_pk_f32_fp8_e32 v[22:23], v48
	v_cvt_pk_f32_fp8_sdwa v[44:45], v48 src0_sel:WORD_1
	v_mov_b32_e32 v67, v30
	s_waitcnt vmcnt(8)
	v_cvt_pk_f32_fp8_e32 v[54:55], v38
	v_cvt_pk_f32_fp8_sdwa v[56:57], v38 src0_sel:WORD_1
	s_waitcnt vmcnt(7)
	v_lshlrev_b32_e32 v84, 16, v24
	v_and_b32_e32 v85, 0xffff0000, v24
	v_lshlrev_b32_e32 v86, 16, v25
	v_and_b32_e32 v87, 0xffff0000, v25
	v_cvt_pk_f32_fp8_e32 v[24:25], v49
	v_cvt_pk_f32_fp8_sdwa v[48:49], v49 src0_sel:WORD_1
	v_cvt_pk_f32_fp8_e32 v[60:61], v39
	v_cvt_pk_f32_fp8_sdwa v[38:39], v39 src0_sel:WORD_1
	v_lshlrev_b32_e32 v88, 16, v26
	v_and_b32_e32 v89, 0xffff0000, v26
	v_lshlrev_b32_e32 v90, 16, v27
	v_and_b32_e32 v91, 0xffff0000, v27
	s_waitcnt vmcnt(4)
	v_max3_f32 v74, v19, v66, v68
	s_waitcnt vmcnt(3)
	v_cvt_pk_f32_fp8_e32 v[26:27], v50
	v_cvt_pk_f32_fp8_sdwa v[62:63], v50 src0_sel:WORD_1
	v_cvt_pk_f32_fp8_e32 v[64:65], v51
	v_cvt_pk_f32_fp8_sdwa v[50:51], v51 src0_sel:WORD_1
	v_sub_f32_e32 v19, v19, v74
	v_sub_f32_e32 v30, v66, v74
	v_mov_b32_e32 v69, v32
	v_mov_b32_e32 v71, v40
	v_sub_f32_e32 v32, v68, v74
	v_mul_f32_e32 v19, 0x3fb8aa3b, v19
	v_mul_f32_e32 v30, 0x3fb8aa3b, v30
	s_waitcnt vmcnt(0)
; __device__ __forceinline__ float f8c(float v) { return fminf(fmaxf(v, -448.f), 448.f); }
; __device__ __forceinline__ f32x4 f8x4(unsigned u) { const f32x2u a = __builtin_amdgcn_cvt_pk_f32_fp8((int)u, false), b = __builtin_amdgcn_cvt_pk_f32_fp8((int)u, true); return (f32x4){a.x, a.y, b.x, b.y}; }
; __device__ __forceinline__ float bf_lo(unsigned u) { return __uint_as_float(u << 16); }
; __device__ __forceinline__ float bf_hi(unsigned u) { return __uint_as_float(u & 0xffff0000u); }
; __device__ __forceinline__ void ew_phase(const Params& p, int gw, int NGW, int lane) {
;     ...
;         for (int q = 0; q < 2; ++q) {
;             const float mx = fmaxf(l0[q], fmaxf(l1[q], l2[q]));
;             float e0 = __builtin_amdgcn_exp2f((l0[q] - mx) * LOG2E), e1 = __builtin_amdgcn_exp2f((l1[q] - mx) * LOG2E), e2 = __builtin_amdgcn_exp2f((l2[q] - mx) * LOG2E);
;             const float inv = 1.0f / (e0 + e1 + e2); e0 *= inv; e1 *= inv; e2 *= inv;
;             int w8[2] = {0, 0};
; #pragma unroll
;             for (int hj = 0; hj < 2; ++hj) { const f32x4 x0 = f8x4(a0[q][hj]), x1 = f8x4(a1[q][hj]), x2 = f8x4(a2[q][hj]);
;                 const float v0 = (e0 * x0[0] + e1 * x1[0] + e2 * x2[0]) * bf_lo(z[q][2 * hj]), v1 = (e0 * x0[1] + e1 * x1[1] + e2 * x2[1]) * bf_hi(z[q][2 * hj]);
;                 const float v2 = (e0 * x0[2] + e1 * x1[2] + e2 * x2[2]) * bf_lo(z[q][2 * hj + 1]), v3 = (e0 * x0[3] + e1 * x1[3] + e2 * x2[3]) * bf_hi(z[q][2 * hj + 1]);
;                 w8[hj] = __builtin_amdgcn_cvt_pk_fp8_f32(f8c(v0), f8c(v1), w8[hj], false); w8[hj] = __builtin_amdgcn_cvt_pk_fp8_f32(f8c(v2), f8c(v3), w8[hj], true); }
;             { u32x2 o2; o2.x = (unsigned)w8[0]; o2.y = (unsigned)w8[1]; *(u32x2*)((unsigned char*)OZ + offz[q]) = o2; }
	v_max3_f32 v40, v2, v70, v72
	v_mov_b32_e32 v74, v22
	v_mov_b32_e32 v22, v44
	v_mov_b32_e32 v44, v24
	v_mov_b32_e32 v24, v48
	v_mul_f32_e32 v32, 0x3fb8aa3b, v32
	v_exp_f32_e32 v48, v19
	v_exp_f32_e32 v19, v30
	v_sub_f32_e32 v2, v2, v40
	v_sub_f32_e32 v92, v70, v40
	v_mov_b32_e32 v75, v54
	v_mov_b32_e32 v54, v23
	v_mov_b32_e32 v23, v56
	v_mov_b32_e32 v56, v45
	v_mov_b32_e32 v45, v60
	v_mov_b32_e32 v60, v25
	v_mov_b32_e32 v25, v38
	v_mov_b32_e32 v38, v49
	v_exp_f32_e32 v49, v32
	v_sub_f32_e32 v93, v72, v40
	v_mov_b32_e32 v30, v27
	v_mul_f32_e32 v2, 0x3fb8aa3b, v2
	v_mul_f32_e32 v27, 0x3fb8aa3b, v92
	v_mov_b32_e32 v66, v26
	v_mov_b32_e32 v72, v50
	v_mul_f32_e32 v50, 0x3fb8aa3b, v93
	v_exp_f32_e32 v26, v2
	v_exp_f32_e32 v92, v27
	v_exp_f32_e32 v27, v50
	v_add_f32_e32 v2, v48, v19
	v_add_f32_e32 v2, v49, v2
	v_mov_b32_e32 v68, v62
	v_div_scale_f32 v50, s[0:1], v2, v2, 1.0
	v_add_f32_e32 v62, v26, v92
	v_mov_b32_e32 v32, v63
	v_rcp_f32_e32 v63, v50
	v_add_f32_e32 v93, v27, v62
	v_cvt_pk_f32_fp8_sdwa v[42:43], v47 src0_sel:WORD_1
	v_div_scale_f32 v62, s[0:1], v93, v93, 1.0
	v_mov_b32_e32 v40, v65
	v_rcp_f32_e32 v65, v62
	v_fma_f32 v94, -v50, v63, 1.0
	v_mov_b32_e32 v73, v42
	v_mov_b32_e32 v42, v51
	v_div_scale_f32 v51, vcc, 1.0, v2, 1.0
	v_fmac_f32_e32 v63, v94, v63
	v_mul_f32_e32 v94, v51, v63
	v_fma_f32 v95, -v62, v65, 1.0
	v_mov_b32_e32 v70, v64
	v_div_scale_f32 v64, s[0:1], 1.0, v93, 1.0
	v_fma_f32 v96, -v50, v94, v51
	v_fmac_f32_e32 v65, v95, v65
	v_fmac_f32_e32 v94, v96, v63
	v_mul_f32_e32 v95, v64, v65
	v_fma_f32 v50, -v50, v94, v51
	v_fma_f32 v51, -v62, v95, v64
	v_div_fmas_f32 v50, v50, v63, v94
	v_fmac_f32_e32 v95, v51, v65
	v_div_fixup_f32 v2, v50, v2, 1.0
	v_fma_f32 v50, -v62, v95, v64
	s_mov_b64 vcc, s[0:1]
	v_cvt_pk_f32_fp8_e32 v[46:47], v36
	v_cvt_pk_f32_fp8_sdwa v[52:53], v36 src0_sel:WORD_1
	v_cvt_pk_f32_fp8_e32 v[58:59], v37
	v_mul_f32_e32 v19, v19, v2
	v_pk_mul_f32 v[48:49], v[48:49], v[2:3] op_sel_hi:[1,0]
	v_div_fmas_f32 v2, v50, v65, v95
	v_cvt_pk_f32_fp8_sdwa v[36:37], v37 src0_sel:WORD_1
	v_pk_mul_f32 v[50:51], v[48:49], v[66:67]
	v_pk_mul_f32 v[30:31], v[48:49], v[30:31]
	v_pk_mul_f32 v[62:63], v[48:49], v[68:69]
	v_pk_mul_f32 v[32:33], v[48:49], v[32:33]
	v_pk_mul_f32 v[64:65], v[48:49], v[70:71]
	v_pk_mul_f32 v[40:41], v[48:49], v[40:41]
	v_pk_mul_f32 v[66:67], v[48:49], v[72:73]
	v_div_fixup_f32 v2, v2, v93, 1.0
	v_pk_mul_f32 v[42:43], v[48:49], v[42:43]
	v_fma_f32 v48, v19, v8, v50
	v_fma_f32 v30, v19, v9, v30
	v_fma_f32 v28, v19, v28, v62
	v_fma_f32 v29, v19, v29, v32
	v_fma_f32 v20, v19, v20, v64
	v_fma_f32 v21, v19, v21, v40
	v_fma_f32 v32, v19, v34, v66
	v_pk_mul_f32 v[8:9], v[26:27], v[2:3] op_sel_hi:[1,0]
	v_fma_f32 v19, v19, v35, v42
	v_mul_f32_e32 v34, v92, v2
	v_add_f32_e32 v2, v48, v51
	v_add_f32_e32 v35, v30, v31
	v_add_f32_e32 v40, v28, v63
	v_add_f32_e32 v42, v29, v33
	v_add_f32_e32 v48, v20, v65
	v_add_f32_e32 v41, v21, v41
	v_add_f32_e32 v49, v32, v67
	v_pk_mul_f32 v[20:21], v[8:9], v[74:75]
	v_pk_mul_f32 v[26:27], v[8:9], v[54:55]
	v_pk_mul_f32 v[22:23], v[8:9], v[22:23]
	v_pk_mul_f32 v[28:29], v[8:9], v[56:57]
	v_pk_mul_f32 v[30:31], v[8:9], v[44:45]
	v_pk_mul_f32 v[32:33], v[8:9], v[60:61]
	v_pk_mul_f32 v[24:25], v[8:9], v[24:25]
	v_pk_mul_f32 v[8:9], v[8:9], v[38:39]
	v_mul_f32_e32 v2, v2, v76
	v_mul_f32_e32 v35, v35, v77
	v_fma_f32 v20, v34, v46, v20
	v_fma_f32 v26, v34, v47, v26
	v_fma_f32 v22, v34, v52, v22
	v_fma_f32 v28, v34, v53, v28
	v_fma_f32 v30, v34, v58, v30
	v_fma_f32 v32, v34, v59, v32
	v_mul_f32_e32 v38, v40, v78
	v_mul_f32_e32 v40, v48, v80
	v_mul_f32_e32 v41, v41, v81
	v_fma_f32 v24, v34, v36, v24
	v_fma_f32 v8, v34, v37, v8
	v_med3_f32 v2, v2, s11, v1
	v_med3_f32 v34, v35, s11, v1
	v_add_f32_e32 v20, v20, v21
	v_add_f32_e32 v21, v26, v27
	v_add_f32_e32 v22, v22, v23
	v_add_f32_e32 v23, v28, v29
	v_add_f32_e32 v26, v30, v31
	v_add_f32_e32 v27, v32, v33
	v_med3_f32 v35, v38, s11, v1
	v_med3_f32 v37, v40, s11, v1
	v_med3_f32 v38, v41, s11, v1
	v_add_f32_e32 v8, v8, v9
	v_cvt_pk_fp8_f32 v6, v2, v34
	v_mul_f32_e32 v2, v20, v84
	v_mul_f32_e32 v9, v21, v85
	v_mul_f32_e32 v20, v22, v86
	v_mul_f32_e32 v21, v23, v87
	v_mul_f32_e32 v22, v26, v88
	v_mul_f32_e32 v23, v27, v89
	v_cvt_pk_fp8_f32 v7, v37, v38
	v_med3_f32 v2, v2, s11, v1
	v_med3_f32 v9, v9, s11, v1
	v_med3_f32 v22, v22, s11, v1
	v_med3_f32 v23, v23, s11, v1
	v_add_f32_e32 v19, v19, v43
	v_cvt_pk_fp8_f32 v10, v2, v9
	v_cvt_pk_fp8_f32 v11, v22, v23
	v_mul_f32_e32 v39, v42, v79
	v_mul_f32_e32 v42, v49, v82
	v_mul_f32_e32 v19, v19, v83
	v_add_f32_e32 v24, v24, v25
	v_med3_f32 v36, v39, s11, v1
	v_med3_f32 v39, v42, s11, v1
	v_med3_f32 v19, v19, s11, v1
	v_mul_f32_e32 v24, v24, v90
	v_mul_f32_e32 v8, v8, v91
	v_med3_f32 v20, v20, s11, v1
	v_med3_f32 v21, v21, s11, v1
	v_med3_f32 v24, v24, s11, v1
	v_med3_f32 v8, v8, s11, v1
	v_cvt_pk_fp8_f32 v6, v35, v36 op_sel:[0,0,1]
	v_cvt_pk_fp8_f32 v7, v39, v19 op_sel:[0,0,1]
	v_cvt_pk_fp8_f32 v10, v20, v21 op_sel:[0,0,1]
	v_cvt_pk_fp8_f32 v11, v24, v8 op_sel:[0,0,1]
	global_store_dwordx2 v[12:13], v[6:7], off
	global_store_dwordx2 v[14:15], v[10:11], off
	s_cbranch_scc1 .LBB0_343

; __global__ void __launch_bounds__(NTHREADS, 2) fwd(Params p) {
	.amdhsa_kernel _ZN2mk3fwdENS_6ParamsE
		.amdhsa_group_segment_fixed_size 0
		.amdhsa_private_segment_fixed_size 0
		.amdhsa_kernarg_size 376
		.amdhsa_user_sgpr_count 2
		.amdhsa_user_sgpr_dispatch_ptr 0
		.amdhsa_user_sgpr_queue_ptr 0
		.amdhsa_user_sgpr_kernarg_segment_ptr 1
		.amdhsa_user_sgpr_dispatch_id 0
		.amdhsa_user_sgpr_kernarg_preload_length 0
		.amdhsa_user_sgpr_kernarg_preload_offset 0
		.amdhsa_user_sgpr_private_segment_size 0
		.amdhsa_uses_dynamic_stack 0
		.amdhsa_enable_private_segment 0
		.amdhsa_system_sgpr_workgroup_id_x 1
		.amdhsa_system_sgpr_workgroup_id_y 0
		.amdhsa_system_sgpr_workgroup_id_z 0
		.amdhsa_system_sgpr_workgroup_info 0
		.amdhsa_system_vgpr_workitem_id 2
		.amdhsa_next_free_vgpr 256
		.amdhsa_next_free_sgpr 102
		.amdhsa_accum_offset 256
		.amdhsa_reserve_vcc 1
		.amdhsa_float_round_mode_32 0
		.amdhsa_float_round_mode_16_64 0
		.amdhsa_float_denorm_mode_32 3
		.amdhsa_float_denorm_mode_16_64 3
		.amdhsa_dx10_clamp 1
		.amdhsa_ieee_mode 1
		.amdhsa_fp16_overflow 0
		.amdhsa_tg_split 0
		.amdhsa_exception_fp_ieee_invalid_op 0
		.amdhsa_exception_fp_denorm_src 0
		.amdhsa_exception_fp_ieee_div_zero 0
		.amdhsa_exception_fp_ieee_overflow 0
		.amdhsa_exception_fp_ieee_underflow 0
		.amdhsa_exception_fp_ieee_inexact 0
		.amdhsa_exception_int_div_zero 0
	.end_amdhsa_kernel

; __global__ void __launch_bounds__(NTHREADS, 2) fwd(Params p) {
amdhsa.kernels:
  - .agpr_count:     0
    .args:
      - .offset:         0
        .size:           120
        .value_kind:     by_value
      - .offset:         120
        .size:           4
        .value_kind:     hidden_block_count_x
      - .offset:         124
        .size:           4
        .value_kind:     hidden_block_count_y
      - .offset:         128
        .size:           4
        .value_kind:     hidden_block_count_z
      - .offset:         132
        .size:           2
        .value_kind:     hidden_group_size_x
      - .offset:         134
        .size:           2
        .value_kind:     hidden_group_size_y
      - .offset:         136
        .size:           2
        .value_kind:     hidden_group_size_z
      - .offset:         138
        .size:           2
        .value_kind:     hidden_remainder_x
      - .offset:         140
        .size:           2
        .value_kind:     hidden_remainder_y
      - .offset:         142
        .size:           2
        .value_kind:     hidden_remainder_z
      - .offset:         160
        .size:           8
        .value_kind:     hidden_global_offset_x
      - .offset:         168
        .size:           8
        .value_kind:     hidden_global_offset_y
      - .offset:         176
        .size:           8
        .value_kind:     hidden_global_offset_z
      - .offset:         184
        .size:           2
        .value_kind:     hidden_grid_dims
      - .offset:         208
        .size:           8
        .value_kind:     hidden_multigrid_sync_arg
      - .offset:         240
        .size:           4
        .value_kind:     hidden_dynamic_lds_size
    .group_segment_fixed_size: 0
    .kernarg_segment_align: 8
    .kernarg_segment_size: 376
    .language:       OpenCL C
    .language_version:
      - 2
      - 0
    .max_flat_workgroup_size: 512
    .name:           _ZN2mk3fwdENS_6ParamsE
    .private_segment_fixed_size: 0
    .sgpr_count:     108
    .sgpr_spill_count: 137
    .symbol:         _ZN2mk3fwdENS_6ParamsE.kd
    .uniform_work_group_size: 1
    .uses_dynamic_stack: false
    .vgpr_count:     256
    .vgpr_spill_count: 0
    .wavefront_size: 64
